# K-loop load segments: LDS-DMA loads issued earlier, interleaved with the ds_read burst (reorder only)
# speedup vs baseline: 1.0109x; 1.0048x over previous
; #define PG8_STAGE(bufoff, gbase, voff) do { _Pragma("unroll") for (int _i = 0; _i < 2; ++_i) \
;         __builtin_amdgcn_global_load_lds((const unsigned*)((const char*)(gbase) + (voff)[_i]), (LAS unsigned*)(lds + (bufoff) + ldsw + _i * 8192), 16, 0, 0); } while (0)
; #define PG8_LDA(dst, b, h) do { _Pragma("unroll") for (int m = 0; m < 4; ++m) _Pragma("unroll") for (int k = 0; k < 2; ++k) dst[m][k] = *(const LAS bf16x8*)(lds + PG8_SA(b, h) + aoff + m * 2048 + k * 1024); } while (0)
; #define PG8_BAR __builtin_amdgcn_s_barrier()
; template <class Epi>
; __device__ __forceinline__ void gemm_phase(LAS unsigned char* lds, const Gemm g, const StaticOrder& S, const Epi& E, const int tid) {
;     ...
;             const bool last = (t == ntt - 2);
;             const bool s1 = Epi::TWO && (t >= nt), s2 = Epi::TWO && (t + 2 >= nt);
;             const char* a1 = (s1 ? cA2 + (size_t)(t - nt + 1) * kstep : cA + (size_t)(t + 1) * kstep);
;             const char* a2 = last ? nA : (s2 ? cA2 + (size_t)(t + 2 - nt) * kstep : cA + (size_t)(t + 2) * kstep);
;             const char* b2 = last ? nB : (s2 ? cB2 + (size_t)(t + 2 - nt) * kstep : cB + (size_t)(t + 2) * kstep);
;             const char* a3 = a2 + kstep; const char* b3 = b2 + kstep;
;             if constexpr (Epi::TWO) { if (t == nt) E.mid(acc, cur, wr, wc, fr, fq); }
;             if constexpr (SP2) {
;             PG8_LDB(B0, 0, 0); PG8_LDB(B1, 0, 1); PG8_SCHED; PG8_LDA(At, 0, 0); PG8_STAGE(PG8_SA(1, 1), a1 + hstep, voffA);
;             PG8_WAIT_V(8); PG8_WAIT_L(0); PG8_BAR; PG8_MMA(0, 0, At, B0); PG8_MMA(0, 1, At, B1); PG8_BAR; PG8_SCHED;
;             PG8_LDA(At, 0, 1); PG8_STAGE(PG8_SB(0, 0), b2, voffB); PG8_STAGE(PG8_SB(0, 1), b2 + bhs, voffB); PG8_STAGE(PG8_SA(0, 0), a2, voffA);
;             PG8_WAIT_V(8); PG8_WAIT_L(0); PG8_BAR; PG8_MMA(1, 0, At, B0); PG8_MMA(1, 1, At, B1); PG8_BAR; PG8_SCHED;
;             PG8_LDB(B0, 1, 0); PG8_LDB(B1, 1, 1); PG8_SCHED; PG8_LDA(At, 1, 0); PG8_STAGE(PG8_SA(0, 1), a2 + hstep, voffA);
;             PG8_WAIT_V(8); PG8_WAIT_L(0); PG8_BAR; PG8_MMA(0, 0, At, B0); PG8_MMA(0, 1, At, B1); PG8_BAR; PG8_SCHED;
;             PG8_LDA(At, 1, 1); PG8_STAGE(PG8_SB(1, 0), b3, voffB); PG8_STAGE(PG8_SB(1, 1), b3 + bhs, voffB); PG8_STAGE(PG8_SA(1, 0), a3, voffA);
;             PG8_WAIT_V(8); PG8_WAIT_L(0); PG8_BAR; PG8_MMA(1, 0, At, B0); PG8_MMA(1, 1, At, B1); PG8_BAR; PG8_SCHED;
.LBB0_126:
	s_add_u32 s30, s28, 0xffe00080
	s_addc_u32 s31, s29, -1
	s_add_i32 s52, 0, 0x10000
	s_cmpk_eq_i32 s51, 0x7c
	s_cselect_b32 s35, s17, s31
	s_cselect_b32 s34, s27, s30
	s_cselect_b32 s31, s15, s50
	s_cselect_b32 s30, s33, s49
	s_add_i32 s54, 0, 0x14000
	v_add_u32_e32 v30, s52, v193
	v_add_u32_e32 v54, s54, v193
	ds_read_b128 v[18:21], v30
	ds_read_b128 v[22:25], v30 offset:1024
	ds_read_b128 v[26:29], v30 offset:2048
	ds_read_b128 v[30:33], v30 offset:3072
	ds_read_b128 v[42:45], v54
	ds_read_b128 v[46:49], v54 offset:1024
	ds_read_b128 v[50:53], v54 offset:2048
	ds_read_b128 v[54:57], v54 offset:3072
	v_lshl_add_u64 v[172:173], s[28:29], 0, v[180:181]
	s_add_i32 m0, s37, 0xc000
	ds_read_b128 v[182:185], v199
	global_load_lds_dwordx4 v[172:173], off
	ds_read_b128 v[186:189], v199 offset:1024
	ds_read_b128 v[212:215], v199 offset:2048
	v_lshl_add_u64 v[172:173], s[28:29], 0, v[178:179]
	s_add_i32 m0, s37, 0xe000
	s_nop 0
	global_load_lds_dwordx4 v[172:173], off
	ds_read_b128 v[216:219], v199 offset:3072
	ds_read_b128 v[220:223], v199 offset:4096
	ds_read_b128 v[224:227], v199 offset:5120
	ds_read_b128 v[228:231], v199 offset:6144
	ds_read_b128 v[232:235], v199 offset:7168
	s_waitcnt vmcnt(8)
	s_waitcnt lgkmcnt(0)
	s_barrier
	s_setprio 1
	s_waitcnt lgkmcnt(0)
	v_mfma_f32_16x16x32_bf16 v[158:161], v[18:21], v[182:185], v[158:161]
	v_mfma_f32_16x16x32_bf16 v[154:157], v[26:29], v[182:185], v[154:157]
	v_mfma_f32_16x16x32_bf16 v[142:145], v[18:21], v[212:215], v[142:145]
	v_mfma_f32_16x16x32_bf16 v[138:141], v[26:29], v[212:215], v[138:141]
	v_mfma_f32_16x16x32_bf16 v[126:129], v[18:21], v[220:223], v[126:129]
	v_mfma_f32_16x16x32_bf16 v[122:125], v[26:29], v[220:223], v[122:125]
	v_mfma_f32_16x16x32_bf16 v[110:113], v[18:21], v[228:231], v[110:113]
	v_mfma_f32_16x16x32_bf16 v[106:109], v[26:29], v[228:231], v[106:109]
	v_mfma_f32_16x16x32_bf16 v[158:161], v[22:25], v[186:189], v[158:161]
	v_mfma_f32_16x16x32_bf16 v[154:157], v[30:33], v[186:189], v[154:157]
	v_mfma_f32_16x16x32_bf16 v[142:145], v[22:25], v[216:219], v[142:145]
	v_mfma_f32_16x16x32_bf16 v[138:141], v[30:33], v[216:219], v[138:141]
	v_mfma_f32_16x16x32_bf16 v[126:129], v[22:25], v[224:227], v[126:129]
	v_mfma_f32_16x16x32_bf16 v[122:125], v[30:33], v[224:227], v[122:125]
	v_mfma_f32_16x16x32_bf16 v[110:113], v[22:25], v[232:235], v[110:113]
	v_mfma_f32_16x16x32_bf16 v[106:109], v[30:33], v[232:235], v[106:109]
	s_setprio 0
	s_setprio 1
	v_mfma_f32_16x16x32_bf16 v[150:153], v[42:45], v[182:185], v[150:153]
	v_mfma_f32_16x16x32_bf16 v[146:149], v[50:53], v[182:185], v[146:149]
	v_mfma_f32_16x16x32_bf16 v[134:137], v[42:45], v[212:215], v[134:137]
	v_mfma_f32_16x16x32_bf16 v[130:133], v[50:53], v[212:215], v[130:133]
	v_mfma_f32_16x16x32_bf16 v[118:121], v[42:45], v[220:223], v[118:121]
	v_mfma_f32_16x16x32_bf16 v[114:117], v[50:53], v[220:223], v[114:117]
	v_mfma_f32_16x16x32_bf16 v[102:105], v[42:45], v[228:231], v[102:105]
	v_mfma_f32_16x16x32_bf16 v[98:101], v[50:53], v[228:231], v[98:101]
	v_mfma_f32_16x16x32_bf16 v[150:153], v[46:49], v[186:189], v[150:153]
	v_mfma_f32_16x16x32_bf16 v[146:149], v[54:57], v[186:189], v[146:149]
	v_mfma_f32_16x16x32_bf16 v[134:137], v[46:49], v[216:219], v[134:137]
	v_mfma_f32_16x16x32_bf16 v[130:133], v[54:57], v[216:219], v[130:133]
	v_mfma_f32_16x16x32_bf16 v[118:121], v[46:49], v[224:227], v[118:121]
	v_mfma_f32_16x16x32_bf16 v[114:117], v[54:57], v[224:227], v[114:117]
	v_mfma_f32_16x16x32_bf16 v[102:105], v[46:49], v[232:235], v[102:105]
	v_mfma_f32_16x16x32_bf16 v[98:101], v[54:57], v[232:235], v[98:101]
	s_setprio 0
	s_barrier
	s_add_i32 s52, s52, s36
	v_lshl_add_u64 v[172:173], s[30:31], 0, v[0:1]
	s_mov_b32 m0, s52
	ds_read_b128 v[182:185], v199 offset:16384
	global_load_lds_dwordx4 v[172:173], off
	ds_read_b128 v[186:189], v199 offset:17408
	ds_read_b128 v[212:215], v199 offset:18432
	s_add_i32 m0, s52, 0x2000
	s_add_u32 s52, s30, 0x20000
	v_lshl_add_u64 v[174:175], s[30:31], 0, v[166:167]
	s_addc_u32 s53, s31, 0
	s_add_i32 s54, s54, s36
	global_load_lds_dwordx4 v[174:175], off
	ds_read_b128 v[216:219], v199 offset:19456
	ds_read_b128 v[220:223], v199 offset:20480
	v_lshl_add_u64 v[176:177], s[52:53], 0, v[0:1]
	s_mov_b32 m0, s54
	v_lshl_add_u64 v[200:201], s[34:35], 0, v[164:165]
	global_load_lds_dwordx4 v[176:177], off
	ds_read_b128 v[224:227], v199 offset:21504
	ds_read_b128 v[228:231], v199 offset:22528
	v_lshl_add_u64 v[176:177], s[52:53], 0, v[166:167]
	s_add_i32 m0, s54, 0x2000
	s_nop 0
	global_load_lds_dwordx4 v[176:177], off
	ds_read_b128 v[232:235], v199 offset:23552
	v_lshl_add_u64 v[176:177], s[34:35], 0, v[162:163]
	s_mov_b32 m0, s37
	s_nop 0
	global_load_lds_dwordx4 v[176:177], off
	s_mov_b32 m0, s38
	s_nop 0
	global_load_lds_dwordx4 v[200:201], off
	s_waitcnt vmcnt(8)
	s_waitcnt lgkmcnt(0)
	s_barrier
; #define PG8_STAGE(bufoff, gbase, voff) do { _Pragma("unroll") for (int _i = 0; _i < 2; ++_i) \
;         __builtin_amdgcn_global_load_lds((const unsigned*)((const char*)(gbase) + (voff)[_i]), (LAS unsigned*)(lds + (bufoff) + ldsw + _i * 8192), 16, 0, 0); } while (0)
; #define PG8_LDA(dst, b, h) do { _Pragma("unroll") for (int m = 0; m < 4; ++m) _Pragma("unroll") for (int k = 0; k < 2; ++k) dst[m][k] = *(const LAS bf16x8*)(lds + PG8_SA(b, h) + aoff + m * 2048 + k * 1024); } while (0)
; #define PG8_LDB(dst, b, h) do { _Pragma("unroll") for (int n = 0; n < 2; ++n) _Pragma("unroll") for (int k = 0; k < 2; ++k) dst[n][k] = *(const LAS bf16x8*)(lds + PG8_SB(b, h) + boff + n * 2048 + k * 1024); } while (0)
; #define PG8_MMA(ai, bj, At, Bt) do { __builtin_amdgcn_s_setprio(1); _Pragma("unroll") for (int m = 0; m < 4; ++m) _Pragma("unroll") for (int n = 0; n < 2; ++n) _Pragma("unroll") for (int k = 0; k < 2; ++k) \
;         acc[ai][bj][m][n] = __builtin_amdgcn_mfma_f32_16x16x32_bf16(Bt[n][k], At[m][k], acc[ai][bj][m][n], 0, 0, 0); __builtin_amdgcn_s_setprio(0); } while (0)
; #define PG8_WAIT_V(n) asm volatile("s_waitcnt vmcnt(" #n ")" ::: "memory")
; #define PG8_WAIT_L(n) asm volatile("s_waitcnt lgkmcnt(" #n ")" ::: "memory")
; #define PG8_BAR __builtin_amdgcn_s_barrier()
; template <class Epi>
; __device__ __forceinline__ void gemm_phase(LAS unsigned char* lds, const Gemm g, const StaticOrder& S, const Epi& E, const int tid) {
;     ...
;             PG8_LDB(B0, 0, 0); PG8_LDB(B1, 0, 1); PG8_SCHED; PG8_LDA(At, 0, 0); PG8_STAGE(PG8_SA(1, 1), a1 + hstep, voffA);
;             PG8_WAIT_V(8); PG8_WAIT_L(0); PG8_BAR; PG8_MMA(0, 0, At, B0); PG8_MMA(0, 1, At, B1); PG8_BAR; PG8_SCHED;
;             PG8_LDA(At, 0, 1); PG8_STAGE(PG8_SB(0, 0), b2, voffB); PG8_STAGE(PG8_SB(0, 1), b2 + bhs, voffB); PG8_STAGE(PG8_SA(0, 0), a2, voffA);
;             PG8_WAIT_V(8); PG8_WAIT_L(0); PG8_BAR; PG8_MMA(1, 0, At, B0); PG8_MMA(1, 1, At, B1); PG8_BAR; PG8_SCHED;
;             PG8_LDB(B0, 1, 0); PG8_LDB(B1, 1, 1); PG8_SCHED; PG8_LDA(At, 1, 0); PG8_STAGE(PG8_SA(0, 1), a2 + hstep, voffA);
;             PG8_WAIT_V(8); PG8_WAIT_L(0); PG8_BAR; PG8_MMA(0, 0, At, B0); PG8_MMA(0, 1, At, B1); PG8_BAR; PG8_SCHED;
;             PG8_LDA(At, 1, 1); PG8_STAGE(PG8_SB(1, 0), b3, voffB); PG8_STAGE(PG8_SB(1, 1), b3 + bhs, voffB); PG8_STAGE(PG8_SA(1, 0), a3, voffA);
	s_setprio 1
	s_waitcnt lgkmcnt(0)
	v_mfma_f32_16x16x32_bf16 v[94:97], v[18:21], v[182:185], v[94:97]
	v_mfma_f32_16x16x32_bf16 v[90:93], v[26:29], v[182:185], v[90:93]
	v_mfma_f32_16x16x32_bf16 v[78:81], v[18:21], v[212:215], v[78:81]
	v_mfma_f32_16x16x32_bf16 v[74:77], v[26:29], v[212:215], v[74:77]
	v_mfma_f32_16x16x32_bf16 v[62:65], v[18:21], v[220:223], v[62:65]
	v_mfma_f32_16x16x32_bf16 v[58:61], v[26:29], v[220:223], v[58:61]
	v_mfma_f32_16x16x32_bf16 v[14:17], v[18:21], v[228:231], v[14:17]
	v_mfma_f32_16x16x32_bf16 v[10:13], v[26:29], v[228:231], v[10:13]
	v_mfma_f32_16x16x32_bf16 v[94:97], v[22:25], v[186:189], v[94:97]
	v_mfma_f32_16x16x32_bf16 v[90:93], v[30:33], v[186:189], v[90:93]
	v_mfma_f32_16x16x32_bf16 v[78:81], v[22:25], v[216:219], v[78:81]
	v_mfma_f32_16x16x32_bf16 v[74:77], v[30:33], v[216:219], v[74:77]
	v_mfma_f32_16x16x32_bf16 v[62:65], v[22:25], v[224:227], v[62:65]
	v_mfma_f32_16x16x32_bf16 v[58:61], v[30:33], v[224:227], v[58:61]
	v_mfma_f32_16x16x32_bf16 v[14:17], v[22:25], v[232:235], v[14:17]
	v_mfma_f32_16x16x32_bf16 v[10:13], v[30:33], v[232:235], v[10:13]
	s_setprio 0
	s_setprio 1
	v_mfma_f32_16x16x32_bf16 v[38:41], v[42:45], v[220:223], v[38:41]
	v_mfma_f32_16x16x32_bf16 v[34:37], v[50:53], v[220:223], v[34:37]
	v_mfma_f32_16x16x32_bf16 v[6:9], v[42:45], v[228:231], v[6:9]
	v_mfma_f32_16x16x32_bf16 v[2:5], v[50:53], v[228:231], v[2:5]
	v_mfma_f32_16x16x32_bf16 v[18:21], v[42:45], v[182:185], v[86:89]
	v_mfma_f32_16x16x32_bf16 v[22:25], v[50:53], v[182:185], v[82:85]
	v_mfma_f32_16x16x32_bf16 v[26:29], v[42:45], v[212:215], v[70:73]
	v_mfma_f32_16x16x32_bf16 v[30:33], v[50:53], v[212:215], v[66:69]
	v_mfma_f32_16x16x32_bf16 v[38:41], v[46:49], v[224:227], v[38:41]
	v_mfma_f32_16x16x32_bf16 v[34:37], v[54:57], v[224:227], v[34:37]
	v_mfma_f32_16x16x32_bf16 v[6:9], v[46:49], v[232:235], v[6:9]
	v_mfma_f32_16x16x32_bf16 v[2:5], v[54:57], v[232:235], v[2:5]
	v_mfma_f32_16x16x32_bf16 v[18:21], v[46:49], v[186:189], v[18:21]
	v_mfma_f32_16x16x32_bf16 v[22:25], v[54:57], v[186:189], v[22:25]
	v_mfma_f32_16x16x32_bf16 v[26:29], v[46:49], v[216:219], v[26:29]
	v_mfma_f32_16x16x32_bf16 v[30:33], v[54:57], v[216:219], v[30:33]
	s_setprio 0
	s_barrier
	s_add_i32 s52, 0, 0x18000
	s_add_i32 s53, 0, 0x1c000
	v_add_u32_e32 v54, s52, v193
	v_add_u32_e32 v66, s53, v193
	ds_read_b128 v[42:45], v54
	ds_read_b128 v[46:49], v54 offset:1024
	ds_read_b128 v[50:53], v54 offset:2048
	ds_read_b128 v[54:57], v54 offset:3072
	ds_read_b128 v[182:185], v66
	ds_read_b128 v[186:189], v66 offset:1024
	ds_read_b128 v[212:215], v66 offset:2048
	ds_read_b128 v[216:219], v66 offset:3072
	s_add_u32 s34, s34, 0x200000
	s_addc_u32 s35, s35, 0
	s_mov_b32 m0, s39
	v_lshl_add_u64 v[236:237], s[34:35], 0, v[162:163]
	ds_read_b128 v[66:69], v199 offset:32768
	global_load_lds_dwordx4 v[236:237], off
	ds_read_b128 v[70:73], v199 offset:33792
	ds_read_b128 v[82:85], v199 offset:34816
	v_lshl_add_u64 v[236:237], s[34:35], 0, v[164:165]
	s_mov_b32 m0, s44
	s_nop 0
	global_load_lds_dwordx4 v[236:237], off
	ds_read_b128 v[86:89], v199 offset:35840
	ds_read_b128 v[220:223], v199 offset:36864
	ds_read_b128 v[224:227], v199 offset:37888
	ds_read_b128 v[228:231], v199 offset:38912
	ds_read_b128 v[232:235], v199 offset:39936
	s_waitcnt vmcnt(8)
	s_waitcnt lgkmcnt(0)
	s_barrier
	s_setprio 1
	s_waitcnt lgkmcnt(0)
	v_mfma_f32_16x16x32_bf16 v[158:161], v[42:45], v[66:69], v[158:161]
	v_mfma_f32_16x16x32_bf16 v[154:157], v[50:53], v[66:69], v[154:157]
	v_mfma_f32_16x16x32_bf16 v[142:145], v[42:45], v[82:85], v[142:145]
	v_mfma_f32_16x16x32_bf16 v[138:141], v[50:53], v[82:85], v[138:141]
	v_mfma_f32_16x16x32_bf16 v[126:129], v[42:45], v[220:223], v[126:129]
	v_mfma_f32_16x16x32_bf16 v[122:125], v[50:53], v[220:223], v[122:125]
	v_mfma_f32_16x16x32_bf16 v[110:113], v[42:45], v[228:231], v[110:113]
	v_mfma_f32_16x16x32_bf16 v[106:109], v[50:53], v[228:231], v[106:109]
	v_mfma_f32_16x16x32_bf16 v[158:161], v[46:49], v[70:73], v[158:161]
	v_mfma_f32_16x16x32_bf16 v[154:157], v[54:57], v[70:73], v[154:157]
	v_mfma_f32_16x16x32_bf16 v[142:145], v[46:49], v[86:89], v[142:145]
	v_mfma_f32_16x16x32_bf16 v[138:141], v[54:57], v[86:89], v[138:141]
	v_mfma_f32_16x16x32_bf16 v[126:129], v[46:49], v[224:227], v[126:129]
	v_mfma_f32_16x16x32_bf16 v[122:125], v[54:57], v[224:227], v[122:125]
	v_mfma_f32_16x16x32_bf16 v[110:113], v[46:49], v[232:235], v[110:113]
	v_mfma_f32_16x16x32_bf16 v[106:109], v[54:57], v[232:235], v[106:109]
	s_setprio 0
	s_setprio 1
	v_mfma_f32_16x16x32_bf16 v[150:153], v[182:185], v[66:69], v[150:153]
	v_mfma_f32_16x16x32_bf16 v[66:69], v[212:215], v[66:69], v[146:149]
	v_mfma_f32_16x16x32_bf16 v[146:149], v[216:219], v[70:73], v[66:69]
	v_mfma_f32_16x16x32_bf16 v[66:69], v[182:185], v[82:85], v[134:137]
	v_mfma_f32_16x16x32_bf16 v[134:137], v[186:189], v[86:89], v[66:69]
	v_mfma_f32_16x16x32_bf16 v[66:69], v[212:215], v[82:85], v[130:133]
	v_mfma_f32_16x16x32_bf16 v[130:133], v[216:219], v[86:89], v[66:69]
	v_mfma_f32_16x16x32_bf16 v[66:69], v[182:185], v[220:223], v[118:121]
	v_mfma_f32_16x16x32_bf16 v[118:121], v[186:189], v[224:227], v[66:69]
	v_mfma_f32_16x16x32_bf16 v[66:69], v[212:215], v[220:223], v[114:117]
	v_mfma_f32_16x16x32_bf16 v[114:117], v[216:219], v[224:227], v[66:69]
	v_mfma_f32_16x16x32_bf16 v[66:69], v[182:185], v[228:231], v[102:105]
	v_mfma_f32_16x16x32_bf16 v[102:105], v[186:189], v[232:235], v[66:69]
	v_mfma_f32_16x16x32_bf16 v[66:69], v[212:215], v[228:231], v[98:101]
	v_mfma_f32_16x16x32_bf16 v[150:153], v[186:189], v[70:73], v[150:153]
	v_mfma_f32_16x16x32_bf16 v[98:101], v[216:219], v[232:235], v[66:69]
	s_setprio 0
	s_barrier
; #define PG8_STAGE(bufoff, gbase, voff) do { _Pragma("unroll") for (int _i = 0; _i < 2; ++_i) \
;         __builtin_amdgcn_global_load_lds((const unsigned*)((const char*)(gbase) + (voff)[_i]), (LAS unsigned*)(lds + (bufoff) + ldsw + _i * 8192), 16, 0, 0); } while (0)
; #define PG8_LDA(dst, b, h) do { _Pragma("unroll") for (int m = 0; m < 4; ++m) _Pragma("unroll") for (int k = 0; k < 2; ++k) dst[m][k] = *(const LAS bf16x8*)(lds + PG8_SA(b, h) + aoff + m * 2048 + k * 1024); } while (0)
; #define PG8_LDB(dst, b, h) do { _Pragma("unroll") for (int n = 0; n < 2; ++n) _Pragma("unroll") for (int k = 0; k < 2; ++k) dst[n][k] = *(const LAS bf16x8*)(lds + PG8_SB(b, h) + boff + n * 2048 + k * 1024); } while (0)
; #define PG8_MMA(ai, bj, At, Bt) do { __builtin_amdgcn_s_setprio(1); _Pragma("unroll") for (int m = 0; m < 4; ++m) _Pragma("unroll") for (int n = 0; n < 2; ++n) _Pragma("unroll") for (int k = 0; k < 2; ++k) \
;         acc[ai][bj][m][n] = __builtin_amdgcn_mfma_f32_16x16x32_bf16(Bt[n][k], At[m][k], acc[ai][bj][m][n], 0, 0, 0); __builtin_amdgcn_s_setprio(0); } while (0)
; #define PG8_WAIT_V(n) asm volatile("s_waitcnt vmcnt(" #n ")" ::: "memory")
; template <class Epi>
; __device__ __forceinline__ void gemm_phase(LAS unsigned char* lds, const Gemm g, const StaticOrder& S, const Epi& E, const int tid) {
;     ...
;         for (int t = 0; t < ntt; t += 2) {
;     ...
;             PG8_LDB(B0, 0, 0); PG8_LDB(B1, 0, 1); PG8_SCHED; PG8_LDA(At, 0, 0); PG8_STAGE(PG8_SA(1, 1), a1 + hstep, voffA);
;             PG8_WAIT_V(8); PG8_WAIT_L(0); PG8_BAR; PG8_MMA(0, 0, At, B0); PG8_MMA(0, 1, At, B1); PG8_BAR; PG8_SCHED;
;             PG8_LDA(At, 0, 1); PG8_STAGE(PG8_SB(0, 0), b2, voffB); PG8_STAGE(PG8_SB(0, 1), b2 + bhs, voffB); PG8_STAGE(PG8_SA(0, 0), a2, voffA);
;             PG8_WAIT_V(8); PG8_WAIT_L(0); PG8_BAR; PG8_MMA(1, 0, At, B0); PG8_MMA(1, 1, At, B1); PG8_BAR; PG8_SCHED;
;             PG8_LDB(B0, 1, 0); PG8_LDB(B1, 1, 1); PG8_SCHED; PG8_LDA(At, 1, 0); PG8_STAGE(PG8_SA(0, 1), a2 + hstep, voffA);
;             PG8_WAIT_V(8); PG8_WAIT_L(0); PG8_BAR; PG8_MMA(0, 0, At, B0); PG8_MMA(0, 1, At, B1); PG8_BAR; PG8_SCHED;
;             PG8_LDA(At, 1, 1); PG8_STAGE(PG8_SB(1, 0), b3, voffB); PG8_STAGE(PG8_SB(1, 1), b3 + bhs, voffB); PG8_STAGE(PG8_SA(1, 0), a3, voffA);
;             PG8_WAIT_V(8); PG8_WAIT_L(0); PG8_BAR; PG8_MMA(1, 0, At, B0); PG8_MMA(1, 1, At, B1); PG8_BAR; PG8_SCHED;
	s_add_i32 s34, s52, s36
	v_lshl_add_u64 v[82:83], v[172:173], 0, s[70:71]
	s_mov_b32 m0, s34
	s_nop 0
	ds_read_b128 v[66:69], v199 offset:49152
	global_load_lds_dwordx4 v[82:83], off
	ds_read_b128 v[70:73], v199 offset:50176
	ds_read_b128 v[220:223], v199 offset:51200
	s_add_i32 m0, s34, 0x2000
	s_add_u32 s30, s30, 0x20080
	v_lshl_add_u64 v[82:83], v[174:175], 0, s[70:71]
	s_addc_u32 s31, s31, 0
	s_add_i32 s34, s53, s36
	global_load_lds_dwordx4 v[82:83], off
	ds_read_b128 v[224:227], v199 offset:52224
	ds_read_b128 v[228:231], v199 offset:53248
	v_lshl_add_u64 v[82:83], s[30:31], 0, v[0:1]
	s_mov_b32 m0, s34
	s_nop 0
	global_load_lds_dwordx4 v[82:83], off
	ds_read_b128 v[232:235], v199 offset:54272
	ds_read_b128 v[236:239], v199 offset:55296
	v_lshl_add_u64 v[82:83], s[30:31], 0, v[166:167]
	s_add_i32 m0, s34, 0x2000
	s_nop 0
	global_load_lds_dwordx4 v[82:83], off
	ds_read_b128 v[240:243], v199 offset:56320
	v_lshl_add_u64 v[82:83], v[176:177], 0, s[70:71]
	s_mov_b32 m0, s45
	s_nop 0
	global_load_lds_dwordx4 v[82:83], off
	v_lshl_add_u64 v[82:83], v[200:201], 0, s[70:71]
	s_mov_b32 m0, s46
	s_nop 0
	global_load_lds_dwordx4 v[82:83], off
	s_waitcnt vmcnt(8)
	s_waitcnt lgkmcnt(0)
	s_barrier
	s_setprio 1
	s_waitcnt lgkmcnt(0)
	v_mfma_f32_16x16x32_bf16 v[82:85], v[42:45], v[66:69], v[94:97]
	v_mfma_f32_16x16x32_bf16 v[94:97], v[46:49], v[70:73], v[82:85]
	v_mfma_f32_16x16x32_bf16 v[82:85], v[50:53], v[66:69], v[90:93]
	v_mfma_f32_16x16x32_bf16 v[78:81], v[42:45], v[220:223], v[78:81]
	v_mfma_f32_16x16x32_bf16 v[74:77], v[50:53], v[220:223], v[74:77]
	v_mfma_f32_16x16x32_bf16 v[62:65], v[42:45], v[228:231], v[62:65]
	v_mfma_f32_16x16x32_bf16 v[58:61], v[50:53], v[228:231], v[58:61]
	v_mfma_f32_16x16x32_bf16 v[14:17], v[42:45], v[236:239], v[14:17]
	v_mfma_f32_16x16x32_bf16 v[10:13], v[50:53], v[236:239], v[10:13]
	v_mfma_f32_16x16x32_bf16 v[90:93], v[54:57], v[70:73], v[82:85]
	v_mfma_f32_16x16x32_bf16 v[78:81], v[46:49], v[224:227], v[78:81]
	v_mfma_f32_16x16x32_bf16 v[74:77], v[54:57], v[224:227], v[74:77]
	v_mfma_f32_16x16x32_bf16 v[62:65], v[46:49], v[232:235], v[62:65]
	v_mfma_f32_16x16x32_bf16 v[58:61], v[54:57], v[232:235], v[58:61]
	v_mfma_f32_16x16x32_bf16 v[14:17], v[46:49], v[240:243], v[14:17]
	v_mfma_f32_16x16x32_bf16 v[10:13], v[54:57], v[240:243], v[10:13]
	s_setprio 0
	s_setprio 1
	v_mfma_f32_16x16x32_bf16 v[18:21], v[182:185], v[66:69], v[18:21]
	v_mfma_f32_16x16x32_bf16 v[86:89], v[186:189], v[70:73], v[18:21]
	v_mfma_f32_16x16x32_bf16 v[18:21], v[212:215], v[66:69], v[22:25]
	v_mfma_f32_16x16x32_bf16 v[82:85], v[216:219], v[70:73], v[18:21]
	v_mfma_f32_16x16x32_bf16 v[18:21], v[182:185], v[220:223], v[26:29]
	v_mfma_f32_16x16x32_bf16 v[70:73], v[186:189], v[224:227], v[18:21]
	v_mfma_f32_16x16x32_bf16 v[18:21], v[212:215], v[220:223], v[30:33]
	v_mfma_f32_16x16x32_bf16 v[66:69], v[216:219], v[224:227], v[18:21]
	v_mfma_f32_16x16x32_bf16 v[18:21], v[182:185], v[228:231], v[38:41]
	v_mfma_f32_16x16x32_bf16 v[38:41], v[186:189], v[232:235], v[18:21]
	v_mfma_f32_16x16x32_bf16 v[18:21], v[212:215], v[228:231], v[34:37]
	v_mfma_f32_16x16x32_bf16 v[6:9], v[182:185], v[236:239], v[6:9]
	v_mfma_f32_16x16x32_bf16 v[2:5], v[212:215], v[236:239], v[2:5]
	v_mfma_f32_16x16x32_bf16 v[34:37], v[216:219], v[232:235], v[18:21]
	v_mfma_f32_16x16x32_bf16 v[6:9], v[186:189], v[240:243], v[6:9]
	v_mfma_f32_16x16x32_bf16 v[2:5], v[216:219], v[240:243], v[2:5]
	s_setprio 0
	s_barrier
	s_add_i32 s51, s51, 2
	s_add_u32 s49, s49, 0x100
	s_addc_u32 s50, s50, 0
	s_add_u32 s28, s28, 0x100
	s_addc_u32 s29, s29, 0
	s_cmpk_gt_u32 s51, 0x7d
	s_cbranch_scc0 .LBB0_126
	s_and_b64 vcc, exec, s[12:13]
	s_cbranch_vccz .LBB0_129
	s_barrier

; #define PG8_STAGE(bufoff, gbase, voff) do { _Pragma("unroll") for (int _i = 0; _i < 2; ++_i) \
;         __builtin_amdgcn_global_load_lds((const unsigned*)((const char*)(gbase) + (voff)[_i]), (LAS unsigned*)(lds + (bufoff) + ldsw + _i * 8192), 16, 0, 0); } while (0)
; #define PG8_LDA(dst, b, h) do { _Pragma("unroll") for (int m = 0; m < 4; ++m) _Pragma("unroll") for (int k = 0; k < 2; ++k) dst[m][k] = *(const LAS bf16x8*)(lds + PG8_SA(b, h) + aoff + m * 2048 + k * 1024); } while (0)
; #define PG8_LDB(dst, b, h) do { _Pragma("unroll") for (int n = 0; n < 2; ++n) _Pragma("unroll") for (int k = 0; k < 2; ++k) dst[n][k] = *(const LAS bf16x8*)(lds + PG8_SB(b, h) + boff + n * 2048 + k * 1024); } while (0)
; #define PG8_WAIT_V(n) asm volatile("s_waitcnt vmcnt(" #n ")" ::: "memory")
; template <class Epi>
; __device__ __forceinline__ void gemm_phase(LAS unsigned char* lds, const Gemm g, const StaticOrder& S, const Epi& E, const int tid) {
;     ...
;             const bool last = (t == ntt - 2);
;             const bool s1 = Epi::TWO && (t >= nt), s2 = Epi::TWO && (t + 2 >= nt);
;             const char* a1 = (s1 ? cA2 + (size_t)(t - nt + 1) * kstep : cA + (size_t)(t + 1) * kstep);
;             const char* a2 = last ? nA : (s2 ? cA2 + (size_t)(t + 2 - nt) * kstep : cA + (size_t)(t + 2) * kstep);
;             const char* b2 = last ? nB : (s2 ? cB2 + (size_t)(t + 2 - nt) * kstep : cB + (size_t)(t + 2) * kstep);
;             const char* a3 = a2 + kstep; const char* b3 = b2 + kstep;
;             if constexpr (Epi::TWO) { if (t == nt) E.mid(acc, cur, wr, wc, fr, fq); }
;             if constexpr (SP2) {
;             PG8_LDB(B0, 0, 0); PG8_LDB(B1, 0, 1); PG8_SCHED; PG8_LDA(At, 0, 0); PG8_STAGE(PG8_SA(1, 1), a1 + hstep, voffA);
;             PG8_WAIT_V(8); PG8_WAIT_L(0); PG8_BAR; PG8_MMA(0, 0, At, B0); PG8_MMA(0, 1, At, B1); PG8_BAR; PG8_SCHED;
;             PG8_LDA(At, 0, 1); PG8_STAGE(PG8_SB(0, 0), b2, voffB); PG8_STAGE(PG8_SB(0, 1), b2 + bhs, voffB); PG8_STAGE(PG8_SA(0, 0), a2, voffA);
;             PG8_WAIT_V(8); PG8_WAIT_L(0); PG8_BAR; PG8_MMA(1, 0, At, B0); PG8_MMA(1, 1, At, B1); PG8_BAR; PG8_SCHED;
;             PG8_LDB(B0, 1, 0); PG8_LDB(B1, 1, 1); PG8_SCHED; PG8_LDA(At, 1, 0); PG8_STAGE(PG8_SA(0, 1), a2 + hstep, voffA);
;             PG8_WAIT_V(8); PG8_WAIT_L(0); PG8_BAR; PG8_MMA(0, 0, At, B0); PG8_MMA(0, 1, At, B1); PG8_BAR; PG8_SCHED;
.LBB0_173:
	s_add_u32 s28, s26, 0xfff80080
	s_addc_u32 s29, s27, -1
	s_add_i32 s47, 0, 0x10000
	s_cmp_eq_u32 s46, 28
	s_cselect_b32 s31, s17, s29
	s_cselect_b32 s30, s42, s28
	v_add_u32_e32 v142, s47, v149
	s_cselect_b32 s29, s15, s45
	s_cselect_b32 s28, s43, s44
	s_add_i32 s50, 0, 0x14000
	ds_read_b128 v[156:159], v142
	ds_read_b128 v[160:163], v142 offset:1024
	ds_read_b128 v[164:167], v142 offset:2048
	ds_read_b128 v[178:181], v142 offset:3072
	v_add_u32_e32 v142, s50, v149
	ds_read_b128 v[182:185], v142
	ds_read_b128 v[186:189], v142 offset:1024
	ds_read_b128 v[190:193], v142 offset:2048
	ds_read_b128 v[194:197], v142 offset:3072
	v_lshl_add_u64 v[142:143], s[26:27], 0, v[140:141]
	s_add_i32 m0, s2, 0xc000
	ds_read_b128 v[198:201], v154
	global_load_lds_dwordx4 v[142:143], off
	ds_read_b128 v[212:215], v154 offset:1024
	ds_read_b128 v[216:219], v154 offset:2048
	v_lshl_add_u64 v[142:143], s[26:27], 0, v[138:139]
	s_add_i32 m0, s2, 0xe000
	s_nop 0
	global_load_lds_dwordx4 v[142:143], off
	ds_read_b128 v[220:223], v154 offset:3072
	ds_read_b128 v[224:227], v154 offset:4096
	ds_read_b128 v[228:231], v154 offset:5120
	ds_read_b128 v[232:235], v154 offset:6144
	ds_read_b128 v[236:239], v154 offset:7168
	s_waitcnt vmcnt(8)
	s_waitcnt lgkmcnt(0)
	s_barrier
	s_setprio 1
	s_waitcnt lgkmcnt(0)
	v_mfma_f32_16x16x32_bf16 v[126:129], v[156:159], v[198:201], v[126:129]
	v_mfma_f32_16x16x32_bf16 v[122:125], v[164:167], v[198:201], v[122:125]
	v_mfma_f32_16x16x32_bf16 v[110:113], v[156:159], v[216:219], v[110:113]
	v_mfma_f32_16x16x32_bf16 v[106:109], v[164:167], v[216:219], v[106:109]
	v_mfma_f32_16x16x32_bf16 v[94:97], v[156:159], v[224:227], v[94:97]
	v_mfma_f32_16x16x32_bf16 v[90:93], v[164:167], v[224:227], v[90:93]
	v_mfma_f32_16x16x32_bf16 v[78:81], v[156:159], v[232:235], v[78:81]
	v_mfma_f32_16x16x32_bf16 v[74:77], v[164:167], v[232:235], v[74:77]
	v_mfma_f32_16x16x32_bf16 v[126:129], v[160:163], v[212:215], v[126:129]
	v_mfma_f32_16x16x32_bf16 v[122:125], v[178:181], v[212:215], v[122:125]
	v_mfma_f32_16x16x32_bf16 v[110:113], v[160:163], v[220:223], v[110:113]
	v_mfma_f32_16x16x32_bf16 v[106:109], v[178:181], v[220:223], v[106:109]
	v_mfma_f32_16x16x32_bf16 v[94:97], v[160:163], v[228:231], v[94:97]
	v_mfma_f32_16x16x32_bf16 v[90:93], v[178:181], v[228:231], v[90:93]
	v_mfma_f32_16x16x32_bf16 v[78:81], v[160:163], v[236:239], v[78:81]
	v_mfma_f32_16x16x32_bf16 v[74:77], v[178:181], v[236:239], v[74:77]
	s_setprio 0
	s_setprio 1
	v_mfma_f32_16x16x32_bf16 v[118:121], v[182:185], v[198:201], v[118:121]
	v_mfma_f32_16x16x32_bf16 v[114:117], v[190:193], v[198:201], v[114:117]
	v_mfma_f32_16x16x32_bf16 v[102:105], v[182:185], v[216:219], v[102:105]
	v_mfma_f32_16x16x32_bf16 v[98:101], v[190:193], v[216:219], v[98:101]
	v_mfma_f32_16x16x32_bf16 v[86:89], v[182:185], v[224:227], v[86:89]
	v_mfma_f32_16x16x32_bf16 v[82:85], v[190:193], v[224:227], v[82:85]
	v_mfma_f32_16x16x32_bf16 v[70:73], v[182:185], v[232:235], v[70:73]
	v_mfma_f32_16x16x32_bf16 v[66:69], v[190:193], v[232:235], v[66:69]
	v_mfma_f32_16x16x32_bf16 v[118:121], v[186:189], v[212:215], v[118:121]
	v_mfma_f32_16x16x32_bf16 v[114:117], v[194:197], v[212:215], v[114:117]
	v_mfma_f32_16x16x32_bf16 v[102:105], v[186:189], v[220:223], v[102:105]
	v_mfma_f32_16x16x32_bf16 v[98:101], v[194:197], v[220:223], v[98:101]
	v_mfma_f32_16x16x32_bf16 v[86:89], v[186:189], v[228:231], v[86:89]
	v_mfma_f32_16x16x32_bf16 v[82:85], v[194:197], v[228:231], v[82:85]
	v_mfma_f32_16x16x32_bf16 v[70:73], v[186:189], v[236:239], v[70:73]
	v_mfma_f32_16x16x32_bf16 v[66:69], v[194:197], v[236:239], v[66:69]
	s_setprio 0
	s_barrier
	s_add_i32 s47, s47, s34
	v_lshl_add_u64 v[142:143], s[28:29], 0, v[0:1]
	s_mov_b32 m0, s47
	ds_read_b128 v[198:201], v154 offset:16384
	global_load_lds_dwordx4 v[142:143], off
	ds_read_b128 v[212:215], v154 offset:17408
	ds_read_b128 v[216:219], v154 offset:18432
	s_add_i32 m0, s47, 0x2000
	s_add_u32 s48, s28, 0x8000
	v_lshl_add_u64 v[168:169], s[28:29], 0, v[134:135]
	s_addc_u32 s49, s29, 0
	s_add_i32 s47, s50, s34
	global_load_lds_dwordx4 v[168:169], off
	ds_read_b128 v[220:223], v154 offset:19456
	ds_read_b128 v[224:227], v154 offset:20480
	v_lshl_add_u64 v[172:173], s[48:49], 0, v[0:1]
	s_mov_b32 m0, s47
	v_lshl_add_u64 v[174:175], s[30:31], 0, v[132:133]
	global_load_lds_dwordx4 v[172:173], off
	ds_read_b128 v[228:231], v154 offset:21504
	ds_read_b128 v[232:235], v154 offset:22528
	v_lshl_add_u64 v[172:173], s[48:49], 0, v[134:135]
	s_add_i32 m0, s47, 0x2000
	s_nop 0
	global_load_lds_dwordx4 v[172:173], off
	ds_read_b128 v[236:239], v154 offset:23552
	v_lshl_add_u64 v[172:173], s[30:31], 0, v[130:131]
	s_mov_b32 m0, s2
	s_nop 0
	global_load_lds_dwordx4 v[172:173], off
	s_mov_b32 m0, s25
	s_nop 0
	global_load_lds_dwordx4 v[174:175], off
	s_waitcnt vmcnt(8)
	s_waitcnt lgkmcnt(0)
	s_barrier
; #define PG8_STAGE(bufoff, gbase, voff) do { _Pragma("unroll") for (int _i = 0; _i < 2; ++_i) \
;         __builtin_amdgcn_global_load_lds((const unsigned*)((const char*)(gbase) + (voff)[_i]), (LAS unsigned*)(lds + (bufoff) + ldsw + _i * 8192), 16, 0, 0); } while (0)
; #define PG8_LDA(dst, b, h) do { _Pragma("unroll") for (int m = 0; m < 4; ++m) _Pragma("unroll") for (int k = 0; k < 2; ++k) dst[m][k] = *(const LAS bf16x8*)(lds + PG8_SA(b, h) + aoff + m * 2048 + k * 1024); } while (0)
; #define PG8_LDB(dst, b, h) do { _Pragma("unroll") for (int n = 0; n < 2; ++n) _Pragma("unroll") for (int k = 0; k < 2; ++k) dst[n][k] = *(const LAS bf16x8*)(lds + PG8_SB(b, h) + boff + n * 2048 + k * 1024); } while (0)
; #define PG8_MMA(ai, bj, At, Bt) do { __builtin_amdgcn_s_setprio(1); _Pragma("unroll") for (int m = 0; m < 4; ++m) _Pragma("unroll") for (int n = 0; n < 2; ++n) _Pragma("unroll") for (int k = 0; k < 2; ++k) \
;         acc[ai][bj][m][n] = __builtin_amdgcn_mfma_f32_16x16x32_bf16(Bt[n][k], At[m][k], acc[ai][bj][m][n], 0, 0, 0); __builtin_amdgcn_s_setprio(0); } while (0)
; #define PG8_WAIT_V(n) asm volatile("s_waitcnt vmcnt(" #n ")" ::: "memory")
; #define PG8_WAIT_L(n) asm volatile("s_waitcnt lgkmcnt(" #n ")" ::: "memory")
; #define PG8_BAR __builtin_amdgcn_s_barrier()
; #define PG8_SCHED __builtin_amdgcn_sched_barrier(0)
; template <class Epi>
; __device__ __forceinline__ void gemm_phase(LAS unsigned char* lds, const Gemm g, const StaticOrder& S, const Epi& E, const int tid) {
;     ...
;             PG8_WAIT_V(8); PG8_WAIT_L(0); PG8_BAR; PG8_MMA(0, 0, At, B0); PG8_MMA(0, 1, At, B1); PG8_BAR; PG8_SCHED;
;             PG8_LDA(At, 0, 1); PG8_STAGE(PG8_SB(0, 0), b2, voffB); PG8_STAGE(PG8_SB(0, 1), b2 + bhs, voffB); PG8_STAGE(PG8_SA(0, 0), a2, voffA);
;             PG8_WAIT_V(8); PG8_WAIT_L(0); PG8_BAR; PG8_MMA(1, 0, At, B0); PG8_MMA(1, 1, At, B1); PG8_BAR; PG8_SCHED;
;             PG8_LDB(B0, 1, 0); PG8_LDB(B1, 1, 1); PG8_SCHED; PG8_LDA(At, 1, 0); PG8_STAGE(PG8_SA(0, 1), a2 + hstep, voffA);
;             PG8_WAIT_V(8); PG8_WAIT_L(0); PG8_BAR; PG8_MMA(0, 0, At, B0); PG8_MMA(0, 1, At, B1); PG8_BAR; PG8_SCHED;
	s_setprio 1
	s_waitcnt lgkmcnt(0)
	v_mfma_f32_16x16x32_bf16 v[62:65], v[156:159], v[198:201], v[62:65]
	v_mfma_f32_16x16x32_bf16 v[58:61], v[164:167], v[198:201], v[58:61]
	v_mfma_f32_16x16x32_bf16 v[46:49], v[156:159], v[216:219], v[46:49]
	v_mfma_f32_16x16x32_bf16 v[42:45], v[164:167], v[216:219], v[42:45]
	v_mfma_f32_16x16x32_bf16 v[30:33], v[156:159], v[224:227], v[30:33]
	v_mfma_f32_16x16x32_bf16 v[26:29], v[164:167], v[224:227], v[26:29]
	v_mfma_f32_16x16x32_bf16 v[14:17], v[156:159], v[232:235], v[14:17]
	v_mfma_f32_16x16x32_bf16 v[10:13], v[164:167], v[232:235], v[10:13]
	v_mfma_f32_16x16x32_bf16 v[62:65], v[160:163], v[212:215], v[62:65]
	v_mfma_f32_16x16x32_bf16 v[58:61], v[178:181], v[212:215], v[58:61]
	v_mfma_f32_16x16x32_bf16 v[46:49], v[160:163], v[220:223], v[46:49]
	v_mfma_f32_16x16x32_bf16 v[42:45], v[178:181], v[220:223], v[42:45]
	v_mfma_f32_16x16x32_bf16 v[30:33], v[160:163], v[228:231], v[30:33]
	v_mfma_f32_16x16x32_bf16 v[26:29], v[178:181], v[228:231], v[26:29]
	v_mfma_f32_16x16x32_bf16 v[14:17], v[160:163], v[236:239], v[14:17]
	v_mfma_f32_16x16x32_bf16 v[10:13], v[178:181], v[236:239], v[10:13]
	s_setprio 0
	s_setprio 1
	v_mfma_f32_16x16x32_bf16 v[54:57], v[182:185], v[198:201], v[54:57]
	v_mfma_f32_16x16x32_bf16 v[50:53], v[190:193], v[198:201], v[50:53]
	v_mfma_f32_16x16x32_bf16 v[38:41], v[182:185], v[216:219], v[38:41]
	v_mfma_f32_16x16x32_bf16 v[34:37], v[190:193], v[216:219], v[34:37]
	v_mfma_f32_16x16x32_bf16 v[22:25], v[182:185], v[224:227], v[22:25]
	v_mfma_f32_16x16x32_bf16 v[18:21], v[190:193], v[224:227], v[18:21]
	v_mfma_f32_16x16x32_bf16 v[6:9], v[182:185], v[232:235], v[6:9]
	v_mfma_f32_16x16x32_bf16 v[2:5], v[190:193], v[232:235], v[2:5]
	v_mfma_f32_16x16x32_bf16 v[54:57], v[186:189], v[212:215], v[54:57]
	v_mfma_f32_16x16x32_bf16 v[50:53], v[194:197], v[212:215], v[50:53]
	v_mfma_f32_16x16x32_bf16 v[38:41], v[186:189], v[220:223], v[38:41]
	v_mfma_f32_16x16x32_bf16 v[34:37], v[194:197], v[220:223], v[34:37]
	v_mfma_f32_16x16x32_bf16 v[22:25], v[186:189], v[228:231], v[22:25]
	v_mfma_f32_16x16x32_bf16 v[18:21], v[194:197], v[228:231], v[18:21]
	v_mfma_f32_16x16x32_bf16 v[6:9], v[186:189], v[236:239], v[6:9]
	v_mfma_f32_16x16x32_bf16 v[2:5], v[194:197], v[236:239], v[2:5]
	s_setprio 0
	s_barrier
	s_add_i32 s47, 0, 0x18000
	v_add_u32_e32 v155, s47, v149
	s_add_i32 s48, 0, 0x1c000
	ds_read_b128 v[156:159], v155
	ds_read_b128 v[160:163], v155 offset:1024
	ds_read_b128 v[164:167], v155 offset:2048
	ds_read_b128 v[178:181], v155 offset:3072
	v_add_u32_e32 v155, s48, v149
	ds_read_b128 v[182:185], v155
	ds_read_b128 v[186:189], v155 offset:1024
	ds_read_b128 v[190:193], v155 offset:2048
	ds_read_b128 v[194:197], v155 offset:3072
	s_add_u32 s30, s30, 0x80000
	s_addc_u32 s31, s31, 0
	s_mov_b32 m0, s35
	v_lshl_add_u64 v[176:177], s[30:31], 0, v[130:131]
	ds_read_b128 v[198:201], v154 offset:32768
	global_load_lds_dwordx4 v[176:177], off
	ds_read_b128 v[212:215], v154 offset:33792
	ds_read_b128 v[216:219], v154 offset:34816
	v_lshl_add_u64 v[176:177], s[30:31], 0, v[132:133]
	s_mov_b32 m0, s36
	s_nop 0
	global_load_lds_dwordx4 v[176:177], off
	ds_read_b128 v[220:223], v154 offset:35840
	ds_read_b128 v[224:227], v154 offset:36864
	ds_read_b128 v[228:231], v154 offset:37888
	ds_read_b128 v[232:235], v154 offset:38912
	ds_read_b128 v[236:239], v154 offset:39936
	s_waitcnt vmcnt(8)
	s_waitcnt lgkmcnt(0)
	s_barrier
	s_setprio 1
	s_waitcnt lgkmcnt(0)
	v_mfma_f32_16x16x32_bf16 v[126:129], v[156:159], v[198:201], v[126:129]
	v_mfma_f32_16x16x32_bf16 v[122:125], v[164:167], v[198:201], v[122:125]
	v_mfma_f32_16x16x32_bf16 v[110:113], v[156:159], v[216:219], v[110:113]
	v_mfma_f32_16x16x32_bf16 v[106:109], v[164:167], v[216:219], v[106:109]
	v_mfma_f32_16x16x32_bf16 v[94:97], v[156:159], v[224:227], v[94:97]
	v_mfma_f32_16x16x32_bf16 v[90:93], v[164:167], v[224:227], v[90:93]
	v_mfma_f32_16x16x32_bf16 v[78:81], v[156:159], v[232:235], v[78:81]
	v_mfma_f32_16x16x32_bf16 v[74:77], v[164:167], v[232:235], v[74:77]
	v_mfma_f32_16x16x32_bf16 v[126:129], v[160:163], v[212:215], v[126:129]
	v_mfma_f32_16x16x32_bf16 v[122:125], v[178:181], v[212:215], v[122:125]
	v_mfma_f32_16x16x32_bf16 v[110:113], v[160:163], v[220:223], v[110:113]
	v_mfma_f32_16x16x32_bf16 v[106:109], v[178:181], v[220:223], v[106:109]
	v_mfma_f32_16x16x32_bf16 v[94:97], v[160:163], v[228:231], v[94:97]
	v_mfma_f32_16x16x32_bf16 v[90:93], v[178:181], v[228:231], v[90:93]
	v_mfma_f32_16x16x32_bf16 v[78:81], v[160:163], v[236:239], v[78:81]
	v_mfma_f32_16x16x32_bf16 v[74:77], v[178:181], v[236:239], v[74:77]
	s_setprio 0
	s_setprio 1
	v_mfma_f32_16x16x32_bf16 v[118:121], v[182:185], v[198:201], v[118:121]
	v_mfma_f32_16x16x32_bf16 v[114:117], v[190:193], v[198:201], v[114:117]
	v_mfma_f32_16x16x32_bf16 v[102:105], v[182:185], v[216:219], v[102:105]
	v_mfma_f32_16x16x32_bf16 v[98:101], v[190:193], v[216:219], v[98:101]
	v_mfma_f32_16x16x32_bf16 v[86:89], v[182:185], v[224:227], v[86:89]
	v_mfma_f32_16x16x32_bf16 v[82:85], v[190:193], v[224:227], v[82:85]
	v_mfma_f32_16x16x32_bf16 v[70:73], v[182:185], v[232:235], v[70:73]
	v_mfma_f32_16x16x32_bf16 v[66:69], v[190:193], v[232:235], v[66:69]
	v_mfma_f32_16x16x32_bf16 v[118:121], v[186:189], v[212:215], v[118:121]
	v_mfma_f32_16x16x32_bf16 v[114:117], v[194:197], v[212:215], v[114:117]
	v_mfma_f32_16x16x32_bf16 v[102:105], v[186:189], v[220:223], v[102:105]
	v_mfma_f32_16x16x32_bf16 v[98:101], v[194:197], v[220:223], v[98:101]
	v_mfma_f32_16x16x32_bf16 v[86:89], v[186:189], v[228:231], v[86:89]
	v_mfma_f32_16x16x32_bf16 v[82:85], v[194:197], v[228:231], v[82:85]
	v_mfma_f32_16x16x32_bf16 v[70:73], v[186:189], v[236:239], v[70:73]
	v_mfma_f32_16x16x32_bf16 v[66:69], v[194:197], v[236:239], v[66:69]
	s_setprio 0
	s_barrier
; #define PG8_STAGE(bufoff, gbase, voff) do { _Pragma("unroll") for (int _i = 0; _i < 2; ++_i) \
;         __builtin_amdgcn_global_load_lds((const unsigned*)((const char*)(gbase) + (voff)[_i]), (LAS unsigned*)(lds + (bufoff) + ldsw + _i * 8192), 16, 0, 0); } while (0)
; #define PG8_LDA(dst, b, h) do { _Pragma("unroll") for (int m = 0; m < 4; ++m) _Pragma("unroll") for (int k = 0; k < 2; ++k) dst[m][k] = *(const LAS bf16x8*)(lds + PG8_SA(b, h) + aoff + m * 2048 + k * 1024); } while (0)
; #define PG8_MMA(ai, bj, At, Bt) do { __builtin_amdgcn_s_setprio(1); _Pragma("unroll") for (int m = 0; m < 4; ++m) _Pragma("unroll") for (int n = 0; n < 2; ++n) _Pragma("unroll") for (int k = 0; k < 2; ++k) \
;         acc[ai][bj][m][n] = __builtin_amdgcn_mfma_f32_16x16x32_bf16(Bt[n][k], At[m][k], acc[ai][bj][m][n], 0, 0, 0); __builtin_amdgcn_s_setprio(0); } while (0)
; #define PG8_WAIT_V(n) asm volatile("s_waitcnt vmcnt(" #n ")" ::: "memory")
; #define PG8_WAIT_L(n) asm volatile("s_waitcnt lgkmcnt(" #n ")" ::: "memory")
; #define PG8_BAR __builtin_amdgcn_s_barrier()
; #define PG8_SCHED __builtin_amdgcn_sched_barrier(0)
; template <class Epi>
; __device__ __forceinline__ void gemm_phase(LAS unsigned char* lds, const Gemm g, const StaticOrder& S, const Epi& E, const int tid) {
;     ...
;         for (int t = 0; t < ntt; t += 2) {
;     ...
;             PG8_LDA(At, 1, 1); PG8_STAGE(PG8_SB(1, 0), b3, voffB); PG8_STAGE(PG8_SB(1, 1), b3 + bhs, voffB); PG8_STAGE(PG8_SA(1, 0), a3, voffA);
;             PG8_WAIT_V(8); PG8_WAIT_L(0); PG8_BAR; PG8_MMA(1, 0, At, B0); PG8_MMA(1, 1, At, B1); PG8_BAR; PG8_SCHED;
	s_add_i32 s30, s47, s34
	v_lshl_add_u64 v[142:143], v[142:143], 0, s[70:71]
	s_mov_b32 m0, s30
	ds_read_b128 v[198:201], v154 offset:49152
	global_load_lds_dwordx4 v[142:143], off
	ds_read_b128 v[212:215], v154 offset:50176
	ds_read_b128 v[216:219], v154 offset:51200
	s_add_i32 m0, s30, 0x2000
	s_add_u32 s28, s28, 0x8080
	v_lshl_add_u64 v[142:143], v[168:169], 0, s[70:71]
	s_addc_u32 s29, s29, 0
	s_add_i32 s30, s48, s34
	global_load_lds_dwordx4 v[142:143], off
	ds_read_b128 v[220:223], v154 offset:52224
	ds_read_b128 v[224:227], v154 offset:53248
	v_lshl_add_u64 v[142:143], s[28:29], 0, v[0:1]
	s_mov_b32 m0, s30
	s_nop 0
	global_load_lds_dwordx4 v[142:143], off
	ds_read_b128 v[228:231], v154 offset:54272
	ds_read_b128 v[232:235], v154 offset:55296
	v_lshl_add_u64 v[142:143], s[28:29], 0, v[134:135]
	s_add_i32 m0, s30, 0x2000
	s_nop 0
	global_load_lds_dwordx4 v[142:143], off
	ds_read_b128 v[236:239], v154 offset:56320
	v_lshl_add_u64 v[142:143], v[172:173], 0, s[70:71]
	s_mov_b32 m0, s37
	s_nop 0
	global_load_lds_dwordx4 v[142:143], off
	v_lshl_add_u64 v[142:143], v[174:175], 0, s[70:71]
	s_mov_b32 m0, s38
	s_nop 0
	global_load_lds_dwordx4 v[142:143], off
	s_waitcnt vmcnt(8)
	s_waitcnt lgkmcnt(0)
	s_barrier
	s_setprio 1
	s_waitcnt lgkmcnt(0)
	v_mfma_f32_16x16x32_bf16 v[62:65], v[156:159], v[198:201], v[62:65]
	v_mfma_f32_16x16x32_bf16 v[58:61], v[164:167], v[198:201], v[58:61]
	v_mfma_f32_16x16x32_bf16 v[46:49], v[156:159], v[216:219], v[46:49]
	v_mfma_f32_16x16x32_bf16 v[42:45], v[164:167], v[216:219], v[42:45]
	v_mfma_f32_16x16x32_bf16 v[30:33], v[156:159], v[224:227], v[30:33]
	v_mfma_f32_16x16x32_bf16 v[26:29], v[164:167], v[224:227], v[26:29]
	v_mfma_f32_16x16x32_bf16 v[14:17], v[156:159], v[232:235], v[14:17]
	v_mfma_f32_16x16x32_bf16 v[10:13], v[164:167], v[232:235], v[10:13]
	v_mfma_f32_16x16x32_bf16 v[62:65], v[160:163], v[212:215], v[62:65]
	v_mfma_f32_16x16x32_bf16 v[58:61], v[178:181], v[212:215], v[58:61]
	v_mfma_f32_16x16x32_bf16 v[46:49], v[160:163], v[220:223], v[46:49]
	v_mfma_f32_16x16x32_bf16 v[42:45], v[178:181], v[220:223], v[42:45]
	v_mfma_f32_16x16x32_bf16 v[30:33], v[160:163], v[228:231], v[30:33]
	v_mfma_f32_16x16x32_bf16 v[26:29], v[178:181], v[228:231], v[26:29]
	v_mfma_f32_16x16x32_bf16 v[14:17], v[160:163], v[236:239], v[14:17]
	v_mfma_f32_16x16x32_bf16 v[10:13], v[178:181], v[236:239], v[10:13]
	s_setprio 0
	s_setprio 1
	v_mfma_f32_16x16x32_bf16 v[54:57], v[182:185], v[198:201], v[54:57]
	v_mfma_f32_16x16x32_bf16 v[50:53], v[190:193], v[198:201], v[50:53]
	v_mfma_f32_16x16x32_bf16 v[38:41], v[182:185], v[216:219], v[38:41]
	v_mfma_f32_16x16x32_bf16 v[34:37], v[190:193], v[216:219], v[34:37]
	v_mfma_f32_16x16x32_bf16 v[22:25], v[182:185], v[224:227], v[22:25]
	v_mfma_f32_16x16x32_bf16 v[18:21], v[190:193], v[224:227], v[18:21]
	v_mfma_f32_16x16x32_bf16 v[6:9], v[182:185], v[232:235], v[6:9]
	v_mfma_f32_16x16x32_bf16 v[2:5], v[190:193], v[232:235], v[2:5]
	v_mfma_f32_16x16x32_bf16 v[54:57], v[186:189], v[212:215], v[54:57]
	v_mfma_f32_16x16x32_bf16 v[50:53], v[194:197], v[212:215], v[50:53]
	v_mfma_f32_16x16x32_bf16 v[38:41], v[186:189], v[220:223], v[38:41]
	v_mfma_f32_16x16x32_bf16 v[34:37], v[194:197], v[220:223], v[34:37]
	v_mfma_f32_16x16x32_bf16 v[22:25], v[186:189], v[228:231], v[22:25]
	v_mfma_f32_16x16x32_bf16 v[18:21], v[194:197], v[228:231], v[18:21]
	v_mfma_f32_16x16x32_bf16 v[6:9], v[186:189], v[236:239], v[6:9]
	v_mfma_f32_16x16x32_bf16 v[2:5], v[194:197], v[236:239], v[2:5]
	s_setprio 0
	s_barrier
	s_add_i32 s46, s46, 2
	s_add_u32 s44, s44, 0x100
	s_addc_u32 s45, s45, 0
	s_add_u32 s26, s26, 0x100
	s_addc_u32 s27, s27, 0
	s_cmp_gt_u32 s46, 29
	s_cbranch_scc0 .LBB0_173
	v_readlane_b32 s42, v251, 53
	s_and_b64 vcc, exec, s[12:13]
	v_readlane_b32 s43, v251, 54
	s_cbranch_vccz .LBB0_176
	s_barrier

; #define PG8_STAGE(bufoff, gbase, voff) do { _Pragma("unroll") for (int _i = 0; _i < 2; ++_i) \
;         __builtin_amdgcn_global_load_lds((const unsigned*)((const char*)(gbase) + (voff)[_i]), (LAS unsigned*)(lds + (bufoff) + ldsw + _i * 8192), 16, 0, 0); } while (0)
; #define PG8_LDA(dst, b, h) do { _Pragma("unroll") for (int m = 0; m < 4; ++m) _Pragma("unroll") for (int k = 0; k < 2; ++k) dst[m][k] = *(const LAS bf16x8*)(lds + PG8_SA(b, h) + aoff + m * 2048 + k * 1024); } while (0)
; #define PG8_LDB(dst, b, h) do { _Pragma("unroll") for (int n = 0; n < 2; ++n) _Pragma("unroll") for (int k = 0; k < 2; ++k) dst[n][k] = *(const LAS bf16x8*)(lds + PG8_SB(b, h) + boff + n * 2048 + k * 1024); } while (0)
; #define PG8_WAIT_V(n) asm volatile("s_waitcnt vmcnt(" #n ")" ::: "memory")
; template <class Epi>
; __device__ __forceinline__ void gemm_phase(LAS unsigned char* lds, const Gemm g, const StaticOrder& S, const Epi& E, const int tid) {
;     ...
;             const bool last = (t == ntt - 2);
;             const bool s1 = Epi::TWO && (t >= nt), s2 = Epi::TWO && (t + 2 >= nt);
;             const char* a1 = (s1 ? cA2 + (size_t)(t - nt + 1) * kstep : cA + (size_t)(t + 1) * kstep);
;             const char* a2 = last ? nA : (s2 ? cA2 + (size_t)(t + 2 - nt) * kstep : cA + (size_t)(t + 2) * kstep);
;             const char* b2 = last ? nB : (s2 ? cB2 + (size_t)(t + 2 - nt) * kstep : cB + (size_t)(t + 2) * kstep);
;             const char* a3 = a2 + kstep; const char* b3 = b2 + kstep;
;             if constexpr (Epi::TWO) { if (t == nt) E.mid(acc, cur, wr, wc, fr, fq); }
;             if constexpr (SP2) {
;             PG8_LDB(B0, 0, 0); PG8_LDB(B1, 0, 1); PG8_SCHED; PG8_LDA(At, 0, 0); PG8_STAGE(PG8_SA(1, 1), a1 + hstep, voffA);
;             PG8_WAIT_V(8); PG8_WAIT_L(0); PG8_BAR; PG8_MMA(0, 0, At, B0); PG8_MMA(0, 1, At, B1); PG8_BAR; PG8_SCHED;
;             PG8_LDA(At, 0, 1); PG8_STAGE(PG8_SB(0, 0), b2, voffB); PG8_STAGE(PG8_SB(0, 1), b2 + bhs, voffB); PG8_STAGE(PG8_SA(0, 0), a2, voffA);
;             PG8_WAIT_V(8); PG8_WAIT_L(0); PG8_BAR; PG8_MMA(1, 0, At, B0); PG8_MMA(1, 1, At, B1); PG8_BAR; PG8_SCHED;
;             PG8_LDB(B0, 1, 0); PG8_LDB(B1, 1, 1); PG8_SCHED; PG8_LDA(At, 1, 0); PG8_STAGE(PG8_SA(0, 1), a2 + hstep, voffA);
;             PG8_WAIT_V(8); PG8_WAIT_L(0); PG8_BAR; PG8_MMA(0, 0, At, B0); PG8_MMA(0, 1, At, B1); PG8_BAR; PG8_SCHED;
.LBB0_206:
	s_add_u32 s30, s28, 0xfffe0080
	s_addc_u32 s31, s29, -1
	s_add_i32 s52, 0, 0x10000
	s_cmp_eq_u32 s51, 4
	s_cselect_b32 s35, s17, s31
	s_cselect_b32 s34, s27, s30
	s_cselect_b32 s31, s15, s50
	s_cselect_b32 s30, s33, s49
	s_add_i32 s54, 0, 0x14000
	v_add_u32_e32 v30, s52, v193
	v_add_u32_e32 v54, s54, v193
	ds_read_b128 v[18:21], v30
	ds_read_b128 v[22:25], v30 offset:1024
	ds_read_b128 v[26:29], v30 offset:2048
	ds_read_b128 v[30:33], v30 offset:3072
	ds_read_b128 v[42:45], v54
	ds_read_b128 v[46:49], v54 offset:1024
	ds_read_b128 v[50:53], v54 offset:2048
	ds_read_b128 v[54:57], v54 offset:3072
	v_lshl_add_u64 v[172:173], s[28:29], 0, v[180:181]
	s_add_i32 m0, s37, 0xc000
	ds_read_b128 v[182:185], v199
	global_load_lds_dwordx4 v[172:173], off
	ds_read_b128 v[186:189], v199 offset:1024
	ds_read_b128 v[212:215], v199 offset:2048
	v_lshl_add_u64 v[172:173], s[28:29], 0, v[178:179]
	s_add_i32 m0, s37, 0xe000
	s_nop 0
	global_load_lds_dwordx4 v[172:173], off
	ds_read_b128 v[216:219], v199 offset:3072
	ds_read_b128 v[220:223], v199 offset:4096
	ds_read_b128 v[224:227], v199 offset:5120
	ds_read_b128 v[228:231], v199 offset:6144
	ds_read_b128 v[232:235], v199 offset:7168
	s_waitcnt vmcnt(8)
	s_waitcnt lgkmcnt(0)
	s_barrier
	s_setprio 1
	s_waitcnt lgkmcnt(0)
	v_mfma_f32_16x16x32_bf16 v[158:161], v[18:21], v[182:185], v[158:161]
	v_mfma_f32_16x16x32_bf16 v[154:157], v[26:29], v[182:185], v[154:157]
	v_mfma_f32_16x16x32_bf16 v[142:145], v[18:21], v[212:215], v[142:145]
	v_mfma_f32_16x16x32_bf16 v[138:141], v[26:29], v[212:215], v[138:141]
	v_mfma_f32_16x16x32_bf16 v[126:129], v[18:21], v[220:223], v[126:129]
	v_mfma_f32_16x16x32_bf16 v[122:125], v[26:29], v[220:223], v[122:125]
	v_mfma_f32_16x16x32_bf16 v[110:113], v[18:21], v[228:231], v[110:113]
	v_mfma_f32_16x16x32_bf16 v[106:109], v[26:29], v[228:231], v[106:109]
	v_mfma_f32_16x16x32_bf16 v[158:161], v[22:25], v[186:189], v[158:161]
	v_mfma_f32_16x16x32_bf16 v[154:157], v[30:33], v[186:189], v[154:157]
	v_mfma_f32_16x16x32_bf16 v[142:145], v[22:25], v[216:219], v[142:145]
	v_mfma_f32_16x16x32_bf16 v[138:141], v[30:33], v[216:219], v[138:141]
	v_mfma_f32_16x16x32_bf16 v[126:129], v[22:25], v[224:227], v[126:129]
	v_mfma_f32_16x16x32_bf16 v[122:125], v[30:33], v[224:227], v[122:125]
	v_mfma_f32_16x16x32_bf16 v[110:113], v[22:25], v[232:235], v[110:113]
	v_mfma_f32_16x16x32_bf16 v[106:109], v[30:33], v[232:235], v[106:109]
	s_setprio 0
	s_setprio 1
	v_mfma_f32_16x16x32_bf16 v[150:153], v[42:45], v[182:185], v[150:153]
	v_mfma_f32_16x16x32_bf16 v[146:149], v[50:53], v[182:185], v[146:149]
	v_mfma_f32_16x16x32_bf16 v[134:137], v[42:45], v[212:215], v[134:137]
	v_mfma_f32_16x16x32_bf16 v[130:133], v[50:53], v[212:215], v[130:133]
	v_mfma_f32_16x16x32_bf16 v[118:121], v[42:45], v[220:223], v[118:121]
	v_mfma_f32_16x16x32_bf16 v[114:117], v[50:53], v[220:223], v[114:117]
	v_mfma_f32_16x16x32_bf16 v[102:105], v[42:45], v[228:231], v[102:105]
	v_mfma_f32_16x16x32_bf16 v[98:101], v[50:53], v[228:231], v[98:101]
	v_mfma_f32_16x16x32_bf16 v[150:153], v[46:49], v[186:189], v[150:153]
	v_mfma_f32_16x16x32_bf16 v[146:149], v[54:57], v[186:189], v[146:149]
	v_mfma_f32_16x16x32_bf16 v[134:137], v[46:49], v[216:219], v[134:137]
	v_mfma_f32_16x16x32_bf16 v[130:133], v[54:57], v[216:219], v[130:133]
	v_mfma_f32_16x16x32_bf16 v[118:121], v[46:49], v[224:227], v[118:121]
	v_mfma_f32_16x16x32_bf16 v[114:117], v[54:57], v[224:227], v[114:117]
	v_mfma_f32_16x16x32_bf16 v[102:105], v[46:49], v[232:235], v[102:105]
	v_mfma_f32_16x16x32_bf16 v[98:101], v[54:57], v[232:235], v[98:101]
	s_setprio 0
	s_barrier
	s_add_i32 s52, s52, s36
	v_lshl_add_u64 v[172:173], s[30:31], 0, v[0:1]
	s_mov_b32 m0, s52
	ds_read_b128 v[182:185], v199 offset:16384
	global_load_lds_dwordx4 v[172:173], off
	ds_read_b128 v[186:189], v199 offset:17408
	ds_read_b128 v[212:215], v199 offset:18432
	s_add_i32 m0, s52, 0x2000
	s_add_u32 s52, s30, 0x2000
	v_lshl_add_u64 v[174:175], s[30:31], 0, v[166:167]
	s_addc_u32 s53, s31, 0
	s_add_i32 s54, s54, s36
	global_load_lds_dwordx4 v[174:175], off
	ds_read_b128 v[216:219], v199 offset:19456
	ds_read_b128 v[220:223], v199 offset:20480
	v_lshl_add_u64 v[176:177], s[52:53], 0, v[0:1]
	s_mov_b32 m0, s54
	v_lshl_add_u64 v[200:201], s[34:35], 0, v[164:165]
	global_load_lds_dwordx4 v[176:177], off
	ds_read_b128 v[224:227], v199 offset:21504
	ds_read_b128 v[228:231], v199 offset:22528
	v_lshl_add_u64 v[176:177], s[52:53], 0, v[166:167]
	s_add_i32 m0, s54, 0x2000
	s_nop 0
	global_load_lds_dwordx4 v[176:177], off
	ds_read_b128 v[232:235], v199 offset:23552
	v_lshl_add_u64 v[176:177], s[34:35], 0, v[162:163]
	s_mov_b32 m0, s37
	s_nop 0
	global_load_lds_dwordx4 v[176:177], off
	s_mov_b32 m0, s38
	s_nop 0
	global_load_lds_dwordx4 v[200:201], off
	s_waitcnt vmcnt(8)
	s_waitcnt lgkmcnt(0)
	s_barrier
; #define PG8_STAGE(bufoff, gbase, voff) do { _Pragma("unroll") for (int _i = 0; _i < 2; ++_i) \
;         __builtin_amdgcn_global_load_lds((const unsigned*)((const char*)(gbase) + (voff)[_i]), (LAS unsigned*)(lds + (bufoff) + ldsw + _i * 8192), 16, 0, 0); } while (0)
; #define PG8_LDA(dst, b, h) do { _Pragma("unroll") for (int m = 0; m < 4; ++m) _Pragma("unroll") for (int k = 0; k < 2; ++k) dst[m][k] = *(const LAS bf16x8*)(lds + PG8_SA(b, h) + aoff + m * 2048 + k * 1024); } while (0)
; #define PG8_LDB(dst, b, h) do { _Pragma("unroll") for (int n = 0; n < 2; ++n) _Pragma("unroll") for (int k = 0; k < 2; ++k) dst[n][k] = *(const LAS bf16x8*)(lds + PG8_SB(b, h) + boff + n * 2048 + k * 1024); } while (0)
; #define PG8_MMA(ai, bj, At, Bt) do { __builtin_amdgcn_s_setprio(1); _Pragma("unroll") for (int m = 0; m < 4; ++m) _Pragma("unroll") for (int n = 0; n < 2; ++n) _Pragma("unroll") for (int k = 0; k < 2; ++k) \
;         acc[ai][bj][m][n] = __builtin_amdgcn_mfma_f32_16x16x32_bf16(Bt[n][k], At[m][k], acc[ai][bj][m][n], 0, 0, 0); __builtin_amdgcn_s_setprio(0); } while (0)
; #define PG8_WAIT_V(n) asm volatile("s_waitcnt vmcnt(" #n ")" ::: "memory")
; #define PG8_WAIT_L(n) asm volatile("s_waitcnt lgkmcnt(" #n ")" ::: "memory")
; #define PG8_BAR __builtin_amdgcn_s_barrier()
; #define PG8_SCHED __builtin_amdgcn_sched_barrier(0)
; template <class Epi>
; __device__ __forceinline__ void gemm_phase(LAS unsigned char* lds, const Gemm g, const StaticOrder& S, const Epi& E, const int tid) {
;     ...
;             PG8_WAIT_V(8); PG8_WAIT_L(0); PG8_BAR; PG8_MMA(1, 0, At, B0); PG8_MMA(1, 1, At, B1); PG8_BAR; PG8_SCHED;
;             PG8_LDB(B0, 1, 0); PG8_LDB(B1, 1, 1); PG8_SCHED; PG8_LDA(At, 1, 0); PG8_STAGE(PG8_SA(0, 1), a2 + hstep, voffA);
;             PG8_WAIT_V(8); PG8_WAIT_L(0); PG8_BAR; PG8_MMA(0, 0, At, B0); PG8_MMA(0, 1, At, B1); PG8_BAR; PG8_SCHED;
;             PG8_LDA(At, 1, 1); PG8_STAGE(PG8_SB(1, 0), b3, voffB); PG8_STAGE(PG8_SB(1, 1), b3 + bhs, voffB); PG8_STAGE(PG8_SA(1, 0), a3, voffA);
	s_setprio 1
	s_waitcnt lgkmcnt(0)
	v_mfma_f32_16x16x32_bf16 v[94:97], v[18:21], v[182:185], v[94:97]
	v_mfma_f32_16x16x32_bf16 v[90:93], v[26:29], v[182:185], v[90:93]
	v_mfma_f32_16x16x32_bf16 v[78:81], v[18:21], v[212:215], v[78:81]
	v_mfma_f32_16x16x32_bf16 v[74:77], v[26:29], v[212:215], v[74:77]
	v_mfma_f32_16x16x32_bf16 v[62:65], v[18:21], v[220:223], v[62:65]
	v_mfma_f32_16x16x32_bf16 v[58:61], v[26:29], v[220:223], v[58:61]
	v_mfma_f32_16x16x32_bf16 v[14:17], v[18:21], v[228:231], v[14:17]
	v_mfma_f32_16x16x32_bf16 v[10:13], v[26:29], v[228:231], v[10:13]
	v_mfma_f32_16x16x32_bf16 v[94:97], v[22:25], v[186:189], v[94:97]
	v_mfma_f32_16x16x32_bf16 v[90:93], v[30:33], v[186:189], v[90:93]
	v_mfma_f32_16x16x32_bf16 v[78:81], v[22:25], v[216:219], v[78:81]
	v_mfma_f32_16x16x32_bf16 v[74:77], v[30:33], v[216:219], v[74:77]
	v_mfma_f32_16x16x32_bf16 v[62:65], v[22:25], v[224:227], v[62:65]
	v_mfma_f32_16x16x32_bf16 v[58:61], v[30:33], v[224:227], v[58:61]
	v_mfma_f32_16x16x32_bf16 v[14:17], v[22:25], v[232:235], v[14:17]
	v_mfma_f32_16x16x32_bf16 v[10:13], v[30:33], v[232:235], v[10:13]
	s_setprio 0
	s_setprio 1
	v_mfma_f32_16x16x32_bf16 v[38:41], v[42:45], v[220:223], v[38:41]
	v_mfma_f32_16x16x32_bf16 v[34:37], v[50:53], v[220:223], v[34:37]
	v_mfma_f32_16x16x32_bf16 v[6:9], v[42:45], v[228:231], v[6:9]
	v_mfma_f32_16x16x32_bf16 v[2:5], v[50:53], v[228:231], v[2:5]
	v_mfma_f32_16x16x32_bf16 v[18:21], v[42:45], v[182:185], v[86:89]
	v_mfma_f32_16x16x32_bf16 v[22:25], v[50:53], v[182:185], v[82:85]
	v_mfma_f32_16x16x32_bf16 v[26:29], v[42:45], v[212:215], v[70:73]
	v_mfma_f32_16x16x32_bf16 v[30:33], v[50:53], v[212:215], v[66:69]
	v_mfma_f32_16x16x32_bf16 v[38:41], v[46:49], v[224:227], v[38:41]
	v_mfma_f32_16x16x32_bf16 v[34:37], v[54:57], v[224:227], v[34:37]
	v_mfma_f32_16x16x32_bf16 v[6:9], v[46:49], v[232:235], v[6:9]
	v_mfma_f32_16x16x32_bf16 v[2:5], v[54:57], v[232:235], v[2:5]
	v_mfma_f32_16x16x32_bf16 v[18:21], v[46:49], v[186:189], v[18:21]
	v_mfma_f32_16x16x32_bf16 v[22:25], v[54:57], v[186:189], v[22:25]
	v_mfma_f32_16x16x32_bf16 v[26:29], v[46:49], v[216:219], v[26:29]
	v_mfma_f32_16x16x32_bf16 v[30:33], v[54:57], v[216:219], v[30:33]
	s_setprio 0
	s_barrier
	s_add_i32 s52, 0, 0x18000
	s_add_i32 s53, 0, 0x1c000
	v_add_u32_e32 v54, s52, v193
	v_add_u32_e32 v66, s53, v193
	ds_read_b128 v[42:45], v54
	ds_read_b128 v[46:49], v54 offset:1024
	ds_read_b128 v[50:53], v54 offset:2048
	ds_read_b128 v[54:57], v54 offset:3072
	ds_read_b128 v[182:185], v66
	ds_read_b128 v[186:189], v66 offset:1024
	ds_read_b128 v[212:215], v66 offset:2048
	ds_read_b128 v[216:219], v66 offset:3072
	s_add_u32 s34, s34, 0x20000
	s_addc_u32 s35, s35, 0
	s_mov_b32 m0, s39
	v_lshl_add_u64 v[236:237], s[34:35], 0, v[162:163]
	ds_read_b128 v[66:69], v199 offset:32768
	global_load_lds_dwordx4 v[236:237], off
	ds_read_b128 v[70:73], v199 offset:33792
	ds_read_b128 v[82:85], v199 offset:34816
	v_lshl_add_u64 v[236:237], s[34:35], 0, v[164:165]
	s_mov_b32 m0, s44
	s_nop 0
	global_load_lds_dwordx4 v[236:237], off
	ds_read_b128 v[86:89], v199 offset:35840
	ds_read_b128 v[220:223], v199 offset:36864
	ds_read_b128 v[224:227], v199 offset:37888
	ds_read_b128 v[228:231], v199 offset:38912
	ds_read_b128 v[232:235], v199 offset:39936
	s_waitcnt vmcnt(8)
	s_waitcnt lgkmcnt(0)
	s_barrier
	s_setprio 1
	s_waitcnt lgkmcnt(0)
	v_mfma_f32_16x16x32_bf16 v[158:161], v[42:45], v[66:69], v[158:161]
	v_mfma_f32_16x16x32_bf16 v[154:157], v[50:53], v[66:69], v[154:157]
	v_mfma_f32_16x16x32_bf16 v[142:145], v[42:45], v[82:85], v[142:145]
	v_mfma_f32_16x16x32_bf16 v[138:141], v[50:53], v[82:85], v[138:141]
	v_mfma_f32_16x16x32_bf16 v[126:129], v[42:45], v[220:223], v[126:129]
	v_mfma_f32_16x16x32_bf16 v[122:125], v[50:53], v[220:223], v[122:125]
	v_mfma_f32_16x16x32_bf16 v[110:113], v[42:45], v[228:231], v[110:113]
	v_mfma_f32_16x16x32_bf16 v[106:109], v[50:53], v[228:231], v[106:109]
	v_mfma_f32_16x16x32_bf16 v[158:161], v[46:49], v[70:73], v[158:161]
	v_mfma_f32_16x16x32_bf16 v[154:157], v[54:57], v[70:73], v[154:157]
	v_mfma_f32_16x16x32_bf16 v[142:145], v[46:49], v[86:89], v[142:145]
	v_mfma_f32_16x16x32_bf16 v[138:141], v[54:57], v[86:89], v[138:141]
	v_mfma_f32_16x16x32_bf16 v[126:129], v[46:49], v[224:227], v[126:129]
	v_mfma_f32_16x16x32_bf16 v[122:125], v[54:57], v[224:227], v[122:125]
	v_mfma_f32_16x16x32_bf16 v[110:113], v[46:49], v[232:235], v[110:113]
	v_mfma_f32_16x16x32_bf16 v[106:109], v[54:57], v[232:235], v[106:109]
	s_setprio 0
	s_setprio 1
	v_mfma_f32_16x16x32_bf16 v[150:153], v[182:185], v[66:69], v[150:153]
	v_mfma_f32_16x16x32_bf16 v[66:69], v[212:215], v[66:69], v[146:149]
	v_mfma_f32_16x16x32_bf16 v[146:149], v[216:219], v[70:73], v[66:69]
	v_mfma_f32_16x16x32_bf16 v[66:69], v[182:185], v[82:85], v[134:137]
	v_mfma_f32_16x16x32_bf16 v[134:137], v[186:189], v[86:89], v[66:69]
	v_mfma_f32_16x16x32_bf16 v[66:69], v[212:215], v[82:85], v[130:133]
	v_mfma_f32_16x16x32_bf16 v[130:133], v[216:219], v[86:89], v[66:69]
	v_mfma_f32_16x16x32_bf16 v[66:69], v[182:185], v[220:223], v[118:121]
	v_mfma_f32_16x16x32_bf16 v[118:121], v[186:189], v[224:227], v[66:69]
	v_mfma_f32_16x16x32_bf16 v[66:69], v[212:215], v[220:223], v[114:117]
	v_mfma_f32_16x16x32_bf16 v[114:117], v[216:219], v[224:227], v[66:69]
	v_mfma_f32_16x16x32_bf16 v[66:69], v[182:185], v[228:231], v[102:105]
	v_mfma_f32_16x16x32_bf16 v[102:105], v[186:189], v[232:235], v[66:69]
	v_mfma_f32_16x16x32_bf16 v[66:69], v[212:215], v[228:231], v[98:101]
	v_mfma_f32_16x16x32_bf16 v[150:153], v[186:189], v[70:73], v[150:153]
	v_mfma_f32_16x16x32_bf16 v[98:101], v[216:219], v[232:235], v[66:69]
	s_setprio 0
	s_barrier
; #define PG8_STAGE(bufoff, gbase, voff) do { _Pragma("unroll") for (int _i = 0; _i < 2; ++_i) \
;         __builtin_amdgcn_global_load_lds((const unsigned*)((const char*)(gbase) + (voff)[_i]), (LAS unsigned*)(lds + (bufoff) + ldsw + _i * 8192), 16, 0, 0); } while (0)
; #define PG8_LDA(dst, b, h) do { _Pragma("unroll") for (int m = 0; m < 4; ++m) _Pragma("unroll") for (int k = 0; k < 2; ++k) dst[m][k] = *(const LAS bf16x8*)(lds + PG8_SA(b, h) + aoff + m * 2048 + k * 1024); } while (0)
; #define PG8_MMA(ai, bj, At, Bt) do { __builtin_amdgcn_s_setprio(1); _Pragma("unroll") for (int m = 0; m < 4; ++m) _Pragma("unroll") for (int n = 0; n < 2; ++n) _Pragma("unroll") for (int k = 0; k < 2; ++k) \
;         acc[ai][bj][m][n] = __builtin_amdgcn_mfma_f32_16x16x32_bf16(Bt[n][k], At[m][k], acc[ai][bj][m][n], 0, 0, 0); __builtin_amdgcn_s_setprio(0); } while (0)
; #define PG8_WAIT_V(n) asm volatile("s_waitcnt vmcnt(" #n ")" ::: "memory")
; #define PG8_WAIT_L(n) asm volatile("s_waitcnt lgkmcnt(" #n ")" ::: "memory")
; #define PG8_BAR __builtin_amdgcn_s_barrier()
; #define PG8_SCHED __builtin_amdgcn_sched_barrier(0)
; template <class Epi>
; __device__ __forceinline__ void gemm_phase(LAS unsigned char* lds, const Gemm g, const StaticOrder& S, const Epi& E, const int tid) {
;     ...
;         for (int t = 0; t < ntt; t += 2) {
;     ...
;             PG8_LDA(At, 1, 1); PG8_STAGE(PG8_SB(1, 0), b3, voffB); PG8_STAGE(PG8_SB(1, 1), b3 + bhs, voffB); PG8_STAGE(PG8_SA(1, 0), a3, voffA);
;             PG8_WAIT_V(8); PG8_WAIT_L(0); PG8_BAR; PG8_MMA(1, 0, At, B0); PG8_MMA(1, 1, At, B1); PG8_BAR; PG8_SCHED;
	s_add_i32 s34, s52, s36
	v_lshl_add_u64 v[82:83], v[172:173], 0, s[70:71]
	s_mov_b32 m0, s34
	s_nop 0
	ds_read_b128 v[66:69], v199 offset:49152
	global_load_lds_dwordx4 v[82:83], off
	ds_read_b128 v[70:73], v199 offset:50176
	ds_read_b128 v[220:223], v199 offset:51200
	s_add_i32 m0, s34, 0x2000
	s_add_u32 s30, s30, 0x2080
	v_lshl_add_u64 v[82:83], v[174:175], 0, s[70:71]
	s_addc_u32 s31, s31, 0
	s_add_i32 s34, s53, s36
	global_load_lds_dwordx4 v[82:83], off
	ds_read_b128 v[224:227], v199 offset:52224
	ds_read_b128 v[228:231], v199 offset:53248
	v_lshl_add_u64 v[82:83], s[30:31], 0, v[0:1]
	s_mov_b32 m0, s34
	s_nop 0
	global_load_lds_dwordx4 v[82:83], off
	ds_read_b128 v[232:235], v199 offset:54272
	ds_read_b128 v[236:239], v199 offset:55296
	v_lshl_add_u64 v[82:83], s[30:31], 0, v[166:167]
	s_add_i32 m0, s34, 0x2000
	s_nop 0
	global_load_lds_dwordx4 v[82:83], off
	ds_read_b128 v[240:243], v199 offset:56320
	v_lshl_add_u64 v[82:83], v[176:177], 0, s[70:71]
	s_mov_b32 m0, s45
	s_nop 0
	global_load_lds_dwordx4 v[82:83], off
	v_lshl_add_u64 v[82:83], v[200:201], 0, s[70:71]
	s_mov_b32 m0, s46
	s_nop 0
	global_load_lds_dwordx4 v[82:83], off
	s_waitcnt vmcnt(8)
	s_waitcnt lgkmcnt(0)
	s_barrier
	s_setprio 1
	s_waitcnt lgkmcnt(0)
	v_mfma_f32_16x16x32_bf16 v[82:85], v[42:45], v[66:69], v[94:97]
	v_mfma_f32_16x16x32_bf16 v[94:97], v[46:49], v[70:73], v[82:85]
	v_mfma_f32_16x16x32_bf16 v[82:85], v[50:53], v[66:69], v[90:93]
	v_mfma_f32_16x16x32_bf16 v[78:81], v[42:45], v[220:223], v[78:81]
	v_mfma_f32_16x16x32_bf16 v[74:77], v[50:53], v[220:223], v[74:77]
	v_mfma_f32_16x16x32_bf16 v[62:65], v[42:45], v[228:231], v[62:65]
	v_mfma_f32_16x16x32_bf16 v[58:61], v[50:53], v[228:231], v[58:61]
	v_mfma_f32_16x16x32_bf16 v[14:17], v[42:45], v[236:239], v[14:17]
	v_mfma_f32_16x16x32_bf16 v[10:13], v[50:53], v[236:239], v[10:13]
	v_mfma_f32_16x16x32_bf16 v[90:93], v[54:57], v[70:73], v[82:85]
	v_mfma_f32_16x16x32_bf16 v[78:81], v[46:49], v[224:227], v[78:81]
	v_mfma_f32_16x16x32_bf16 v[74:77], v[54:57], v[224:227], v[74:77]
	v_mfma_f32_16x16x32_bf16 v[62:65], v[46:49], v[232:235], v[62:65]
	v_mfma_f32_16x16x32_bf16 v[58:61], v[54:57], v[232:235], v[58:61]
	v_mfma_f32_16x16x32_bf16 v[14:17], v[46:49], v[240:243], v[14:17]
	v_mfma_f32_16x16x32_bf16 v[10:13], v[54:57], v[240:243], v[10:13]
	s_setprio 0
	s_setprio 1
	v_mfma_f32_16x16x32_bf16 v[18:21], v[182:185], v[66:69], v[18:21]
	v_mfma_f32_16x16x32_bf16 v[86:89], v[186:189], v[70:73], v[18:21]
	v_mfma_f32_16x16x32_bf16 v[18:21], v[212:215], v[66:69], v[22:25]
	v_mfma_f32_16x16x32_bf16 v[82:85], v[216:219], v[70:73], v[18:21]
	v_mfma_f32_16x16x32_bf16 v[18:21], v[182:185], v[220:223], v[26:29]
	v_mfma_f32_16x16x32_bf16 v[70:73], v[186:189], v[224:227], v[18:21]
	v_mfma_f32_16x16x32_bf16 v[18:21], v[212:215], v[220:223], v[30:33]
	v_mfma_f32_16x16x32_bf16 v[66:69], v[216:219], v[224:227], v[18:21]
	v_mfma_f32_16x16x32_bf16 v[18:21], v[182:185], v[228:231], v[38:41]
	v_mfma_f32_16x16x32_bf16 v[38:41], v[186:189], v[232:235], v[18:21]
	v_mfma_f32_16x16x32_bf16 v[18:21], v[212:215], v[228:231], v[34:37]
	v_mfma_f32_16x16x32_bf16 v[6:9], v[182:185], v[236:239], v[6:9]
	v_mfma_f32_16x16x32_bf16 v[2:5], v[212:215], v[236:239], v[2:5]
	v_mfma_f32_16x16x32_bf16 v[34:37], v[216:219], v[232:235], v[18:21]
	v_mfma_f32_16x16x32_bf16 v[6:9], v[186:189], v[240:243], v[6:9]
	v_mfma_f32_16x16x32_bf16 v[2:5], v[216:219], v[240:243], v[2:5]
	s_setprio 0
	s_barrier
	s_add_i32 s51, s51, 2
	s_add_u32 s49, s49, 0x100
	s_addc_u32 s50, s50, 0
	s_add_u32 s28, s28, 0x100
	s_addc_u32 s29, s29, 0
	s_cmp_gt_u32 s51, 5
	s_cbranch_scc0 .LBB0_206
	s_and_b64 vcc, exec, s[12:13]
	s_cbranch_vccz .LBB0_209
	s_barrier

; #define PG8_STAGE(bufoff, gbase, voff) do { _Pragma("unroll") for (int _i = 0; _i < 2; ++_i) \
;         __builtin_amdgcn_global_load_lds((const unsigned*)((const char*)(gbase) + (voff)[_i]), (LAS unsigned*)(lds + (bufoff) + ldsw + _i * 8192), 16, 0, 0); } while (0)
; #define PG8_LDA(dst, b, h) do { _Pragma("unroll") for (int m = 0; m < 4; ++m) _Pragma("unroll") for (int k = 0; k < 2; ++k) dst[m][k] = *(const LAS bf16x8*)(lds + PG8_SA(b, h) + aoff + m * 2048 + k * 1024); } while (0)
; #define PG8_LDB(dst, b, h) do { _Pragma("unroll") for (int n = 0; n < 2; ++n) _Pragma("unroll") for (int k = 0; k < 2; ++k) dst[n][k] = *(const LAS bf16x8*)(lds + PG8_SB(b, h) + boff + n * 2048 + k * 1024); } while (0)
; #define PG8_WAIT_V(n) asm volatile("s_waitcnt vmcnt(" #n ")" ::: "memory")
; template <class Epi>
; __device__ __forceinline__ void gemm_phase(LAS unsigned char* lds, const Gemm g, const StaticOrder& S, const Epi& E, const int tid) {
;     ...
;             const bool last = (t == ntt - 2);
;             const bool s1 = Epi::TWO && (t >= nt), s2 = Epi::TWO && (t + 2 >= nt);
;             const char* a1 = (s1 ? cA2 + (size_t)(t - nt + 1) * kstep : cA + (size_t)(t + 1) * kstep);
;             const char* a2 = last ? nA : (s2 ? cA2 + (size_t)(t + 2 - nt) * kstep : cA + (size_t)(t + 2) * kstep);
;             const char* b2 = last ? nB : (s2 ? cB2 + (size_t)(t + 2 - nt) * kstep : cB + (size_t)(t + 2) * kstep);
;             const char* a3 = a2 + kstep; const char* b3 = b2 + kstep;
;             if constexpr (Epi::TWO) { if (t == nt) E.mid(acc, cur, wr, wc, fr, fq); }
;             if constexpr (SP2) {
;             PG8_LDB(B0, 0, 0); PG8_LDB(B1, 0, 1); PG8_SCHED; PG8_LDA(At, 0, 0); PG8_STAGE(PG8_SA(1, 1), a1 + hstep, voffA);
;             PG8_WAIT_V(8); PG8_WAIT_L(0); PG8_BAR; PG8_MMA(0, 0, At, B0); PG8_MMA(0, 1, At, B1); PG8_BAR; PG8_SCHED;
;             PG8_LDA(At, 0, 1); PG8_STAGE(PG8_SB(0, 0), b2, voffB); PG8_STAGE(PG8_SB(0, 1), b2 + bhs, voffB); PG8_STAGE(PG8_SA(0, 0), a2, voffA);
;             PG8_WAIT_V(8); PG8_WAIT_L(0); PG8_BAR; PG8_MMA(1, 0, At, B0); PG8_MMA(1, 1, At, B1); PG8_BAR; PG8_SCHED;
;             PG8_LDB(B0, 1, 0); PG8_LDB(B1, 1, 1); PG8_SCHED; PG8_LDA(At, 1, 0); PG8_STAGE(PG8_SA(0, 1), a2 + hstep, voffA);
;             PG8_WAIT_V(8); PG8_WAIT_L(0); PG8_BAR; PG8_MMA(0, 0, At, B0); PG8_MMA(0, 1, At, B1); PG8_BAR; PG8_SCHED;
.LBB0_261:
	s_add_u32 s30, s28, 0xfff80080
	s_addc_u32 s31, s29, -1
	s_add_i32 s49, 0, 0x10000
	s_cmp_eq_u32 s48, 28
	s_cselect_b32 s35, s19, s31
	s_cselect_b32 s34, s44, s30
	v_add_u32_e32 v142, s49, v149
	s_cselect_b32 s31, s17, s47
	s_cselect_b32 s30, s45, s46
	s_add_i32 s52, 0, 0x14000
	ds_read_b128 v[156:159], v142
	ds_read_b128 v[160:163], v142 offset:1024
	ds_read_b128 v[164:167], v142 offset:2048
	ds_read_b128 v[178:181], v142 offset:3072
	v_add_u32_e32 v142, s52, v149
	ds_read_b128 v[182:185], v142
	ds_read_b128 v[186:189], v142 offset:1024
	ds_read_b128 v[190:193], v142 offset:2048
	ds_read_b128 v[194:197], v142 offset:3072
	v_lshl_add_u64 v[142:143], s[28:29], 0, v[140:141]
	s_add_i32 m0, s2, 0xc000
	ds_read_b128 v[198:201], v154
	global_load_lds_dwordx4 v[142:143], off
	ds_read_b128 v[212:215], v154 offset:1024
	ds_read_b128 v[216:219], v154 offset:2048
	v_lshl_add_u64 v[142:143], s[28:29], 0, v[138:139]
	s_add_i32 m0, s2, 0xe000
	s_nop 0
	global_load_lds_dwordx4 v[142:143], off
	ds_read_b128 v[220:223], v154 offset:3072
	ds_read_b128 v[224:227], v154 offset:4096
	ds_read_b128 v[228:231], v154 offset:5120
	ds_read_b128 v[232:235], v154 offset:6144
	ds_read_b128 v[236:239], v154 offset:7168
	s_waitcnt vmcnt(8)
	s_waitcnt lgkmcnt(0)
	s_barrier
	s_setprio 1
	s_waitcnt lgkmcnt(0)
	v_mfma_f32_16x16x32_bf16 v[126:129], v[156:159], v[198:201], v[126:129]
	v_mfma_f32_16x16x32_bf16 v[122:125], v[164:167], v[198:201], v[122:125]
	v_mfma_f32_16x16x32_bf16 v[110:113], v[156:159], v[216:219], v[110:113]
	v_mfma_f32_16x16x32_bf16 v[106:109], v[164:167], v[216:219], v[106:109]
	v_mfma_f32_16x16x32_bf16 v[94:97], v[156:159], v[224:227], v[94:97]
	v_mfma_f32_16x16x32_bf16 v[90:93], v[164:167], v[224:227], v[90:93]
	v_mfma_f32_16x16x32_bf16 v[78:81], v[156:159], v[232:235], v[78:81]
	v_mfma_f32_16x16x32_bf16 v[74:77], v[164:167], v[232:235], v[74:77]
	v_mfma_f32_16x16x32_bf16 v[126:129], v[160:163], v[212:215], v[126:129]
	v_mfma_f32_16x16x32_bf16 v[122:125], v[178:181], v[212:215], v[122:125]
	v_mfma_f32_16x16x32_bf16 v[110:113], v[160:163], v[220:223], v[110:113]
	v_mfma_f32_16x16x32_bf16 v[106:109], v[178:181], v[220:223], v[106:109]
	v_mfma_f32_16x16x32_bf16 v[94:97], v[160:163], v[228:231], v[94:97]
	v_mfma_f32_16x16x32_bf16 v[90:93], v[178:181], v[228:231], v[90:93]
	v_mfma_f32_16x16x32_bf16 v[78:81], v[160:163], v[236:239], v[78:81]
	v_mfma_f32_16x16x32_bf16 v[74:77], v[178:181], v[236:239], v[74:77]
	s_setprio 0
	s_setprio 1
	v_mfma_f32_16x16x32_bf16 v[118:121], v[182:185], v[198:201], v[118:121]
	v_mfma_f32_16x16x32_bf16 v[114:117], v[190:193], v[198:201], v[114:117]
	v_mfma_f32_16x16x32_bf16 v[102:105], v[182:185], v[216:219], v[102:105]
	v_mfma_f32_16x16x32_bf16 v[98:101], v[190:193], v[216:219], v[98:101]
	v_mfma_f32_16x16x32_bf16 v[86:89], v[182:185], v[224:227], v[86:89]
	v_mfma_f32_16x16x32_bf16 v[82:85], v[190:193], v[224:227], v[82:85]
	v_mfma_f32_16x16x32_bf16 v[70:73], v[182:185], v[232:235], v[70:73]
	v_mfma_f32_16x16x32_bf16 v[66:69], v[190:193], v[232:235], v[66:69]
	v_mfma_f32_16x16x32_bf16 v[118:121], v[186:189], v[212:215], v[118:121]
	v_mfma_f32_16x16x32_bf16 v[114:117], v[194:197], v[212:215], v[114:117]
	v_mfma_f32_16x16x32_bf16 v[102:105], v[186:189], v[220:223], v[102:105]
	v_mfma_f32_16x16x32_bf16 v[98:101], v[194:197], v[220:223], v[98:101]
	v_mfma_f32_16x16x32_bf16 v[86:89], v[186:189], v[228:231], v[86:89]
	v_mfma_f32_16x16x32_bf16 v[82:85], v[194:197], v[228:231], v[82:85]
	v_mfma_f32_16x16x32_bf16 v[70:73], v[186:189], v[236:239], v[70:73]
	v_mfma_f32_16x16x32_bf16 v[66:69], v[194:197], v[236:239], v[66:69]
	s_setprio 0
	s_barrier
	s_add_i32 s49, s49, s36
	v_lshl_add_u64 v[142:143], s[30:31], 0, v[0:1]
	s_mov_b32 m0, s49
	ds_read_b128 v[198:201], v154 offset:16384
	global_load_lds_dwordx4 v[142:143], off
	ds_read_b128 v[212:215], v154 offset:17408
	ds_read_b128 v[216:219], v154 offset:18432
	s_add_i32 m0, s49, 0x2000
	s_add_u32 s50, s30, 0x8000
	v_lshl_add_u64 v[168:169], s[30:31], 0, v[134:135]
	s_addc_u32 s51, s31, 0
	s_add_i32 s49, s52, s36
	global_load_lds_dwordx4 v[168:169], off
	ds_read_b128 v[220:223], v154 offset:19456
	ds_read_b128 v[224:227], v154 offset:20480
	v_lshl_add_u64 v[172:173], s[50:51], 0, v[0:1]
	s_mov_b32 m0, s49
	v_lshl_add_u64 v[174:175], s[34:35], 0, v[132:133]
	global_load_lds_dwordx4 v[172:173], off
	ds_read_b128 v[228:231], v154 offset:21504
	ds_read_b128 v[232:235], v154 offset:22528
	v_lshl_add_u64 v[172:173], s[50:51], 0, v[134:135]
	s_add_i32 m0, s49, 0x2000
	s_nop 0
	global_load_lds_dwordx4 v[172:173], off
	ds_read_b128 v[236:239], v154 offset:23552
	v_lshl_add_u64 v[172:173], s[34:35], 0, v[130:131]
	s_mov_b32 m0, s2
	s_nop 0
	global_load_lds_dwordx4 v[172:173], off
	s_mov_b32 m0, s27
	s_nop 0
	global_load_lds_dwordx4 v[174:175], off
	s_waitcnt vmcnt(8)
	s_waitcnt lgkmcnt(0)
	s_barrier
; #define PG8_STAGE(bufoff, gbase, voff) do { _Pragma("unroll") for (int _i = 0; _i < 2; ++_i) \
;         __builtin_amdgcn_global_load_lds((const unsigned*)((const char*)(gbase) + (voff)[_i]), (LAS unsigned*)(lds + (bufoff) + ldsw + _i * 8192), 16, 0, 0); } while (0)
; #define PG8_LDA(dst, b, h) do { _Pragma("unroll") for (int m = 0; m < 4; ++m) _Pragma("unroll") for (int k = 0; k < 2; ++k) dst[m][k] = *(const LAS bf16x8*)(lds + PG8_SA(b, h) + aoff + m * 2048 + k * 1024); } while (0)
; #define PG8_LDB(dst, b, h) do { _Pragma("unroll") for (int n = 0; n < 2; ++n) _Pragma("unroll") for (int k = 0; k < 2; ++k) dst[n][k] = *(const LAS bf16x8*)(lds + PG8_SB(b, h) + boff + n * 2048 + k * 1024); } while (0)
; #define PG8_MMA(ai, bj, At, Bt) do { __builtin_amdgcn_s_setprio(1); _Pragma("unroll") for (int m = 0; m < 4; ++m) _Pragma("unroll") for (int n = 0; n < 2; ++n) _Pragma("unroll") for (int k = 0; k < 2; ++k) \
;         acc[ai][bj][m][n] = __builtin_amdgcn_mfma_f32_16x16x32_bf16(Bt[n][k], At[m][k], acc[ai][bj][m][n], 0, 0, 0); __builtin_amdgcn_s_setprio(0); } while (0)
; #define PG8_WAIT_V(n) asm volatile("s_waitcnt vmcnt(" #n ")" ::: "memory")
; #define PG8_WAIT_L(n) asm volatile("s_waitcnt lgkmcnt(" #n ")" ::: "memory")
; #define PG8_BAR __builtin_amdgcn_s_barrier()
; #define PG8_SCHED __builtin_amdgcn_sched_barrier(0)
; template <class Epi>
; __device__ __forceinline__ void gemm_phase(LAS unsigned char* lds, const Gemm g, const StaticOrder& S, const Epi& E, const int tid) {
;     ...
;             PG8_WAIT_V(8); PG8_WAIT_L(0); PG8_BAR; PG8_MMA(0, 0, At, B0); PG8_MMA(0, 1, At, B1); PG8_BAR; PG8_SCHED;
;             PG8_LDA(At, 0, 1); PG8_STAGE(PG8_SB(0, 0), b2, voffB); PG8_STAGE(PG8_SB(0, 1), b2 + bhs, voffB); PG8_STAGE(PG8_SA(0, 0), a2, voffA);
;             PG8_WAIT_V(8); PG8_WAIT_L(0); PG8_BAR; PG8_MMA(1, 0, At, B0); PG8_MMA(1, 1, At, B1); PG8_BAR; PG8_SCHED;
;             PG8_LDB(B0, 1, 0); PG8_LDB(B1, 1, 1); PG8_SCHED; PG8_LDA(At, 1, 0); PG8_STAGE(PG8_SA(0, 1), a2 + hstep, voffA);
;             PG8_WAIT_V(8); PG8_WAIT_L(0); PG8_BAR; PG8_MMA(0, 0, At, B0); PG8_MMA(0, 1, At, B1); PG8_BAR; PG8_SCHED;
	s_setprio 1
	s_waitcnt lgkmcnt(0)
	v_mfma_f32_16x16x32_bf16 v[62:65], v[156:159], v[198:201], v[62:65]
	v_mfma_f32_16x16x32_bf16 v[58:61], v[164:167], v[198:201], v[58:61]
	v_mfma_f32_16x16x32_bf16 v[46:49], v[156:159], v[216:219], v[46:49]
	v_mfma_f32_16x16x32_bf16 v[42:45], v[164:167], v[216:219], v[42:45]
	v_mfma_f32_16x16x32_bf16 v[30:33], v[156:159], v[224:227], v[30:33]
	v_mfma_f32_16x16x32_bf16 v[26:29], v[164:167], v[224:227], v[26:29]
	v_mfma_f32_16x16x32_bf16 v[14:17], v[156:159], v[232:235], v[14:17]
	v_mfma_f32_16x16x32_bf16 v[10:13], v[164:167], v[232:235], v[10:13]
	v_mfma_f32_16x16x32_bf16 v[62:65], v[160:163], v[212:215], v[62:65]
	v_mfma_f32_16x16x32_bf16 v[58:61], v[178:181], v[212:215], v[58:61]
	v_mfma_f32_16x16x32_bf16 v[46:49], v[160:163], v[220:223], v[46:49]
	v_mfma_f32_16x16x32_bf16 v[42:45], v[178:181], v[220:223], v[42:45]
	v_mfma_f32_16x16x32_bf16 v[30:33], v[160:163], v[228:231], v[30:33]
	v_mfma_f32_16x16x32_bf16 v[26:29], v[178:181], v[228:231], v[26:29]
	v_mfma_f32_16x16x32_bf16 v[14:17], v[160:163], v[236:239], v[14:17]
	v_mfma_f32_16x16x32_bf16 v[10:13], v[178:181], v[236:239], v[10:13]
	s_setprio 0
	s_setprio 1
	v_mfma_f32_16x16x32_bf16 v[54:57], v[182:185], v[198:201], v[54:57]
	v_mfma_f32_16x16x32_bf16 v[50:53], v[190:193], v[198:201], v[50:53]
	v_mfma_f32_16x16x32_bf16 v[38:41], v[182:185], v[216:219], v[38:41]
	v_mfma_f32_16x16x32_bf16 v[34:37], v[190:193], v[216:219], v[34:37]
	v_mfma_f32_16x16x32_bf16 v[22:25], v[182:185], v[224:227], v[22:25]
	v_mfma_f32_16x16x32_bf16 v[18:21], v[190:193], v[224:227], v[18:21]
	v_mfma_f32_16x16x32_bf16 v[6:9], v[182:185], v[232:235], v[6:9]
	v_mfma_f32_16x16x32_bf16 v[2:5], v[190:193], v[232:235], v[2:5]
	v_mfma_f32_16x16x32_bf16 v[54:57], v[186:189], v[212:215], v[54:57]
	v_mfma_f32_16x16x32_bf16 v[50:53], v[194:197], v[212:215], v[50:53]
	v_mfma_f32_16x16x32_bf16 v[38:41], v[186:189], v[220:223], v[38:41]
	v_mfma_f32_16x16x32_bf16 v[34:37], v[194:197], v[220:223], v[34:37]
	v_mfma_f32_16x16x32_bf16 v[22:25], v[186:189], v[228:231], v[22:25]
	v_mfma_f32_16x16x32_bf16 v[18:21], v[194:197], v[228:231], v[18:21]
	v_mfma_f32_16x16x32_bf16 v[6:9], v[186:189], v[236:239], v[6:9]
	v_mfma_f32_16x16x32_bf16 v[2:5], v[194:197], v[236:239], v[2:5]
	s_setprio 0
	s_barrier
	s_add_i32 s49, 0, 0x18000
	v_add_u32_e32 v155, s49, v149
	s_add_i32 s50, 0, 0x1c000
	ds_read_b128 v[156:159], v155
	ds_read_b128 v[160:163], v155 offset:1024
	ds_read_b128 v[164:167], v155 offset:2048
	ds_read_b128 v[178:181], v155 offset:3072
	v_add_u32_e32 v155, s50, v149
	ds_read_b128 v[182:185], v155
	ds_read_b128 v[186:189], v155 offset:1024
	ds_read_b128 v[190:193], v155 offset:2048
	ds_read_b128 v[194:197], v155 offset:3072
	s_add_u32 s34, s34, 0x80000
	s_addc_u32 s35, s35, 0
	s_mov_b32 m0, s37
	v_lshl_add_u64 v[176:177], s[34:35], 0, v[130:131]
	ds_read_b128 v[198:201], v154 offset:32768
	global_load_lds_dwordx4 v[176:177], off
	ds_read_b128 v[212:215], v154 offset:33792
	ds_read_b128 v[216:219], v154 offset:34816
	v_lshl_add_u64 v[176:177], s[34:35], 0, v[132:133]
	s_mov_b32 m0, s38
	s_nop 0
	global_load_lds_dwordx4 v[176:177], off
	ds_read_b128 v[220:223], v154 offset:35840
	ds_read_b128 v[224:227], v154 offset:36864
	ds_read_b128 v[228:231], v154 offset:37888
	ds_read_b128 v[232:235], v154 offset:38912
	ds_read_b128 v[236:239], v154 offset:39936
	s_waitcnt vmcnt(8)
	s_waitcnt lgkmcnt(0)
	s_barrier
	s_setprio 1
	s_waitcnt lgkmcnt(0)
	v_mfma_f32_16x16x32_bf16 v[126:129], v[156:159], v[198:201], v[126:129]
	v_mfma_f32_16x16x32_bf16 v[122:125], v[164:167], v[198:201], v[122:125]
	v_mfma_f32_16x16x32_bf16 v[110:113], v[156:159], v[216:219], v[110:113]
	v_mfma_f32_16x16x32_bf16 v[106:109], v[164:167], v[216:219], v[106:109]
	v_mfma_f32_16x16x32_bf16 v[94:97], v[156:159], v[224:227], v[94:97]
	v_mfma_f32_16x16x32_bf16 v[90:93], v[164:167], v[224:227], v[90:93]
	v_mfma_f32_16x16x32_bf16 v[78:81], v[156:159], v[232:235], v[78:81]
	v_mfma_f32_16x16x32_bf16 v[74:77], v[164:167], v[232:235], v[74:77]
	v_mfma_f32_16x16x32_bf16 v[126:129], v[160:163], v[212:215], v[126:129]
	v_mfma_f32_16x16x32_bf16 v[122:125], v[178:181], v[212:215], v[122:125]
	v_mfma_f32_16x16x32_bf16 v[110:113], v[160:163], v[220:223], v[110:113]
	v_mfma_f32_16x16x32_bf16 v[106:109], v[178:181], v[220:223], v[106:109]
	v_mfma_f32_16x16x32_bf16 v[94:97], v[160:163], v[228:231], v[94:97]
	v_mfma_f32_16x16x32_bf16 v[90:93], v[178:181], v[228:231], v[90:93]
	v_mfma_f32_16x16x32_bf16 v[78:81], v[160:163], v[236:239], v[78:81]
	v_mfma_f32_16x16x32_bf16 v[74:77], v[178:181], v[236:239], v[74:77]
	s_setprio 0
	s_setprio 1
	v_mfma_f32_16x16x32_bf16 v[118:121], v[182:185], v[198:201], v[118:121]
	v_mfma_f32_16x16x32_bf16 v[114:117], v[190:193], v[198:201], v[114:117]
	v_mfma_f32_16x16x32_bf16 v[102:105], v[182:185], v[216:219], v[102:105]
	v_mfma_f32_16x16x32_bf16 v[98:101], v[190:193], v[216:219], v[98:101]
	v_mfma_f32_16x16x32_bf16 v[86:89], v[182:185], v[224:227], v[86:89]
	v_mfma_f32_16x16x32_bf16 v[82:85], v[190:193], v[224:227], v[82:85]
	v_mfma_f32_16x16x32_bf16 v[70:73], v[182:185], v[232:235], v[70:73]
	v_mfma_f32_16x16x32_bf16 v[66:69], v[190:193], v[232:235], v[66:69]
	v_mfma_f32_16x16x32_bf16 v[118:121], v[186:189], v[212:215], v[118:121]
	v_mfma_f32_16x16x32_bf16 v[114:117], v[194:197], v[212:215], v[114:117]
	v_mfma_f32_16x16x32_bf16 v[102:105], v[186:189], v[220:223], v[102:105]
	v_mfma_f32_16x16x32_bf16 v[98:101], v[194:197], v[220:223], v[98:101]
	v_mfma_f32_16x16x32_bf16 v[86:89], v[186:189], v[228:231], v[86:89]
	v_mfma_f32_16x16x32_bf16 v[82:85], v[194:197], v[228:231], v[82:85]
	v_mfma_f32_16x16x32_bf16 v[70:73], v[186:189], v[236:239], v[70:73]
	v_mfma_f32_16x16x32_bf16 v[66:69], v[194:197], v[236:239], v[66:69]
	s_setprio 0
	s_barrier
; #define PG8_STAGE(bufoff, gbase, voff) do { _Pragma("unroll") for (int _i = 0; _i < 2; ++_i) \
;         __builtin_amdgcn_global_load_lds((const unsigned*)((const char*)(gbase) + (voff)[_i]), (LAS unsigned*)(lds + (bufoff) + ldsw + _i * 8192), 16, 0, 0); } while (0)
; #define PG8_LDA(dst, b, h) do { _Pragma("unroll") for (int m = 0; m < 4; ++m) _Pragma("unroll") for (int k = 0; k < 2; ++k) dst[m][k] = *(const LAS bf16x8*)(lds + PG8_SA(b, h) + aoff + m * 2048 + k * 1024); } while (0)
; #define PG8_MMA(ai, bj, At, Bt) do { __builtin_amdgcn_s_setprio(1); _Pragma("unroll") for (int m = 0; m < 4; ++m) _Pragma("unroll") for (int n = 0; n < 2; ++n) _Pragma("unroll") for (int k = 0; k < 2; ++k) \
;         acc[ai][bj][m][n] = __builtin_amdgcn_mfma_f32_16x16x32_bf16(Bt[n][k], At[m][k], acc[ai][bj][m][n], 0, 0, 0); __builtin_amdgcn_s_setprio(0); } while (0)
; #define PG8_WAIT_V(n) asm volatile("s_waitcnt vmcnt(" #n ")" ::: "memory")
; #define PG8_WAIT_L(n) asm volatile("s_waitcnt lgkmcnt(" #n ")" ::: "memory")
; #define PG8_BAR __builtin_amdgcn_s_barrier()
; #define PG8_SCHED __builtin_amdgcn_sched_barrier(0)
; template <class Epi>
; __device__ __forceinline__ void gemm_phase(LAS unsigned char* lds, const Gemm g, const StaticOrder& S, const Epi& E, const int tid) {
;     ...
;         for (int t = 0; t < ntt; t += 2) {
;     ...
;             PG8_LDA(At, 1, 1); PG8_STAGE(PG8_SB(1, 0), b3, voffB); PG8_STAGE(PG8_SB(1, 1), b3 + bhs, voffB); PG8_STAGE(PG8_SA(1, 0), a3, voffA);
;             PG8_WAIT_V(8); PG8_WAIT_L(0); PG8_BAR; PG8_MMA(1, 0, At, B0); PG8_MMA(1, 1, At, B1); PG8_BAR; PG8_SCHED;
	s_add_i32 s34, s49, s36
	v_lshl_add_u64 v[142:143], v[142:143], 0, s[70:71]
	s_mov_b32 m0, s34
	ds_read_b128 v[198:201], v154 offset:49152
	global_load_lds_dwordx4 v[142:143], off
	ds_read_b128 v[212:215], v154 offset:50176
	ds_read_b128 v[216:219], v154 offset:51200
	s_add_i32 m0, s34, 0x2000
	s_add_u32 s30, s30, 0x8080
	v_lshl_add_u64 v[142:143], v[168:169], 0, s[70:71]
	s_addc_u32 s31, s31, 0
	s_add_i32 s34, s50, s36
	global_load_lds_dwordx4 v[142:143], off
	ds_read_b128 v[220:223], v154 offset:52224
	ds_read_b128 v[224:227], v154 offset:53248
	v_lshl_add_u64 v[142:143], s[30:31], 0, v[0:1]
	s_mov_b32 m0, s34
	s_nop 0
	global_load_lds_dwordx4 v[142:143], off
	ds_read_b128 v[228:231], v154 offset:54272
	ds_read_b128 v[232:235], v154 offset:55296
	v_lshl_add_u64 v[142:143], s[30:31], 0, v[134:135]
	s_add_i32 m0, s34, 0x2000
	s_nop 0
	global_load_lds_dwordx4 v[142:143], off
	ds_read_b128 v[236:239], v154 offset:56320
	v_lshl_add_u64 v[142:143], v[172:173], 0, s[70:71]
	s_mov_b32 m0, s39
	s_nop 0
	global_load_lds_dwordx4 v[142:143], off
	v_lshl_add_u64 v[142:143], v[174:175], 0, s[70:71]
	s_mov_b32 m0, s40
	s_nop 0
	global_load_lds_dwordx4 v[142:143], off
	s_waitcnt vmcnt(8)
	s_waitcnt lgkmcnt(0)
	s_barrier
	s_setprio 1
	s_waitcnt lgkmcnt(0)
	v_mfma_f32_16x16x32_bf16 v[62:65], v[156:159], v[198:201], v[62:65]
	v_mfma_f32_16x16x32_bf16 v[58:61], v[164:167], v[198:201], v[58:61]
	v_mfma_f32_16x16x32_bf16 v[46:49], v[156:159], v[216:219], v[46:49]
	v_mfma_f32_16x16x32_bf16 v[42:45], v[164:167], v[216:219], v[42:45]
	v_mfma_f32_16x16x32_bf16 v[30:33], v[156:159], v[224:227], v[30:33]
	v_mfma_f32_16x16x32_bf16 v[26:29], v[164:167], v[224:227], v[26:29]
	v_mfma_f32_16x16x32_bf16 v[14:17], v[156:159], v[232:235], v[14:17]
	v_mfma_f32_16x16x32_bf16 v[10:13], v[164:167], v[232:235], v[10:13]
	v_mfma_f32_16x16x32_bf16 v[62:65], v[160:163], v[212:215], v[62:65]
	v_mfma_f32_16x16x32_bf16 v[58:61], v[178:181], v[212:215], v[58:61]
	v_mfma_f32_16x16x32_bf16 v[46:49], v[160:163], v[220:223], v[46:49]
	v_mfma_f32_16x16x32_bf16 v[42:45], v[178:181], v[220:223], v[42:45]
	v_mfma_f32_16x16x32_bf16 v[30:33], v[160:163], v[228:231], v[30:33]
	v_mfma_f32_16x16x32_bf16 v[26:29], v[178:181], v[228:231], v[26:29]
	v_mfma_f32_16x16x32_bf16 v[14:17], v[160:163], v[236:239], v[14:17]
	v_mfma_f32_16x16x32_bf16 v[10:13], v[178:181], v[236:239], v[10:13]
	s_setprio 0
	s_setprio 1
	v_mfma_f32_16x16x32_bf16 v[54:57], v[182:185], v[198:201], v[54:57]
	v_mfma_f32_16x16x32_bf16 v[50:53], v[190:193], v[198:201], v[50:53]
	v_mfma_f32_16x16x32_bf16 v[38:41], v[182:185], v[216:219], v[38:41]
	v_mfma_f32_16x16x32_bf16 v[34:37], v[190:193], v[216:219], v[34:37]
	v_mfma_f32_16x16x32_bf16 v[22:25], v[182:185], v[224:227], v[22:25]
	v_mfma_f32_16x16x32_bf16 v[18:21], v[190:193], v[224:227], v[18:21]
	v_mfma_f32_16x16x32_bf16 v[6:9], v[182:185], v[232:235], v[6:9]
	v_mfma_f32_16x16x32_bf16 v[2:5], v[190:193], v[232:235], v[2:5]
	v_mfma_f32_16x16x32_bf16 v[54:57], v[186:189], v[212:215], v[54:57]
	v_mfma_f32_16x16x32_bf16 v[50:53], v[194:197], v[212:215], v[50:53]
	v_mfma_f32_16x16x32_bf16 v[38:41], v[186:189], v[220:223], v[38:41]
	v_mfma_f32_16x16x32_bf16 v[34:37], v[194:197], v[220:223], v[34:37]
	v_mfma_f32_16x16x32_bf16 v[22:25], v[186:189], v[228:231], v[22:25]
	v_mfma_f32_16x16x32_bf16 v[18:21], v[194:197], v[228:231], v[18:21]
	v_mfma_f32_16x16x32_bf16 v[6:9], v[186:189], v[236:239], v[6:9]
	v_mfma_f32_16x16x32_bf16 v[2:5], v[194:197], v[236:239], v[2:5]
	s_setprio 0
	s_barrier
	s_add_i32 s48, s48, 2
	s_add_u32 s46, s46, 0x100
	s_addc_u32 s47, s47, 0
	s_add_u32 s28, s28, 0x100
	s_addc_u32 s29, s29, 0
	s_cmp_gt_u32 s48, 29
	s_cbranch_scc0 .LBB0_261
	s_and_b64 vcc, exec, s[14:15]
	s_cbranch_vccz .LBB0_264
	s_barrier

; #define PG8_STAGE(bufoff, gbase, voff) do { _Pragma("unroll") for (int _i = 0; _i < 2; ++_i) \
;         __builtin_amdgcn_global_load_lds((const unsigned*)((const char*)(gbase) + (voff)[_i]), (LAS unsigned*)(lds + (bufoff) + ldsw + _i * 8192), 16, 0, 0); } while (0)
; #define PG8_LDA(dst, b, h) do { _Pragma("unroll") for (int m = 0; m < 4; ++m) _Pragma("unroll") for (int k = 0; k < 2; ++k) dst[m][k] = *(const LAS bf16x8*)(lds + PG8_SA(b, h) + aoff + m * 2048 + k * 1024); } while (0)
; #define PG8_LDB(dst, b, h) do { _Pragma("unroll") for (int n = 0; n < 2; ++n) _Pragma("unroll") for (int k = 0; k < 2; ++k) dst[n][k] = *(const LAS bf16x8*)(lds + PG8_SB(b, h) + boff + n * 2048 + k * 1024); } while (0)
; #define PG8_WAIT_V(n) asm volatile("s_waitcnt vmcnt(" #n ")" ::: "memory")
; template <class Epi>
; __device__ __forceinline__ void gemm_phase(LAS unsigned char* lds, const Gemm g, const StaticOrder& S, const Epi& E, const int tid) {
;     ...
;             const bool last = (t == ntt - 2);
;             const bool s1 = Epi::TWO && (t >= nt), s2 = Epi::TWO && (t + 2 >= nt);
;             const char* a1 = (s1 ? cA2 + (size_t)(t - nt + 1) * kstep : cA + (size_t)(t + 1) * kstep);
;             const char* a2 = last ? nA : (s2 ? cA2 + (size_t)(t + 2 - nt) * kstep : cA + (size_t)(t + 2) * kstep);
;             const char* b2 = last ? nB : (s2 ? cB2 + (size_t)(t + 2 - nt) * kstep : cB + (size_t)(t + 2) * kstep);
;             const char* a3 = a2 + kstep; const char* b3 = b2 + kstep;
;             if constexpr (Epi::TWO) { if (t == nt) E.mid(acc, cur, wr, wc, fr, fq); }
;             if constexpr (SP2) {
;             PG8_LDB(B0, 0, 0); PG8_LDB(B1, 0, 1); PG8_SCHED; PG8_LDA(At, 0, 0); PG8_STAGE(PG8_SA(1, 1), a1 + hstep, voffA);
;             PG8_WAIT_V(8); PG8_WAIT_L(0); PG8_BAR; PG8_MMA(0, 0, At, B0); PG8_MMA(0, 1, At, B1); PG8_BAR; PG8_SCHED;
;             PG8_LDA(At, 0, 1); PG8_STAGE(PG8_SB(0, 0), b2, voffB); PG8_STAGE(PG8_SB(0, 1), b2 + bhs, voffB); PG8_STAGE(PG8_SA(0, 0), a2, voffA);
;             PG8_WAIT_V(8); PG8_WAIT_L(0); PG8_BAR; PG8_MMA(1, 0, At, B0); PG8_MMA(1, 1, At, B1); PG8_BAR; PG8_SCHED;
;             PG8_LDB(B0, 1, 0); PG8_LDB(B1, 1, 1); PG8_SCHED; PG8_LDA(At, 1, 0); PG8_STAGE(PG8_SA(0, 1), a2 + hstep, voffA);
;             PG8_WAIT_V(8); PG8_WAIT_L(0); PG8_BAR; PG8_MMA(0, 0, At, B0); PG8_MMA(0, 1, At, B1); PG8_BAR; PG8_SCHED;
.LBB0_314:
	s_add_u32 s40, s6, 0xfff80080
	s_addc_u32 s41, s7, -1
	s_add_i32 s56, 0, 0x10000
	s_cmp_eq_u32 s55, 28
	s_cselect_b32 s43, s27, s41
	s_cselect_b32 s42, s39, s40
	s_cselect_b32 s41, s25, s54
	s_cselect_b32 s40, s52, s53
	s_add_i32 s58, 0, 0x14000
	v_add_u32_e32 v46, s56, v212
	v_add_u32_e32 v70, s58, v212
	ds_read_b128 v[34:37], v46
	ds_read_b128 v[38:41], v46 offset:1024
	ds_read_b128 v[42:45], v46 offset:2048
	ds_read_b128 v[46:49], v46 offset:3072
	ds_read_b128 v[58:61], v70
	ds_read_b128 v[62:65], v70 offset:1024
	ds_read_b128 v[66:69], v70 offset:2048
	ds_read_b128 v[70:73], v70 offset:3072
	v_lshl_add_u64 v[172:173], s[6:7], 0, v[188:189]
	s_add_i32 m0, s44, 0xc000
	ds_read_b128 v[162:165], v220
	global_load_lds_dwordx4 v[172:173], off
	ds_read_b128 v[166:169], v220 offset:1024
	ds_read_b128 v[190:193], v220 offset:2048
	v_lshl_add_u64 v[172:173], s[6:7], 0, v[186:187]
	s_add_i32 m0, s44, 0xe000
	s_nop 0
	global_load_lds_dwordx4 v[172:173], off
	ds_read_b128 v[194:197], v220 offset:3072
	ds_read_b128 v[198:201], v220 offset:4096
	ds_read_b128 v[222:225], v220 offset:5120
	ds_read_b128 v[226:229], v220 offset:6144
	ds_read_b128 v[230:233], v220 offset:7168
	s_waitcnt vmcnt(8)
	s_waitcnt lgkmcnt(0)
	s_barrier
	s_setprio 1
	s_waitcnt lgkmcnt(0)
	v_mfma_f32_16x16x32_bf16 v[158:161], v[34:37], v[162:165], v[158:161]
	v_mfma_f32_16x16x32_bf16 v[154:157], v[42:45], v[162:165], v[154:157]
	v_mfma_f32_16x16x32_bf16 v[142:145], v[34:37], v[190:193], v[142:145]
	v_mfma_f32_16x16x32_bf16 v[138:141], v[42:45], v[190:193], v[138:141]
	v_mfma_f32_16x16x32_bf16 v[126:129], v[34:37], v[198:201], v[126:129]
	v_mfma_f32_16x16x32_bf16 v[122:125], v[42:45], v[198:201], v[122:125]
	v_mfma_f32_16x16x32_bf16 v[110:113], v[34:37], v[226:229], v[110:113]
	v_mfma_f32_16x16x32_bf16 v[106:109], v[42:45], v[226:229], v[106:109]
	v_mfma_f32_16x16x32_bf16 v[158:161], v[38:41], v[166:169], v[158:161]
	v_mfma_f32_16x16x32_bf16 v[154:157], v[46:49], v[166:169], v[154:157]
	v_mfma_f32_16x16x32_bf16 v[142:145], v[38:41], v[194:197], v[142:145]
	v_mfma_f32_16x16x32_bf16 v[138:141], v[46:49], v[194:197], v[138:141]
	v_mfma_f32_16x16x32_bf16 v[126:129], v[38:41], v[222:225], v[126:129]
	v_mfma_f32_16x16x32_bf16 v[122:125], v[46:49], v[222:225], v[122:125]
	v_mfma_f32_16x16x32_bf16 v[110:113], v[38:41], v[230:233], v[110:113]
	v_mfma_f32_16x16x32_bf16 v[106:109], v[46:49], v[230:233], v[106:109]
	s_setprio 0
	s_setprio 1
	v_mfma_f32_16x16x32_bf16 v[150:153], v[58:61], v[162:165], v[150:153]
	v_mfma_f32_16x16x32_bf16 v[146:149], v[66:69], v[162:165], v[146:149]
	v_mfma_f32_16x16x32_bf16 v[134:137], v[58:61], v[190:193], v[134:137]
	v_mfma_f32_16x16x32_bf16 v[130:133], v[66:69], v[190:193], v[130:133]
	v_mfma_f32_16x16x32_bf16 v[118:121], v[58:61], v[198:201], v[118:121]
	v_mfma_f32_16x16x32_bf16 v[114:117], v[66:69], v[198:201], v[114:117]
	v_mfma_f32_16x16x32_bf16 v[102:105], v[58:61], v[226:229], v[102:105]
	v_mfma_f32_16x16x32_bf16 v[98:101], v[66:69], v[226:229], v[98:101]
	v_mfma_f32_16x16x32_bf16 v[150:153], v[62:65], v[166:169], v[150:153]
	v_mfma_f32_16x16x32_bf16 v[146:149], v[70:73], v[166:169], v[146:149]
	v_mfma_f32_16x16x32_bf16 v[134:137], v[62:65], v[194:197], v[134:137]
	v_mfma_f32_16x16x32_bf16 v[130:133], v[70:73], v[194:197], v[130:133]
	v_mfma_f32_16x16x32_bf16 v[118:121], v[62:65], v[222:225], v[118:121]
	v_mfma_f32_16x16x32_bf16 v[114:117], v[70:73], v[222:225], v[114:117]
	v_mfma_f32_16x16x32_bf16 v[102:105], v[62:65], v[230:233], v[102:105]
	v_mfma_f32_16x16x32_bf16 v[98:101], v[70:73], v[230:233], v[98:101]
	s_setprio 0
	s_barrier
	s_add_i32 s56, s56, s33
	v_lshl_add_u64 v[172:173], s[40:41], 0, v[0:1]
	s_mov_b32 m0, s56
	ds_read_b128 v[162:165], v220 offset:16384
	global_load_lds_dwordx4 v[172:173], off
	ds_read_b128 v[166:169], v220 offset:17408
	ds_read_b128 v[190:193], v220 offset:18432
	s_add_i32 m0, s56, 0x2000
	s_add_u32 s56, s40, 0x8000
	v_lshl_add_u64 v[174:175], s[40:41], 0, v[182:183]
	s_addc_u32 s57, s41, 0
	s_add_i32 s58, s58, s33
	global_load_lds_dwordx4 v[174:175], off
	ds_read_b128 v[194:197], v220 offset:19456
	ds_read_b128 v[198:201], v220 offset:20480
	v_lshl_add_u64 v[176:177], s[56:57], 0, v[0:1]
	s_mov_b32 m0, s58
	v_lshl_add_u64 v[238:239], s[42:43], 0, v[180:181]
	global_load_lds_dwordx4 v[176:177], off
	ds_read_b128 v[222:225], v220 offset:21504
	ds_read_b128 v[226:229], v220 offset:22528
	v_lshl_add_u64 v[176:177], s[56:57], 0, v[182:183]
	s_add_i32 m0, s58, 0x2000
	s_nop 0
	global_load_lds_dwordx4 v[176:177], off
	ds_read_b128 v[230:233], v220 offset:23552
	v_lshl_add_u64 v[176:177], s[42:43], 0, v[178:179]
	s_mov_b32 m0, s44
	s_nop 0
	global_load_lds_dwordx4 v[176:177], off
	s_mov_b32 m0, s45
	s_nop 0
	global_load_lds_dwordx4 v[238:239], off
	s_waitcnt vmcnt(8)
	s_waitcnt lgkmcnt(0)
	s_barrier
; #define PG8_STAGE(bufoff, gbase, voff) do { _Pragma("unroll") for (int _i = 0; _i < 2; ++_i) \
;         __builtin_amdgcn_global_load_lds((const unsigned*)((const char*)(gbase) + (voff)[_i]), (LAS unsigned*)(lds + (bufoff) + ldsw + _i * 8192), 16, 0, 0); } while (0)
; #define PG8_LDA(dst, b, h) do { _Pragma("unroll") for (int m = 0; m < 4; ++m) _Pragma("unroll") for (int k = 0; k < 2; ++k) dst[m][k] = *(const LAS bf16x8*)(lds + PG8_SA(b, h) + aoff + m * 2048 + k * 1024); } while (0)
; #define PG8_LDB(dst, b, h) do { _Pragma("unroll") for (int n = 0; n < 2; ++n) _Pragma("unroll") for (int k = 0; k < 2; ++k) dst[n][k] = *(const LAS bf16x8*)(lds + PG8_SB(b, h) + boff + n * 2048 + k * 1024); } while (0)
; #define PG8_MMA(ai, bj, At, Bt) do { __builtin_amdgcn_s_setprio(1); _Pragma("unroll") for (int m = 0; m < 4; ++m) _Pragma("unroll") for (int n = 0; n < 2; ++n) _Pragma("unroll") for (int k = 0; k < 2; ++k) \
;         acc[ai][bj][m][n] = __builtin_amdgcn_mfma_f32_16x16x32_bf16(Bt[n][k], At[m][k], acc[ai][bj][m][n], 0, 0, 0); __builtin_amdgcn_s_setprio(0); } while (0)
; #define PG8_WAIT_V(n) asm volatile("s_waitcnt vmcnt(" #n ")" ::: "memory")
; #define PG8_WAIT_L(n) asm volatile("s_waitcnt lgkmcnt(" #n ")" ::: "memory")
; #define PG8_BAR __builtin_amdgcn_s_barrier()
; #define PG8_SCHED __builtin_amdgcn_sched_barrier(0)
; template <class Epi>
; __device__ __forceinline__ void gemm_phase(LAS unsigned char* lds, const Gemm g, const StaticOrder& S, const Epi& E, const int tid) {
;     ...
;             PG8_WAIT_V(8); PG8_WAIT_L(0); PG8_BAR; PG8_MMA(0, 0, At, B0); PG8_MMA(0, 1, At, B1); PG8_BAR; PG8_SCHED;
;             PG8_LDA(At, 0, 1); PG8_STAGE(PG8_SB(0, 0), b2, voffB); PG8_STAGE(PG8_SB(0, 1), b2 + bhs, voffB); PG8_STAGE(PG8_SA(0, 0), a2, voffA);
;             PG8_WAIT_V(8); PG8_WAIT_L(0); PG8_BAR; PG8_MMA(1, 0, At, B0); PG8_MMA(1, 1, At, B1); PG8_BAR; PG8_SCHED;
;             PG8_LDB(B0, 1, 0); PG8_LDB(B1, 1, 1); PG8_SCHED; PG8_LDA(At, 1, 0); PG8_STAGE(PG8_SA(0, 1), a2 + hstep, voffA);
;             PG8_WAIT_V(8); PG8_WAIT_L(0); PG8_BAR; PG8_MMA(0, 0, At, B0); PG8_MMA(0, 1, At, B1); PG8_BAR; PG8_SCHED;
;             PG8_LDA(At, 1, 1); PG8_STAGE(PG8_SB(1, 0), b3, voffB); PG8_STAGE(PG8_SB(1, 1), b3 + bhs, voffB); PG8_STAGE(PG8_SA(1, 0), a3, voffA);
	s_setprio 1
	s_waitcnt lgkmcnt(0)
	v_mfma_f32_16x16x32_bf16 v[94:97], v[34:37], v[162:165], v[94:97]
	v_mfma_f32_16x16x32_bf16 v[90:93], v[42:45], v[162:165], v[90:93]
	v_mfma_f32_16x16x32_bf16 v[78:81], v[34:37], v[190:193], v[78:81]
	v_mfma_f32_16x16x32_bf16 v[74:77], v[42:45], v[190:193], v[74:77]
	v_mfma_f32_16x16x32_bf16 v[30:33], v[34:37], v[198:201], v[30:33]
	v_mfma_f32_16x16x32_bf16 v[26:29], v[42:45], v[198:201], v[26:29]
	v_mfma_f32_16x16x32_bf16 v[14:17], v[34:37], v[226:229], v[14:17]
	v_mfma_f32_16x16x32_bf16 v[10:13], v[42:45], v[226:229], v[10:13]
	v_mfma_f32_16x16x32_bf16 v[94:97], v[38:41], v[166:169], v[94:97]
	v_mfma_f32_16x16x32_bf16 v[90:93], v[46:49], v[166:169], v[90:93]
	v_mfma_f32_16x16x32_bf16 v[78:81], v[38:41], v[194:197], v[78:81]
	v_mfma_f32_16x16x32_bf16 v[74:77], v[46:49], v[194:197], v[74:77]
	v_mfma_f32_16x16x32_bf16 v[30:33], v[38:41], v[222:225], v[30:33]
	v_mfma_f32_16x16x32_bf16 v[26:29], v[46:49], v[222:225], v[26:29]
	v_mfma_f32_16x16x32_bf16 v[14:17], v[38:41], v[230:233], v[14:17]
	v_mfma_f32_16x16x32_bf16 v[10:13], v[46:49], v[230:233], v[10:13]
	s_setprio 0
	s_setprio 1
	v_mfma_f32_16x16x32_bf16 v[22:25], v[58:61], v[198:201], v[22:25]
	v_mfma_f32_16x16x32_bf16 v[18:21], v[66:69], v[198:201], v[18:21]
	v_mfma_f32_16x16x32_bf16 v[6:9], v[58:61], v[226:229], v[6:9]
	v_mfma_f32_16x16x32_bf16 v[2:5], v[66:69], v[226:229], v[2:5]
	v_mfma_f32_16x16x32_bf16 v[34:37], v[58:61], v[162:165], v[86:89]
	v_mfma_f32_16x16x32_bf16 v[38:41], v[66:69], v[162:165], v[82:85]
	v_mfma_f32_16x16x32_bf16 v[42:45], v[58:61], v[190:193], v[54:57]
	v_mfma_f32_16x16x32_bf16 v[46:49], v[66:69], v[190:193], v[50:53]
	v_mfma_f32_16x16x32_bf16 v[22:25], v[62:65], v[222:225], v[22:25]
	v_mfma_f32_16x16x32_bf16 v[18:21], v[70:73], v[222:225], v[18:21]
	v_mfma_f32_16x16x32_bf16 v[6:9], v[62:65], v[230:233], v[6:9]
	v_mfma_f32_16x16x32_bf16 v[2:5], v[70:73], v[230:233], v[2:5]
	v_mfma_f32_16x16x32_bf16 v[34:37], v[62:65], v[166:169], v[34:37]
	v_mfma_f32_16x16x32_bf16 v[38:41], v[70:73], v[166:169], v[38:41]
	v_mfma_f32_16x16x32_bf16 v[42:45], v[62:65], v[194:197], v[42:45]
	v_mfma_f32_16x16x32_bf16 v[46:49], v[70:73], v[194:197], v[46:49]
	s_setprio 0
	s_barrier
	s_add_i32 s56, 0, 0x18000
	s_add_i32 s57, 0, 0x1c000
	v_add_u32_e32 v62, s56, v212
	v_add_u32_e32 v82, s57, v212
	ds_read_b128 v[50:53], v62
	ds_read_b128 v[54:57], v62 offset:1024
	ds_read_b128 v[58:61], v62 offset:2048
	ds_read_b128 v[62:65], v62 offset:3072
	ds_read_b128 v[66:69], v82
	ds_read_b128 v[70:73], v82 offset:1024
	ds_read_b128 v[162:165], v82 offset:2048
	ds_read_b128 v[166:169], v82 offset:3072
	s_add_u32 s42, s42, 0x80000
	s_addc_u32 s43, s43, 0
	s_mov_b32 m0, s46
	v_lshl_add_u64 v[234:235], s[42:43], 0, v[178:179]
	ds_read_b128 v[82:85], v220 offset:32768
	global_load_lds_dwordx4 v[234:235], off
	ds_read_b128 v[86:89], v220 offset:33792
	ds_read_b128 v[190:193], v220 offset:34816
	v_lshl_add_u64 v[234:235], s[42:43], 0, v[180:181]
	s_mov_b32 m0, s47
	s_nop 0
	global_load_lds_dwordx4 v[234:235], off
	ds_read_b128 v[194:197], v220 offset:35840
	ds_read_b128 v[198:201], v220 offset:36864
	ds_read_b128 v[222:225], v220 offset:37888
	ds_read_b128 v[226:229], v220 offset:38912
	ds_read_b128 v[230:233], v220 offset:39936
	s_waitcnt vmcnt(8)
	s_waitcnt lgkmcnt(0)
	s_barrier
	s_setprio 1
	s_waitcnt lgkmcnt(0)
	v_mfma_f32_16x16x32_bf16 v[158:161], v[50:53], v[82:85], v[158:161]
	v_mfma_f32_16x16x32_bf16 v[154:157], v[58:61], v[82:85], v[154:157]
	v_mfma_f32_16x16x32_bf16 v[142:145], v[50:53], v[190:193], v[142:145]
	v_mfma_f32_16x16x32_bf16 v[138:141], v[58:61], v[190:193], v[138:141]
	v_mfma_f32_16x16x32_bf16 v[126:129], v[50:53], v[198:201], v[126:129]
	v_mfma_f32_16x16x32_bf16 v[122:125], v[58:61], v[198:201], v[122:125]
	v_mfma_f32_16x16x32_bf16 v[110:113], v[50:53], v[226:229], v[110:113]
	v_mfma_f32_16x16x32_bf16 v[106:109], v[58:61], v[226:229], v[106:109]
	v_mfma_f32_16x16x32_bf16 v[158:161], v[54:57], v[86:89], v[158:161]
	v_mfma_f32_16x16x32_bf16 v[154:157], v[62:65], v[86:89], v[154:157]
	v_mfma_f32_16x16x32_bf16 v[142:145], v[54:57], v[194:197], v[142:145]
	v_mfma_f32_16x16x32_bf16 v[138:141], v[62:65], v[194:197], v[138:141]
	v_mfma_f32_16x16x32_bf16 v[126:129], v[54:57], v[222:225], v[126:129]
	v_mfma_f32_16x16x32_bf16 v[122:125], v[62:65], v[222:225], v[122:125]
	v_mfma_f32_16x16x32_bf16 v[110:113], v[54:57], v[230:233], v[110:113]
	v_mfma_f32_16x16x32_bf16 v[106:109], v[62:65], v[230:233], v[106:109]
	s_setprio 0
	s_setprio 1
	v_mfma_f32_16x16x32_bf16 v[150:153], v[66:69], v[82:85], v[150:153]
	v_mfma_f32_16x16x32_bf16 v[82:85], v[162:165], v[82:85], v[146:149]
	v_mfma_f32_16x16x32_bf16 v[146:149], v[166:169], v[86:89], v[82:85]
	v_mfma_f32_16x16x32_bf16 v[82:85], v[66:69], v[190:193], v[134:137]
	v_mfma_f32_16x16x32_bf16 v[134:137], v[70:73], v[194:197], v[82:85]
	v_mfma_f32_16x16x32_bf16 v[82:85], v[162:165], v[190:193], v[130:133]
	v_mfma_f32_16x16x32_bf16 v[130:133], v[166:169], v[194:197], v[82:85]
	v_mfma_f32_16x16x32_bf16 v[82:85], v[66:69], v[198:201], v[118:121]
	v_mfma_f32_16x16x32_bf16 v[118:121], v[70:73], v[222:225], v[82:85]
	v_mfma_f32_16x16x32_bf16 v[82:85], v[162:165], v[198:201], v[114:117]
	v_mfma_f32_16x16x32_bf16 v[114:117], v[166:169], v[222:225], v[82:85]
	v_mfma_f32_16x16x32_bf16 v[82:85], v[66:69], v[226:229], v[102:105]
	v_mfma_f32_16x16x32_bf16 v[102:105], v[70:73], v[230:233], v[82:85]
	v_mfma_f32_16x16x32_bf16 v[82:85], v[162:165], v[226:229], v[98:101]
	v_mfma_f32_16x16x32_bf16 v[150:153], v[70:73], v[86:89], v[150:153]
	v_mfma_f32_16x16x32_bf16 v[98:101], v[166:169], v[230:233], v[82:85]
	s_setprio 0
	s_barrier
; #define PG8_STAGE(bufoff, gbase, voff) do { _Pragma("unroll") for (int _i = 0; _i < 2; ++_i) \
;         __builtin_amdgcn_global_load_lds((const unsigned*)((const char*)(gbase) + (voff)[_i]), (LAS unsigned*)(lds + (bufoff) + ldsw + _i * 8192), 16, 0, 0); } while (0)
; #define PG8_LDA(dst, b, h) do { _Pragma("unroll") for (int m = 0; m < 4; ++m) _Pragma("unroll") for (int k = 0; k < 2; ++k) dst[m][k] = *(const LAS bf16x8*)(lds + PG8_SA(b, h) + aoff + m * 2048 + k * 1024); } while (0)
; #define PG8_MMA(ai, bj, At, Bt) do { __builtin_amdgcn_s_setprio(1); _Pragma("unroll") for (int m = 0; m < 4; ++m) _Pragma("unroll") for (int n = 0; n < 2; ++n) _Pragma("unroll") for (int k = 0; k < 2; ++k) \
;         acc[ai][bj][m][n] = __builtin_amdgcn_mfma_f32_16x16x32_bf16(Bt[n][k], At[m][k], acc[ai][bj][m][n], 0, 0, 0); __builtin_amdgcn_s_setprio(0); } while (0)
; #define PG8_WAIT_V(n) asm volatile("s_waitcnt vmcnt(" #n ")" ::: "memory")
; #define PG8_WAIT_L(n) asm volatile("s_waitcnt lgkmcnt(" #n ")" ::: "memory")
; #define PG8_BAR __builtin_amdgcn_s_barrier()
; #define PG8_SCHED __builtin_amdgcn_sched_barrier(0)
; template <class Epi>
; __device__ __forceinline__ void gemm_phase(LAS unsigned char* lds, const Gemm g, const StaticOrder& S, const Epi& E, const int tid) {
;     ...
;         for (int t = 0; t < ntt; t += 2) {
;     ...
;             PG8_LDA(At, 1, 1); PG8_STAGE(PG8_SB(1, 0), b3, voffB); PG8_STAGE(PG8_SB(1, 1), b3 + bhs, voffB); PG8_STAGE(PG8_SA(1, 0), a3, voffA);
;             PG8_WAIT_V(8); PG8_WAIT_L(0); PG8_BAR; PG8_MMA(1, 0, At, B0); PG8_MMA(1, 1, At, B1); PG8_BAR; PG8_SCHED;
	s_add_i32 s42, s56, s33
	v_lshl_add_u64 v[86:87], v[172:173], 0, s[70:71]
	s_mov_b32 m0, s42
	s_nop 0
	ds_read_b128 v[82:85], v220 offset:49152
	global_load_lds_dwordx4 v[86:87], off
	ds_read_b128 v[190:193], v220 offset:50176
	ds_read_b128 v[194:197], v220 offset:51200
	s_add_i32 m0, s42, 0x2000
	s_add_u32 s40, s40, 0x8080
	v_lshl_add_u64 v[86:87], v[174:175], 0, s[70:71]
	s_addc_u32 s41, s41, 0
	s_add_i32 s42, s57, s33
	global_load_lds_dwordx4 v[86:87], off
	ds_read_b128 v[198:201], v220 offset:52224
	ds_read_b128 v[222:225], v220 offset:53248
	v_lshl_add_u64 v[86:87], s[40:41], 0, v[0:1]
	s_mov_b32 m0, s42
	s_nop 0
	global_load_lds_dwordx4 v[86:87], off
	ds_read_b128 v[226:229], v220 offset:54272
	ds_read_b128 v[230:233], v220 offset:55296
	v_lshl_add_u64 v[86:87], s[40:41], 0, v[182:183]
	s_add_i32 m0, s42, 0x2000
	s_nop 0
	global_load_lds_dwordx4 v[86:87], off
	ds_read_b128 v[234:237], v220 offset:56320
	v_lshl_add_u64 v[86:87], v[176:177], 0, s[70:71]
	s_mov_b32 m0, s48
	s_nop 0
	global_load_lds_dwordx4 v[86:87], off
	v_lshl_add_u64 v[86:87], v[238:239], 0, s[70:71]
	s_mov_b32 m0, s49
	s_nop 0
	global_load_lds_dwordx4 v[86:87], off
	s_waitcnt vmcnt(8)
	s_waitcnt lgkmcnt(0)
	s_barrier
	s_setprio 1
	s_waitcnt lgkmcnt(0)
	v_mfma_f32_16x16x32_bf16 v[86:89], v[50:53], v[82:85], v[94:97]
	v_mfma_f32_16x16x32_bf16 v[94:97], v[54:57], v[190:193], v[86:89]
	v_mfma_f32_16x16x32_bf16 v[86:89], v[58:61], v[82:85], v[90:93]
	v_mfma_f32_16x16x32_bf16 v[78:81], v[50:53], v[194:197], v[78:81]
	v_mfma_f32_16x16x32_bf16 v[74:77], v[58:61], v[194:197], v[74:77]
	v_mfma_f32_16x16x32_bf16 v[30:33], v[50:53], v[222:225], v[30:33]
	v_mfma_f32_16x16x32_bf16 v[26:29], v[58:61], v[222:225], v[26:29]
	v_mfma_f32_16x16x32_bf16 v[14:17], v[50:53], v[230:233], v[14:17]
	v_mfma_f32_16x16x32_bf16 v[10:13], v[58:61], v[230:233], v[10:13]
	v_mfma_f32_16x16x32_bf16 v[90:93], v[62:65], v[190:193], v[86:89]
	v_mfma_f32_16x16x32_bf16 v[78:81], v[54:57], v[198:201], v[78:81]
	v_mfma_f32_16x16x32_bf16 v[74:77], v[62:65], v[198:201], v[74:77]
	v_mfma_f32_16x16x32_bf16 v[30:33], v[54:57], v[226:229], v[30:33]
	v_mfma_f32_16x16x32_bf16 v[26:29], v[62:65], v[226:229], v[26:29]
	v_mfma_f32_16x16x32_bf16 v[14:17], v[54:57], v[234:237], v[14:17]
	v_mfma_f32_16x16x32_bf16 v[10:13], v[62:65], v[234:237], v[10:13]
	s_setprio 0
	s_setprio 1
	v_mfma_f32_16x16x32_bf16 v[34:37], v[66:69], v[82:85], v[34:37]
	v_mfma_f32_16x16x32_bf16 v[86:89], v[70:73], v[190:193], v[34:37]
	v_mfma_f32_16x16x32_bf16 v[34:37], v[162:165], v[82:85], v[38:41]
	v_mfma_f32_16x16x32_bf16 v[82:85], v[166:169], v[190:193], v[34:37]
	v_mfma_f32_16x16x32_bf16 v[34:37], v[66:69], v[194:197], v[42:45]
	v_mfma_f32_16x16x32_bf16 v[54:57], v[70:73], v[198:201], v[34:37]
	v_mfma_f32_16x16x32_bf16 v[34:37], v[162:165], v[194:197], v[46:49]
	v_mfma_f32_16x16x32_bf16 v[22:25], v[66:69], v[222:225], v[22:25]
	v_mfma_f32_16x16x32_bf16 v[18:21], v[162:165], v[222:225], v[18:21]
	v_mfma_f32_16x16x32_bf16 v[6:9], v[66:69], v[230:233], v[6:9]
	v_mfma_f32_16x16x32_bf16 v[2:5], v[162:165], v[230:233], v[2:5]
	v_mfma_f32_16x16x32_bf16 v[50:53], v[166:169], v[198:201], v[34:37]
	v_mfma_f32_16x16x32_bf16 v[22:25], v[70:73], v[226:229], v[22:25]
	v_mfma_f32_16x16x32_bf16 v[18:21], v[166:169], v[226:229], v[18:21]
	v_mfma_f32_16x16x32_bf16 v[6:9], v[70:73], v[234:237], v[6:9]
	v_mfma_f32_16x16x32_bf16 v[2:5], v[166:169], v[234:237], v[2:5]
	s_setprio 0
	s_barrier
	s_add_i32 s55, s55, 2
	s_add_u32 s53, s53, 0x100
	s_addc_u32 s54, s54, 0
	s_add_u32 s6, s6, 0x100
	s_addc_u32 s7, s7, 0
	s_cmp_gt_u32 s55, 29
	s_cbranch_scc0 .LBB0_314
	s_and_b64 vcc, exec, s[22:23]
	s_cbranch_vccz .LBB0_317
	s_barrier

; #define PG8_STAGE(bufoff, gbase, voff) do { _Pragma("unroll") for (int _i = 0; _i < 2; ++_i) \
;         __builtin_amdgcn_global_load_lds((const unsigned*)((const char*)(gbase) + (voff)[_i]), (LAS unsigned*)(lds + (bufoff) + ldsw + _i * 8192), 16, 0, 0); } while (0)
; #define PG8_LDA(dst, b, h) do { _Pragma("unroll") for (int m = 0; m < 4; ++m) _Pragma("unroll") for (int k = 0; k < 2; ++k) dst[m][k] = *(const LAS bf16x8*)(lds + PG8_SA(b, h) + aoff + m * 2048 + k * 1024); } while (0)
; #define PG8_LDB(dst, b, h) do { _Pragma("unroll") for (int n = 0; n < 2; ++n) _Pragma("unroll") for (int k = 0; k < 2; ++k) dst[n][k] = *(const LAS bf16x8*)(lds + PG8_SB(b, h) + boff + n * 2048 + k * 1024); } while (0)
; #define PG8_MMA(ai, bj, At, Bt) do { __builtin_amdgcn_s_setprio(1); _Pragma("unroll") for (int m = 0; m < 4; ++m) _Pragma("unroll") for (int n = 0; n < 2; ++n) _Pragma("unroll") for (int k = 0; k < 2; ++k) \
;         acc[ai][bj][m][n] = __builtin_amdgcn_mfma_f32_16x16x32_bf16(Bt[n][k], At[m][k], acc[ai][bj][m][n], 0, 0, 0); __builtin_amdgcn_s_setprio(0); } while (0)
; #define PG8_WAIT_V(n) asm volatile("s_waitcnt vmcnt(" #n ")" ::: "memory")
; #define PG8_WAIT_L(n) asm volatile("s_waitcnt lgkmcnt(" #n ")" ::: "memory")
; #define PG8_BAR __builtin_amdgcn_s_barrier()
; #define PG8_SCHED __builtin_amdgcn_sched_barrier(0)
; template <class Epi>
; __device__ __forceinline__ void gemm_phase(LAS unsigned char* lds, const Gemm g, const StaticOrder& S, const Epi& E, const int tid) {
;     ...
;             PG8_LDB(B0, 0, 0); PG8_LDB(B1, 0, 1); PG8_SCHED; PG8_LDA(At, 0, 0); PG8_STAGE(PG8_SA(1, 1), a1 + hstep, voffA);
;             PG8_WAIT_V(8); PG8_WAIT_L(0); PG8_BAR; PG8_MMA(0, 0, At, B0); PG8_MMA(0, 1, At, B1); PG8_BAR; PG8_SCHED;
;             PG8_LDA(At, 0, 1); PG8_STAGE(PG8_SB(0, 0), b2, voffB); PG8_STAGE(PG8_SB(0, 1), b2 + bhs, voffB); PG8_STAGE(PG8_SA(0, 0), a2, voffA);
;             PG8_WAIT_V(8); PG8_WAIT_L(0); PG8_BAR; PG8_MMA(1, 0, At, B0); PG8_MMA(1, 1, At, B1); PG8_BAR; PG8_SCHED;
;             PG8_LDB(B0, 1, 0); PG8_LDB(B1, 1, 1); PG8_SCHED; PG8_LDA(At, 1, 0); PG8_STAGE(PG8_SA(0, 1), a2 + hstep, voffA);
;             PG8_WAIT_V(8); PG8_WAIT_L(0); PG8_BAR; PG8_MMA(0, 0, At, B0); PG8_MMA(0, 1, At, B1); PG8_BAR; PG8_SCHED;
.LBB0_454:
	s_add_i32 s13, 0, 0x10000
	v_add_u32_e32 v0, s13, v153
	s_add_i32 s36, 0, 0x14000
	ds_read_b128 v[132:135], v0
	ds_read_b128 v[136:139], v0 offset:1024
	ds_read_b128 v[156:159], v0 offset:2048
	ds_read_b128 v[160:163], v0 offset:3072
	v_add_u32_e32 v0, s36, v153
	ds_read_b128 v[164:167], v0
	ds_read_b128 v[178:181], v0 offset:1024
	ds_read_b128 v[182:185], v0 offset:2048
	ds_read_b128 v[186:189], v0 offset:3072
	s_add_u32 s34, s34, 0x40000
	s_addc_u32 s35, s35, 0
	v_lshl_add_u64 v[2:3], s[34:35], 0, v[140:141]
	s_add_i32 m0, s43, 0xc000
	ds_read_b128 v[190:193], v155
	global_load_lds_dwordx4 v[2:3], off
	ds_read_b128 v[194:197], v155 offset:1024
	ds_read_b128 v[198:201], v155 offset:2048
	v_lshl_add_u64 v[2:3], s[34:35], 0, v[144:145]
	s_add_i32 m0, s43, 0xe000
	s_nop 0
	global_load_lds_dwordx4 v[2:3], off
	ds_read_b128 v[212:215], v155 offset:3072
	ds_read_b128 v[216:219], v155 offset:4096
	ds_read_b128 v[220:223], v155 offset:5120
	ds_read_b128 v[224:227], v155 offset:6144
	ds_read_b128 v[228:231], v155 offset:7168
	s_waitcnt vmcnt(8)
	s_waitcnt lgkmcnt(0)
	s_barrier
	s_setprio 1
	s_waitcnt lgkmcnt(0)
	v_mfma_f32_16x16x32_bf16 v[128:131], v[132:135], v[190:193], v[128:131]
	v_mfma_f32_16x16x32_bf16 v[124:127], v[156:159], v[190:193], v[124:127]
	v_mfma_f32_16x16x32_bf16 v[112:115], v[132:135], v[198:201], v[112:115]
	v_mfma_f32_16x16x32_bf16 v[108:111], v[156:159], v[198:201], v[108:111]
	v_mfma_f32_16x16x32_bf16 v[96:99], v[132:135], v[216:219], v[96:99]
	v_mfma_f32_16x16x32_bf16 v[92:95], v[156:159], v[216:219], v[92:95]
	v_mfma_f32_16x16x32_bf16 v[80:83], v[132:135], v[224:227], v[80:83]
	v_mfma_f32_16x16x32_bf16 v[76:79], v[156:159], v[224:227], v[76:79]
	v_mfma_f32_16x16x32_bf16 v[128:131], v[136:139], v[194:197], v[128:131]
	v_mfma_f32_16x16x32_bf16 v[124:127], v[160:163], v[194:197], v[124:127]
	v_mfma_f32_16x16x32_bf16 v[112:115], v[136:139], v[212:215], v[112:115]
	v_mfma_f32_16x16x32_bf16 v[108:111], v[160:163], v[212:215], v[108:111]
	v_mfma_f32_16x16x32_bf16 v[96:99], v[136:139], v[220:223], v[96:99]
	v_mfma_f32_16x16x32_bf16 v[92:95], v[160:163], v[220:223], v[92:95]
	v_mfma_f32_16x16x32_bf16 v[80:83], v[136:139], v[228:231], v[80:83]
	v_mfma_f32_16x16x32_bf16 v[76:79], v[160:163], v[228:231], v[76:79]
	s_setprio 0
	s_setprio 1
	v_mfma_f32_16x16x32_bf16 v[120:123], v[164:167], v[190:193], v[120:123]
	v_mfma_f32_16x16x32_bf16 v[116:119], v[182:185], v[190:193], v[116:119]
	v_mfma_f32_16x16x32_bf16 v[104:107], v[164:167], v[198:201], v[104:107]
	v_mfma_f32_16x16x32_bf16 v[100:103], v[182:185], v[198:201], v[100:103]
	v_mfma_f32_16x16x32_bf16 v[88:91], v[164:167], v[216:219], v[88:91]
	v_mfma_f32_16x16x32_bf16 v[84:87], v[182:185], v[216:219], v[84:87]
	v_mfma_f32_16x16x32_bf16 v[72:75], v[164:167], v[224:227], v[72:75]
	v_mfma_f32_16x16x32_bf16 v[68:71], v[182:185], v[224:227], v[68:71]
	v_mfma_f32_16x16x32_bf16 v[120:123], v[178:181], v[194:197], v[120:123]
	v_mfma_f32_16x16x32_bf16 v[116:119], v[186:189], v[194:197], v[116:119]
	v_mfma_f32_16x16x32_bf16 v[104:107], v[178:181], v[212:215], v[104:107]
	v_mfma_f32_16x16x32_bf16 v[100:103], v[186:189], v[212:215], v[100:103]
	v_mfma_f32_16x16x32_bf16 v[88:91], v[178:181], v[220:223], v[88:91]
	v_mfma_f32_16x16x32_bf16 v[84:87], v[186:189], v[220:223], v[84:87]
	v_mfma_f32_16x16x32_bf16 v[72:75], v[178:181], v[228:231], v[72:75]
	v_mfma_f32_16x16x32_bf16 v[68:71], v[186:189], v[228:231], v[68:71]
	s_setprio 0
	s_barrier
	s_add_i32 s13, s13, s42
	v_lshl_add_u64 v[168:169], s[28:29], 0, v[142:143]
	s_mov_b32 m0, s13
	ds_read_b128 v[190:193], v155 offset:16384
	global_load_lds_dwordx4 v[168:169], off
	ds_read_b128 v[194:197], v155 offset:17408
	ds_read_b128 v[198:201], v155 offset:18432
	s_add_i32 m0, s13, 0x2000
	s_add_u32 s34, s28, 0x4000
	v_lshl_add_u64 v[172:173], s[28:29], 0, v[146:147]
	s_addc_u32 s35, s29, 0
	s_add_i32 s13, s36, s42
	global_load_lds_dwordx4 v[172:173], off
	ds_read_b128 v[212:215], v155 offset:19456
	ds_read_b128 v[216:219], v155 offset:20480
	v_lshl_add_u64 v[2:3], s[34:35], 0, v[142:143]
	s_mov_b32 m0, s13
	v_lshl_add_u64 v[174:175], s[30:31], 0, v[140:141]
	global_load_lds_dwordx4 v[2:3], off
	ds_read_b128 v[220:223], v155 offset:21504
	ds_read_b128 v[224:227], v155 offset:22528
	v_lshl_add_u64 v[2:3], s[34:35], 0, v[146:147]
	s_add_i32 m0, s13, 0x2000
	v_lshl_add_u64 v[176:177], s[30:31], 0, v[144:145]
	global_load_lds_dwordx4 v[2:3], off
	ds_read_b128 v[228:231], v155 offset:23552
	s_mov_b32 m0, s43
	s_nop 0
	global_load_lds_dwordx4 v[174:175], off
	s_mov_b32 m0, s44
	s_nop 0
	global_load_lds_dwordx4 v[176:177], off
	s_waitcnt vmcnt(8)
	s_waitcnt lgkmcnt(0)
	s_barrier
; #define PG8_STAGE(bufoff, gbase, voff) do { _Pragma("unroll") for (int _i = 0; _i < 2; ++_i) \
;         __builtin_amdgcn_global_load_lds((const unsigned*)((const char*)(gbase) + (voff)[_i]), (LAS unsigned*)(lds + (bufoff) + ldsw + _i * 8192), 16, 0, 0); } while (0)
; #define PG8_LDA(dst, b, h) do { _Pragma("unroll") for (int m = 0; m < 4; ++m) _Pragma("unroll") for (int k = 0; k < 2; ++k) dst[m][k] = *(const LAS bf16x8*)(lds + PG8_SA(b, h) + aoff + m * 2048 + k * 1024); } while (0)
; #define PG8_LDB(dst, b, h) do { _Pragma("unroll") for (int n = 0; n < 2; ++n) _Pragma("unroll") for (int k = 0; k < 2; ++k) dst[n][k] = *(const LAS bf16x8*)(lds + PG8_SB(b, h) + boff + n * 2048 + k * 1024); } while (0)
; #define PG8_MMA(ai, bj, At, Bt) do { __builtin_amdgcn_s_setprio(1); _Pragma("unroll") for (int m = 0; m < 4; ++m) _Pragma("unroll") for (int n = 0; n < 2; ++n) _Pragma("unroll") for (int k = 0; k < 2; ++k) \
;         acc[ai][bj][m][n] = __builtin_amdgcn_mfma_f32_16x16x32_bf16(Bt[n][k], At[m][k], acc[ai][bj][m][n], 0, 0, 0); __builtin_amdgcn_s_setprio(0); } while (0)
; #define PG8_WAIT_V(n) asm volatile("s_waitcnt vmcnt(" #n ")" ::: "memory")
; #define PG8_WAIT_L(n) asm volatile("s_waitcnt lgkmcnt(" #n ")" ::: "memory")
; #define PG8_BAR __builtin_amdgcn_s_barrier()
; #define PG8_SCHED __builtin_amdgcn_sched_barrier(0)
; template <class Epi>
; __device__ __forceinline__ void gemm_phase(LAS unsigned char* lds, const Gemm g, const StaticOrder& S, const Epi& E, const int tid) {
;     ...
;             PG8_WAIT_V(8); PG8_WAIT_L(0); PG8_BAR; PG8_MMA(0, 0, At, B0); PG8_MMA(0, 1, At, B1); PG8_BAR; PG8_SCHED;
;             PG8_LDA(At, 0, 1); PG8_STAGE(PG8_SB(0, 0), b2, voffB); PG8_STAGE(PG8_SB(0, 1), b2 + bhs, voffB); PG8_STAGE(PG8_SA(0, 0), a2, voffA);
;             PG8_WAIT_V(8); PG8_WAIT_L(0); PG8_BAR; PG8_MMA(1, 0, At, B0); PG8_MMA(1, 1, At, B1); PG8_BAR; PG8_SCHED;
;             PG8_LDB(B0, 1, 0); PG8_LDB(B1, 1, 1); PG8_SCHED; PG8_LDA(At, 1, 0); PG8_STAGE(PG8_SA(0, 1), a2 + hstep, voffA);
;             PG8_WAIT_V(8); PG8_WAIT_L(0); PG8_BAR; PG8_MMA(0, 0, At, B0); PG8_MMA(0, 1, At, B1); PG8_BAR; PG8_SCHED;
;             PG8_LDA(At, 1, 1); PG8_STAGE(PG8_SB(1, 0), b3, voffB); PG8_STAGE(PG8_SB(1, 1), b3 + bhs, voffB); PG8_STAGE(PG8_SA(1, 0), a3, voffA);
	s_setprio 1
	s_waitcnt lgkmcnt(0)
	v_mfma_f32_16x16x32_bf16 v[64:67], v[132:135], v[190:193], v[64:67]
	v_mfma_f32_16x16x32_bf16 v[60:63], v[156:159], v[190:193], v[60:63]
	v_mfma_f32_16x16x32_bf16 v[48:51], v[132:135], v[198:201], v[48:51]
	v_mfma_f32_16x16x32_bf16 v[44:47], v[156:159], v[198:201], v[44:47]
	v_mfma_f32_16x16x32_bf16 v[32:35], v[132:135], v[216:219], v[32:35]
	v_mfma_f32_16x16x32_bf16 v[28:31], v[156:159], v[216:219], v[28:31]
	v_mfma_f32_16x16x32_bf16 v[16:19], v[132:135], v[224:227], v[16:19]
	v_mfma_f32_16x16x32_bf16 v[12:15], v[156:159], v[224:227], v[12:15]
	v_mfma_f32_16x16x32_bf16 v[64:67], v[136:139], v[194:197], v[64:67]
	v_mfma_f32_16x16x32_bf16 v[60:63], v[160:163], v[194:197], v[60:63]
	v_mfma_f32_16x16x32_bf16 v[48:51], v[136:139], v[212:215], v[48:51]
	v_mfma_f32_16x16x32_bf16 v[44:47], v[160:163], v[212:215], v[44:47]
	v_mfma_f32_16x16x32_bf16 v[32:35], v[136:139], v[220:223], v[32:35]
	v_mfma_f32_16x16x32_bf16 v[28:31], v[160:163], v[220:223], v[28:31]
	v_mfma_f32_16x16x32_bf16 v[16:19], v[136:139], v[228:231], v[16:19]
	v_mfma_f32_16x16x32_bf16 v[12:15], v[160:163], v[228:231], v[12:15]
	s_setprio 0
	s_setprio 1
	v_mfma_f32_16x16x32_bf16 v[56:59], v[164:167], v[190:193], v[56:59]
	v_mfma_f32_16x16x32_bf16 v[52:55], v[182:185], v[190:193], v[52:55]
	v_mfma_f32_16x16x32_bf16 v[40:43], v[164:167], v[198:201], v[40:43]
	v_mfma_f32_16x16x32_bf16 v[36:39], v[182:185], v[198:201], v[36:39]
	v_mfma_f32_16x16x32_bf16 v[24:27], v[164:167], v[216:219], v[24:27]
	v_mfma_f32_16x16x32_bf16 v[20:23], v[182:185], v[216:219], v[20:23]
	v_mfma_f32_16x16x32_bf16 v[8:11], v[164:167], v[224:227], v[8:11]
	v_mfma_f32_16x16x32_bf16 v[2:5], v[182:185], v[224:227], v[4:7]
	v_mfma_f32_16x16x32_bf16 v[56:59], v[178:181], v[194:197], v[56:59]
	v_mfma_f32_16x16x32_bf16 v[52:55], v[186:189], v[194:197], v[52:55]
	v_mfma_f32_16x16x32_bf16 v[40:43], v[178:181], v[212:215], v[40:43]
	v_mfma_f32_16x16x32_bf16 v[36:39], v[186:189], v[212:215], v[36:39]
	v_mfma_f32_16x16x32_bf16 v[24:27], v[178:181], v[220:223], v[24:27]
	v_mfma_f32_16x16x32_bf16 v[20:23], v[186:189], v[220:223], v[20:23]
	v_mfma_f32_16x16x32_bf16 v[8:11], v[178:181], v[228:231], v[8:11]
	v_mfma_f32_16x16x32_bf16 v[2:5], v[186:189], v[228:231], v[2:5]
	s_setprio 0
	s_barrier
	s_add_i32 s13, 0, 0x18000
	v_add_u32_e32 v0, s13, v153
	s_add_i32 s34, 0, 0x1c000
	ds_read_b128 v[132:135], v0
	ds_read_b128 v[136:139], v0 offset:1024
	ds_read_b128 v[156:159], v0 offset:2048
	ds_read_b128 v[160:163], v0 offset:3072
	v_add_u32_e32 v0, s34, v153
	ds_read_b128 v[164:167], v0
	ds_read_b128 v[178:181], v0 offset:1024
	ds_read_b128 v[182:185], v0 offset:2048
	ds_read_b128 v[186:189], v0 offset:3072
	s_add_u32 s30, s30, 0x40000
	s_addc_u32 s31, s31, 0
	s_mov_b32 m0, s45
	v_lshl_add_u64 v[6:7], s[30:31], 0, v[140:141]
	ds_read_b128 v[190:193], v155 offset:32768
	global_load_lds_dwordx4 v[6:7], off
	ds_read_b128 v[194:197], v155 offset:33792
	ds_read_b128 v[198:201], v155 offset:34816
	v_lshl_add_u64 v[6:7], s[30:31], 0, v[144:145]
	s_mov_b32 m0, s46
	s_nop 0
	global_load_lds_dwordx4 v[6:7], off
	ds_read_b128 v[212:215], v155 offset:35840
	ds_read_b128 v[216:219], v155 offset:36864
	ds_read_b128 v[220:223], v155 offset:37888
	ds_read_b128 v[224:227], v155 offset:38912
	ds_read_b128 v[228:231], v155 offset:39936
	s_waitcnt vmcnt(8)
	s_waitcnt lgkmcnt(0)
	s_barrier
	s_setprio 1
	s_waitcnt lgkmcnt(0)
	v_mfma_f32_16x16x32_bf16 v[128:131], v[132:135], v[190:193], v[128:131]
	v_mfma_f32_16x16x32_bf16 v[124:127], v[156:159], v[190:193], v[124:127]
	v_mfma_f32_16x16x32_bf16 v[112:115], v[132:135], v[198:201], v[112:115]
	v_mfma_f32_16x16x32_bf16 v[108:111], v[156:159], v[198:201], v[108:111]
	v_mfma_f32_16x16x32_bf16 v[96:99], v[132:135], v[216:219], v[96:99]
	v_mfma_f32_16x16x32_bf16 v[92:95], v[156:159], v[216:219], v[92:95]
	v_mfma_f32_16x16x32_bf16 v[80:83], v[132:135], v[224:227], v[80:83]
	v_mfma_f32_16x16x32_bf16 v[76:79], v[156:159], v[224:227], v[76:79]
	v_mfma_f32_16x16x32_bf16 v[128:131], v[136:139], v[194:197], v[128:131]
	v_mfma_f32_16x16x32_bf16 v[124:127], v[160:163], v[194:197], v[124:127]
	v_mfma_f32_16x16x32_bf16 v[112:115], v[136:139], v[212:215], v[112:115]
	v_mfma_f32_16x16x32_bf16 v[108:111], v[160:163], v[212:215], v[108:111]
	v_mfma_f32_16x16x32_bf16 v[96:99], v[136:139], v[220:223], v[96:99]
	v_mfma_f32_16x16x32_bf16 v[92:95], v[160:163], v[220:223], v[92:95]
	v_mfma_f32_16x16x32_bf16 v[80:83], v[136:139], v[228:231], v[80:83]
	v_mfma_f32_16x16x32_bf16 v[76:79], v[160:163], v[228:231], v[76:79]
	s_setprio 0
	s_setprio 1
	v_mfma_f32_16x16x32_bf16 v[120:123], v[164:167], v[190:193], v[120:123]
	v_mfma_f32_16x16x32_bf16 v[116:119], v[182:185], v[190:193], v[116:119]
	v_mfma_f32_16x16x32_bf16 v[104:107], v[164:167], v[198:201], v[104:107]
	v_mfma_f32_16x16x32_bf16 v[100:103], v[182:185], v[198:201], v[100:103]
	v_mfma_f32_16x16x32_bf16 v[88:91], v[164:167], v[216:219], v[88:91]
	v_mfma_f32_16x16x32_bf16 v[84:87], v[182:185], v[216:219], v[84:87]
	v_mfma_f32_16x16x32_bf16 v[72:75], v[164:167], v[224:227], v[72:75]
	v_mfma_f32_16x16x32_bf16 v[68:71], v[182:185], v[224:227], v[68:71]
	v_mfma_f32_16x16x32_bf16 v[120:123], v[178:181], v[194:197], v[120:123]
	v_mfma_f32_16x16x32_bf16 v[116:119], v[186:189], v[194:197], v[116:119]
	v_mfma_f32_16x16x32_bf16 v[104:107], v[178:181], v[212:215], v[104:107]
	v_mfma_f32_16x16x32_bf16 v[100:103], v[186:189], v[212:215], v[100:103]
	v_mfma_f32_16x16x32_bf16 v[88:91], v[178:181], v[220:223], v[88:91]
	v_mfma_f32_16x16x32_bf16 v[84:87], v[186:189], v[220:223], v[84:87]
	v_mfma_f32_16x16x32_bf16 v[72:75], v[178:181], v[228:231], v[72:75]
	v_mfma_f32_16x16x32_bf16 v[68:71], v[186:189], v[228:231], v[68:71]
	s_setprio 0
	s_barrier
; #define PG8_STAGE(bufoff, gbase, voff) do { _Pragma("unroll") for (int _i = 0; _i < 2; ++_i) \
;         __builtin_amdgcn_global_load_lds((const unsigned*)((const char*)(gbase) + (voff)[_i]), (LAS unsigned*)(lds + (bufoff) + ldsw + _i * 8192), 16, 0, 0); } while (0)
; #define PG8_LDA(dst, b, h) do { _Pragma("unroll") for (int m = 0; m < 4; ++m) _Pragma("unroll") for (int k = 0; k < 2; ++k) dst[m][k] = *(const LAS bf16x8*)(lds + PG8_SA(b, h) + aoff + m * 2048 + k * 1024); } while (0)
; #define PG8_MMA(ai, bj, At, Bt) do { __builtin_amdgcn_s_setprio(1); _Pragma("unroll") for (int m = 0; m < 4; ++m) _Pragma("unroll") for (int n = 0; n < 2; ++n) _Pragma("unroll") for (int k = 0; k < 2; ++k) \
;         acc[ai][bj][m][n] = __builtin_amdgcn_mfma_f32_16x16x32_bf16(Bt[n][k], At[m][k], acc[ai][bj][m][n], 0, 0, 0); __builtin_amdgcn_s_setprio(0); } while (0)
; #define PG8_WAIT_V(n) asm volatile("s_waitcnt vmcnt(" #n ")" ::: "memory")
; #define PG8_WAIT_L(n) asm volatile("s_waitcnt lgkmcnt(" #n ")" ::: "memory")
; #define PG8_BAR __builtin_amdgcn_s_barrier()
; #define PG8_SCHED __builtin_amdgcn_sched_barrier(0)
; template <class Epi>
; __device__ __forceinline__ void gemm_phase(LAS unsigned char* lds, const Gemm g, const StaticOrder& S, const Epi& E, const int tid) {
;     ...
;             PG8_LDA(At, 1, 1); PG8_STAGE(PG8_SB(1, 0), b3, voffB); PG8_STAGE(PG8_SB(1, 1), b3 + bhs, voffB); PG8_STAGE(PG8_SA(1, 0), a3, voffA);
;             PG8_WAIT_V(8); PG8_WAIT_L(0); PG8_BAR; PG8_MMA(1, 0, At, B0); PG8_MMA(1, 1, At, B1); PG8_BAR; PG8_SCHED;
	s_add_i32 s13, s13, s42
	v_lshl_add_u64 v[6:7], v[168:169], 0, s[70:71]
	s_mov_b32 m0, s13
	ds_read_b128 v[190:193], v155 offset:49152
	global_load_lds_dwordx4 v[6:7], off
	ds_read_b128 v[194:197], v155 offset:50176
	ds_read_b128 v[198:201], v155 offset:51200
	s_add_i32 m0, s13, 0x2000
	s_add_u32 s28, s28, 0x4080
	v_lshl_add_u64 v[6:7], v[172:173], 0, s[70:71]
	s_addc_u32 s29, s29, 0
	s_add_i32 s13, s34, s42
	global_load_lds_dwordx4 v[6:7], off
	ds_read_b128 v[212:215], v155 offset:52224
	ds_read_b128 v[216:219], v155 offset:53248
	v_lshl_add_u64 v[6:7], s[28:29], 0, v[142:143]
	s_mov_b32 m0, s13
	s_nop 0
	global_load_lds_dwordx4 v[6:7], off
	ds_read_b128 v[220:223], v155 offset:54272
	ds_read_b128 v[224:227], v155 offset:55296
	v_lshl_add_u64 v[6:7], s[28:29], 0, v[146:147]
	s_add_i32 m0, s13, 0x2000
	s_nop 0
	global_load_lds_dwordx4 v[6:7], off
	ds_read_b128 v[228:231], v155 offset:56320
	v_lshl_add_u64 v[6:7], v[174:175], 0, s[70:71]
	s_mov_b32 m0, s47
	s_nop 0
	global_load_lds_dwordx4 v[6:7], off
	v_lshl_add_u64 v[6:7], v[176:177], 0, s[70:71]
	s_mov_b32 m0, s48
	s_nop 0
	global_load_lds_dwordx4 v[6:7], off
	s_waitcnt vmcnt(8)
	s_waitcnt lgkmcnt(0)
	s_barrier
	s_setprio 1
	s_waitcnt lgkmcnt(0)
	v_mfma_f32_16x16x32_bf16 v[64:67], v[132:135], v[190:193], v[64:67]
	v_mfma_f32_16x16x32_bf16 v[60:63], v[156:159], v[190:193], v[60:63]
	v_mfma_f32_16x16x32_bf16 v[48:51], v[132:135], v[198:201], v[48:51]
	v_mfma_f32_16x16x32_bf16 v[44:47], v[156:159], v[198:201], v[44:47]
	v_mfma_f32_16x16x32_bf16 v[32:35], v[132:135], v[216:219], v[32:35]
	v_mfma_f32_16x16x32_bf16 v[28:31], v[156:159], v[216:219], v[28:31]
	v_mfma_f32_16x16x32_bf16 v[16:19], v[132:135], v[224:227], v[16:19]
	v_mfma_f32_16x16x32_bf16 v[12:15], v[156:159], v[224:227], v[12:15]
	v_mfma_f32_16x16x32_bf16 v[64:67], v[136:139], v[194:197], v[64:67]
	v_mfma_f32_16x16x32_bf16 v[60:63], v[160:163], v[194:197], v[60:63]
	v_mfma_f32_16x16x32_bf16 v[48:51], v[136:139], v[212:215], v[48:51]
	v_mfma_f32_16x16x32_bf16 v[44:47], v[160:163], v[212:215], v[44:47]
	v_mfma_f32_16x16x32_bf16 v[32:35], v[136:139], v[220:223], v[32:35]
	v_mfma_f32_16x16x32_bf16 v[28:31], v[160:163], v[220:223], v[28:31]
	v_mfma_f32_16x16x32_bf16 v[16:19], v[136:139], v[228:231], v[16:19]
	v_mfma_f32_16x16x32_bf16 v[12:15], v[160:163], v[228:231], v[12:15]
	s_setprio 0
	s_setprio 1
	v_mfma_f32_16x16x32_bf16 v[56:59], v[164:167], v[190:193], v[56:59]
	v_mfma_f32_16x16x32_bf16 v[52:55], v[182:185], v[190:193], v[52:55]
	v_mfma_f32_16x16x32_bf16 v[40:43], v[164:167], v[198:201], v[40:43]
	v_mfma_f32_16x16x32_bf16 v[36:39], v[182:185], v[198:201], v[36:39]
	v_mfma_f32_16x16x32_bf16 v[24:27], v[164:167], v[216:219], v[24:27]
	v_mfma_f32_16x16x32_bf16 v[20:23], v[182:185], v[216:219], v[20:23]
	v_mfma_f32_16x16x32_bf16 v[6:9], v[164:167], v[224:227], v[8:11]
	v_mfma_f32_16x16x32_bf16 v[2:5], v[182:185], v[224:227], v[2:5]
	v_mfma_f32_16x16x32_bf16 v[56:59], v[178:181], v[194:197], v[56:59]
	v_mfma_f32_16x16x32_bf16 v[52:55], v[186:189], v[194:197], v[52:55]
	v_mfma_f32_16x16x32_bf16 v[40:43], v[178:181], v[212:215], v[40:43]
	v_mfma_f32_16x16x32_bf16 v[36:39], v[186:189], v[212:215], v[36:39]
	v_mfma_f32_16x16x32_bf16 v[24:27], v[178:181], v[220:223], v[24:27]
	v_mfma_f32_16x16x32_bf16 v[20:23], v[186:189], v[220:223], v[20:23]
	v_mfma_f32_16x16x32_bf16 v[8:11], v[178:181], v[228:231], v[6:9]
	v_mfma_f32_16x16x32_bf16 v[4:7], v[186:189], v[228:231], v[2:5]
	s_setprio 0
	s_barrier
	s_add_i32 s2, s2, 2
	s_add_u32 s24, s24, 0x100
	s_addc_u32 s25, s25, 0
	s_add_u32 s26, s26, 0x100
	s_addc_u32 s27, s27, 0
	s_cmp_gt_u32 s11, 29
	s_cbranch_scc1 .LBB0_467

; #define PG8_STAGE(bufoff, gbase, voff) do { _Pragma("unroll") for (int _i = 0; _i < 2; ++_i) \
;         __builtin_amdgcn_global_load_lds((const unsigned*)((const char*)(gbase) + (voff)[_i]), (LAS unsigned*)(lds + (bufoff) + ldsw + _i * 8192), 16, 0, 0); } while (0)
; #define PG8_LDA(dst, b, h) do { _Pragma("unroll") for (int m = 0; m < 4; ++m) _Pragma("unroll") for (int k = 0; k < 2; ++k) dst[m][k] = *(const LAS bf16x8*)(lds + PG8_SA(b, h) + aoff + m * 2048 + k * 1024); } while (0)
; #define PG8_LDB(dst, b, h) do { _Pragma("unroll") for (int n = 0; n < 2; ++n) _Pragma("unroll") for (int k = 0; k < 2; ++k) dst[n][k] = *(const LAS bf16x8*)(lds + PG8_SB(b, h) + boff + n * 2048 + k * 1024); } while (0)
; #define PG8_MMA(ai, bj, At, Bt) do { __builtin_amdgcn_s_setprio(1); _Pragma("unroll") for (int m = 0; m < 4; ++m) _Pragma("unroll") for (int n = 0; n < 2; ++n) _Pragma("unroll") for (int k = 0; k < 2; ++k) \
;         acc[ai][bj][m][n] = __builtin_amdgcn_mfma_f32_16x16x32_bf16(Bt[n][k], At[m][k], acc[ai][bj][m][n], 0, 0, 0); __builtin_amdgcn_s_setprio(0); } while (0)
; #define PG8_WAIT_V(n) asm volatile("s_waitcnt vmcnt(" #n ")" ::: "memory")
; #define PG8_WAIT_L(n) asm volatile("s_waitcnt lgkmcnt(" #n ")" ::: "memory")
; #define PG8_BAR __builtin_amdgcn_s_barrier()
; template <class Epi>
; __device__ __forceinline__ void gemm_phase(LAS unsigned char* lds, const Gemm g, const StaticOrder& S, const Epi& E, const int tid) {
;     ...
;             const char* a2 = last ? nA : (s2 ? cA2 + (size_t)(t + 2 - nt) * kstep : cA + (size_t)(t + 2) * kstep);
;             const char* b2 = last ? nB : (s2 ? cB2 + (size_t)(t + 2 - nt) * kstep : cB + (size_t)(t + 2) * kstep);
;             const char* a3 = a2 + kstep; const char* b3 = b2 + kstep;
;             if constexpr (Epi::TWO) { if (t == nt) E.mid(acc, cur, wr, wc, fr, fq); }
;             if constexpr (SP2) {
;             PG8_LDB(B0, 0, 0); PG8_LDB(B1, 0, 1); PG8_SCHED; PG8_LDA(At, 0, 0); PG8_STAGE(PG8_SA(1, 1), a1 + hstep, voffA);
;             PG8_WAIT_V(8); PG8_WAIT_L(0); PG8_BAR; PG8_MMA(0, 0, At, B0); PG8_MMA(0, 1, At, B1); PG8_BAR; PG8_SCHED;
;             PG8_LDA(At, 0, 1); PG8_STAGE(PG8_SB(0, 0), b2, voffB); PG8_STAGE(PG8_SB(0, 1), b2 + bhs, voffB); PG8_STAGE(PG8_SA(0, 0), a2, voffA);
;             PG8_WAIT_V(8); PG8_WAIT_L(0); PG8_BAR; PG8_MMA(1, 0, At, B0); PG8_MMA(1, 1, At, B1); PG8_BAR; PG8_SCHED;
.LBB0_546:
	s_add_u32 s28, s26, 0xfff80080
	s_addc_u32 s29, s27, -1
	s_add_i32 s44, 0, 0x10000
	s_cmp_eq_u32 s39, 28
	s_cselect_b32 s35, s19, s29
	s_cselect_b32 s34, s31, s28
	v_add_u32_e32 v0, s44, v149
	s_cselect_b32 s29, s17, s38
	s_cselect_b32 s28, s33, s37
	s_add_i32 s46, 0, 0x14000
	ds_read_b128 v[150:153], v0
	ds_read_b128 v[154:157], v0 offset:1024
	ds_read_b128 v[158:161], v0 offset:2048
	ds_read_b128 v[186:189], v0 offset:3072
	v_add_u32_e32 v0, s46, v149
	ds_read_b128 v[190:193], v0
	ds_read_b128 v[194:197], v0 offset:1024
	ds_read_b128 v[198:201], v0 offset:2048
	ds_read_b128 v[212:215], v0 offset:3072
	v_lshl_add_u64 v[162:163], s[26:27], 0, v[146:147]
	s_add_i32 m0, s57, 0xc000
	ds_read_b128 v[216:219], v184
	global_load_lds_dwordx4 v[162:163], off
	ds_read_b128 v[220:223], v184 offset:1024
	ds_read_b128 v[224:227], v184 offset:2048
	v_lshl_add_u64 v[162:163], s[26:27], 0, v[144:145]
	s_add_i32 m0, s57, 0xe000
	s_nop 0
	global_load_lds_dwordx4 v[162:163], off
	ds_read_b128 v[228:231], v184 offset:3072
	ds_read_b128 v[232:235], v184 offset:4096
	ds_read_b128 v[236:239], v184 offset:5120
	ds_read_b128 v[240:243], v184 offset:6144
	ds_read_b128 v[244:247], v184 offset:7168
	s_waitcnt vmcnt(8)
	s_waitcnt lgkmcnt(0)
	s_barrier
	s_setprio 1
	s_waitcnt lgkmcnt(0)
	v_mfma_f32_16x16x32_bf16 v[126:129], v[150:153], v[216:219], v[126:129]
	v_mfma_f32_16x16x32_bf16 v[122:125], v[158:161], v[216:219], v[122:125]
	v_mfma_f32_16x16x32_bf16 v[110:113], v[150:153], v[224:227], v[110:113]
	v_mfma_f32_16x16x32_bf16 v[106:109], v[158:161], v[224:227], v[106:109]
	v_mfma_f32_16x16x32_bf16 v[94:97], v[150:153], v[232:235], v[94:97]
	v_mfma_f32_16x16x32_bf16 v[90:93], v[158:161], v[232:235], v[90:93]
	v_mfma_f32_16x16x32_bf16 v[78:81], v[150:153], v[240:243], v[78:81]
	v_mfma_f32_16x16x32_bf16 v[74:77], v[158:161], v[240:243], v[74:77]
	v_mfma_f32_16x16x32_bf16 v[126:129], v[154:157], v[220:223], v[126:129]
	v_mfma_f32_16x16x32_bf16 v[122:125], v[186:189], v[220:223], v[122:125]
	v_mfma_f32_16x16x32_bf16 v[110:113], v[154:157], v[228:231], v[110:113]
	v_mfma_f32_16x16x32_bf16 v[106:109], v[186:189], v[228:231], v[106:109]
	v_mfma_f32_16x16x32_bf16 v[94:97], v[154:157], v[236:239], v[94:97]
	v_mfma_f32_16x16x32_bf16 v[90:93], v[186:189], v[236:239], v[90:93]
	v_mfma_f32_16x16x32_bf16 v[78:81], v[154:157], v[244:247], v[78:81]
	v_mfma_f32_16x16x32_bf16 v[74:77], v[186:189], v[244:247], v[74:77]
	s_setprio 0
	s_setprio 1
	v_mfma_f32_16x16x32_bf16 v[118:121], v[190:193], v[216:219], v[118:121]
	v_mfma_f32_16x16x32_bf16 v[114:117], v[198:201], v[216:219], v[114:117]
	v_mfma_f32_16x16x32_bf16 v[102:105], v[190:193], v[224:227], v[102:105]
	v_mfma_f32_16x16x32_bf16 v[98:101], v[198:201], v[224:227], v[98:101]
	v_mfma_f32_16x16x32_bf16 v[86:89], v[190:193], v[232:235], v[86:89]
	v_mfma_f32_16x16x32_bf16 v[82:85], v[198:201], v[232:235], v[82:85]
	v_mfma_f32_16x16x32_bf16 v[70:73], v[190:193], v[240:243], v[70:73]
	v_mfma_f32_16x16x32_bf16 v[66:69], v[198:201], v[240:243], v[66:69]
	v_mfma_f32_16x16x32_bf16 v[118:121], v[194:197], v[220:223], v[118:121]
	v_mfma_f32_16x16x32_bf16 v[114:117], v[212:215], v[220:223], v[114:117]
	v_mfma_f32_16x16x32_bf16 v[102:105], v[194:197], v[228:231], v[102:105]
	v_mfma_f32_16x16x32_bf16 v[98:101], v[212:215], v[228:231], v[98:101]
	v_mfma_f32_16x16x32_bf16 v[86:89], v[194:197], v[236:239], v[86:89]
	v_mfma_f32_16x16x32_bf16 v[82:85], v[212:215], v[236:239], v[82:85]
	v_mfma_f32_16x16x32_bf16 v[70:73], v[194:197], v[244:247], v[70:73]
	v_mfma_f32_16x16x32_bf16 v[66:69], v[212:215], v[244:247], v[66:69]
	s_setprio 0
	s_barrier
	s_add_i32 s44, s44, s56
	v_lshl_add_u64 v[162:163], s[28:29], 0, v[132:133]
	s_mov_b32 m0, s44
	ds_read_b128 v[216:219], v184 offset:16384
	global_load_lds_dwordx4 v[162:163], off
	ds_read_b128 v[220:223], v184 offset:17408
	ds_read_b128 v[224:227], v184 offset:18432
	s_add_i32 m0, s44, 0x2000
	s_add_u32 s44, s28, 0x8000
	v_lshl_add_u64 v[248:249], s[28:29], 0, v[136:137]
	s_addc_u32 s45, s29, 0
	s_add_i32 s46, s46, s56
	global_load_lds_dwordx4 v[248:249], off
	ds_read_b128 v[228:231], v184 offset:19456
	ds_read_b128 v[232:235], v184 offset:20480
	v_lshl_add_u64 v[172:173], s[44:45], 0, v[132:133]
	s_mov_b32 m0, s46
	v_lshl_add_u64 v[174:175], s[34:35], 0, v[134:135]
	global_load_lds_dwordx4 v[172:173], off
	ds_read_b128 v[236:239], v184 offset:21504
	ds_read_b128 v[240:243], v184 offset:22528
	v_lshl_add_u64 v[172:173], s[44:45], 0, v[136:137]
	s_add_i32 m0, s46, 0x2000
	s_nop 0
	global_load_lds_dwordx4 v[172:173], off
	ds_read_b128 v[244:247], v184 offset:23552
	v_lshl_add_u64 v[172:173], s[34:35], 0, v[130:131]
	s_mov_b32 m0, s57
	s_nop 0
	global_load_lds_dwordx4 v[172:173], off
	s_mov_b32 m0, s58
	s_nop 0
	global_load_lds_dwordx4 v[174:175], off
	s_waitcnt vmcnt(8)
	s_waitcnt lgkmcnt(0)
	s_barrier
; #define PG8_STAGE(bufoff, gbase, voff) do { _Pragma("unroll") for (int _i = 0; _i < 2; ++_i) \
;         __builtin_amdgcn_global_load_lds((const unsigned*)((const char*)(gbase) + (voff)[_i]), (LAS unsigned*)(lds + (bufoff) + ldsw + _i * 8192), 16, 0, 0); } while (0)
; #define PG8_LDA(dst, b, h) do { _Pragma("unroll") for (int m = 0; m < 4; ++m) _Pragma("unroll") for (int k = 0; k < 2; ++k) dst[m][k] = *(const LAS bf16x8*)(lds + PG8_SA(b, h) + aoff + m * 2048 + k * 1024); } while (0)
; #define PG8_LDB(dst, b, h) do { _Pragma("unroll") for (int n = 0; n < 2; ++n) _Pragma("unroll") for (int k = 0; k < 2; ++k) dst[n][k] = *(const LAS bf16x8*)(lds + PG8_SB(b, h) + boff + n * 2048 + k * 1024); } while (0)
; #define PG8_MMA(ai, bj, At, Bt) do { __builtin_amdgcn_s_setprio(1); _Pragma("unroll") for (int m = 0; m < 4; ++m) _Pragma("unroll") for (int n = 0; n < 2; ++n) _Pragma("unroll") for (int k = 0; k < 2; ++k) \
;         acc[ai][bj][m][n] = __builtin_amdgcn_mfma_f32_16x16x32_bf16(Bt[n][k], At[m][k], acc[ai][bj][m][n], 0, 0, 0); __builtin_amdgcn_s_setprio(0); } while (0)
; #define PG8_WAIT_V(n) asm volatile("s_waitcnt vmcnt(" #n ")" ::: "memory")
; #define PG8_WAIT_L(n) asm volatile("s_waitcnt lgkmcnt(" #n ")" ::: "memory")
; #define PG8_BAR __builtin_amdgcn_s_barrier()
; #define PG8_SCHED __builtin_amdgcn_sched_barrier(0)
; template <class Epi>
; __device__ __forceinline__ void gemm_phase(LAS unsigned char* lds, const Gemm g, const StaticOrder& S, const Epi& E, const int tid) {
;     ...
;             PG8_WAIT_V(8); PG8_WAIT_L(0); PG8_BAR; PG8_MMA(1, 0, At, B0); PG8_MMA(1, 1, At, B1); PG8_BAR; PG8_SCHED;
;             PG8_LDB(B0, 1, 0); PG8_LDB(B1, 1, 1); PG8_SCHED; PG8_LDA(At, 1, 0); PG8_STAGE(PG8_SA(0, 1), a2 + hstep, voffA);
;             PG8_WAIT_V(8); PG8_WAIT_L(0); PG8_BAR; PG8_MMA(0, 0, At, B0); PG8_MMA(0, 1, At, B1); PG8_BAR; PG8_SCHED;
	s_setprio 1
	s_waitcnt lgkmcnt(0)
	v_mfma_f32_16x16x32_bf16 v[62:65], v[150:153], v[216:219], v[62:65]
	v_mfma_f32_16x16x32_bf16 v[58:61], v[158:161], v[216:219], v[58:61]
	v_mfma_f32_16x16x32_bf16 v[46:49], v[150:153], v[224:227], v[46:49]
	v_mfma_f32_16x16x32_bf16 v[42:45], v[158:161], v[224:227], v[42:45]
	v_mfma_f32_16x16x32_bf16 v[30:33], v[150:153], v[232:235], v[30:33]
	v_mfma_f32_16x16x32_bf16 v[26:29], v[158:161], v[232:235], v[26:29]
	v_mfma_f32_16x16x32_bf16 v[14:17], v[150:153], v[240:243], v[14:17]
	v_mfma_f32_16x16x32_bf16 v[10:13], v[158:161], v[240:243], v[10:13]
	v_mfma_f32_16x16x32_bf16 v[62:65], v[154:157], v[220:223], v[62:65]
	v_mfma_f32_16x16x32_bf16 v[58:61], v[186:189], v[220:223], v[58:61]
	v_mfma_f32_16x16x32_bf16 v[46:49], v[154:157], v[228:231], v[46:49]
	v_mfma_f32_16x16x32_bf16 v[42:45], v[186:189], v[228:231], v[42:45]
	v_mfma_f32_16x16x32_bf16 v[30:33], v[154:157], v[236:239], v[30:33]
	v_mfma_f32_16x16x32_bf16 v[26:29], v[186:189], v[236:239], v[26:29]
	v_mfma_f32_16x16x32_bf16 v[14:17], v[154:157], v[244:247], v[14:17]
	v_mfma_f32_16x16x32_bf16 v[10:13], v[186:189], v[244:247], v[10:13]
	s_setprio 0
	s_setprio 1
	v_mfma_f32_16x16x32_bf16 v[54:57], v[190:193], v[216:219], v[54:57]
	v_mfma_f32_16x16x32_bf16 v[50:53], v[198:201], v[216:219], v[50:53]
	v_mfma_f32_16x16x32_bf16 v[38:41], v[190:193], v[224:227], v[38:41]
	v_mfma_f32_16x16x32_bf16 v[34:37], v[198:201], v[224:227], v[34:37]
	v_mfma_f32_16x16x32_bf16 v[22:25], v[190:193], v[232:235], v[22:25]
	v_mfma_f32_16x16x32_bf16 v[18:21], v[198:201], v[232:235], v[18:21]
	v_mfma_f32_16x16x32_bf16 v[6:9], v[190:193], v[240:243], v[6:9]
	v_mfma_f32_16x16x32_bf16 v[2:5], v[198:201], v[240:243], v[2:5]
	v_mfma_f32_16x16x32_bf16 v[54:57], v[194:197], v[220:223], v[54:57]
	v_mfma_f32_16x16x32_bf16 v[50:53], v[212:215], v[220:223], v[50:53]
	v_mfma_f32_16x16x32_bf16 v[38:41], v[194:197], v[228:231], v[38:41]
	v_mfma_f32_16x16x32_bf16 v[34:37], v[212:215], v[228:231], v[34:37]
	v_mfma_f32_16x16x32_bf16 v[22:25], v[194:197], v[236:239], v[22:25]
	v_mfma_f32_16x16x32_bf16 v[18:21], v[212:215], v[236:239], v[18:21]
	v_mfma_f32_16x16x32_bf16 v[6:9], v[194:197], v[244:247], v[6:9]
	v_mfma_f32_16x16x32_bf16 v[2:5], v[212:215], v[244:247], v[2:5]
	s_setprio 0
	s_barrier
	s_add_i32 s44, 0, 0x18000
	v_add_u32_e32 v0, s44, v149
	s_add_i32 s45, 0, 0x1c000
	ds_read_b128 v[150:153], v0
	ds_read_b128 v[154:157], v0 offset:1024
	ds_read_b128 v[158:161], v0 offset:2048
	ds_read_b128 v[186:189], v0 offset:3072
	v_add_u32_e32 v0, s45, v149
	ds_read_b128 v[190:193], v0
	ds_read_b128 v[194:197], v0 offset:1024
	ds_read_b128 v[198:201], v0 offset:2048
	ds_read_b128 v[212:215], v0 offset:3072
	s_add_u32 s34, s34, 0x80000
	s_addc_u32 s35, s35, 0
	s_mov_b32 m0, s59
	v_lshl_add_u64 v[176:177], s[34:35], 0, v[130:131]
	ds_read_b128 v[216:219], v184 offset:32768
	global_load_lds_dwordx4 v[176:177], off
	ds_read_b128 v[220:223], v184 offset:33792
	ds_read_b128 v[224:227], v184 offset:34816
	v_lshl_add_u64 v[176:177], s[34:35], 0, v[134:135]
	s_mov_b32 m0, s60
	s_nop 0
	global_load_lds_dwordx4 v[176:177], off
	ds_read_b128 v[228:231], v184 offset:35840
	ds_read_b128 v[232:235], v184 offset:36864
	ds_read_b128 v[236:239], v184 offset:37888
	ds_read_b128 v[240:243], v184 offset:38912
	ds_read_b128 v[244:247], v184 offset:39936
	s_waitcnt vmcnt(8)
	s_waitcnt lgkmcnt(0)
	s_barrier
	s_setprio 1
	s_waitcnt lgkmcnt(0)
	v_mfma_f32_16x16x32_bf16 v[126:129], v[150:153], v[216:219], v[126:129]
	v_mfma_f32_16x16x32_bf16 v[122:125], v[158:161], v[216:219], v[122:125]
	v_mfma_f32_16x16x32_bf16 v[110:113], v[150:153], v[224:227], v[110:113]
	v_mfma_f32_16x16x32_bf16 v[106:109], v[158:161], v[224:227], v[106:109]
	v_mfma_f32_16x16x32_bf16 v[94:97], v[150:153], v[232:235], v[94:97]
	v_mfma_f32_16x16x32_bf16 v[90:93], v[158:161], v[232:235], v[90:93]
	v_mfma_f32_16x16x32_bf16 v[78:81], v[150:153], v[240:243], v[78:81]
	v_mfma_f32_16x16x32_bf16 v[74:77], v[158:161], v[240:243], v[74:77]
	v_mfma_f32_16x16x32_bf16 v[126:129], v[154:157], v[220:223], v[126:129]
	v_mfma_f32_16x16x32_bf16 v[122:125], v[186:189], v[220:223], v[122:125]
	v_mfma_f32_16x16x32_bf16 v[110:113], v[154:157], v[228:231], v[110:113]
	v_mfma_f32_16x16x32_bf16 v[106:109], v[186:189], v[228:231], v[106:109]
	v_mfma_f32_16x16x32_bf16 v[94:97], v[154:157], v[236:239], v[94:97]
	v_mfma_f32_16x16x32_bf16 v[90:93], v[186:189], v[236:239], v[90:93]
	v_mfma_f32_16x16x32_bf16 v[78:81], v[154:157], v[244:247], v[78:81]
	v_mfma_f32_16x16x32_bf16 v[74:77], v[186:189], v[244:247], v[74:77]
	s_setprio 0
	s_setprio 1
	v_mfma_f32_16x16x32_bf16 v[118:121], v[190:193], v[216:219], v[118:121]
	v_mfma_f32_16x16x32_bf16 v[114:117], v[198:201], v[216:219], v[114:117]
	v_mfma_f32_16x16x32_bf16 v[102:105], v[190:193], v[224:227], v[102:105]
	v_mfma_f32_16x16x32_bf16 v[98:101], v[198:201], v[224:227], v[98:101]
	v_mfma_f32_16x16x32_bf16 v[86:89], v[190:193], v[232:235], v[86:89]
	v_mfma_f32_16x16x32_bf16 v[82:85], v[198:201], v[232:235], v[82:85]
	v_mfma_f32_16x16x32_bf16 v[70:73], v[190:193], v[240:243], v[70:73]
	v_mfma_f32_16x16x32_bf16 v[66:69], v[198:201], v[240:243], v[66:69]
	v_mfma_f32_16x16x32_bf16 v[118:121], v[194:197], v[220:223], v[118:121]
	v_mfma_f32_16x16x32_bf16 v[114:117], v[212:215], v[220:223], v[114:117]
	v_mfma_f32_16x16x32_bf16 v[102:105], v[194:197], v[228:231], v[102:105]
	v_mfma_f32_16x16x32_bf16 v[98:101], v[212:215], v[228:231], v[98:101]
	v_mfma_f32_16x16x32_bf16 v[86:89], v[194:197], v[236:239], v[86:89]
	v_mfma_f32_16x16x32_bf16 v[82:85], v[212:215], v[236:239], v[82:85]
	v_mfma_f32_16x16x32_bf16 v[70:73], v[194:197], v[244:247], v[70:73]
	v_mfma_f32_16x16x32_bf16 v[66:69], v[212:215], v[244:247], v[66:69]
	s_setprio 0
	s_barrier
; #define PG8_STAGE(bufoff, gbase, voff) do { _Pragma("unroll") for (int _i = 0; _i < 2; ++_i) \
;         __builtin_amdgcn_global_load_lds((const unsigned*)((const char*)(gbase) + (voff)[_i]), (LAS unsigned*)(lds + (bufoff) + ldsw + _i * 8192), 16, 0, 0); } while (0)
; #define PG8_LDA(dst, b, h) do { _Pragma("unroll") for (int m = 0; m < 4; ++m) _Pragma("unroll") for (int k = 0; k < 2; ++k) dst[m][k] = *(const LAS bf16x8*)(lds + PG8_SA(b, h) + aoff + m * 2048 + k * 1024); } while (0)
; #define PG8_MMA(ai, bj, At, Bt) do { __builtin_amdgcn_s_setprio(1); _Pragma("unroll") for (int m = 0; m < 4; ++m) _Pragma("unroll") for (int n = 0; n < 2; ++n) _Pragma("unroll") for (int k = 0; k < 2; ++k) \
;         acc[ai][bj][m][n] = __builtin_amdgcn_mfma_f32_16x16x32_bf16(Bt[n][k], At[m][k], acc[ai][bj][m][n], 0, 0, 0); __builtin_amdgcn_s_setprio(0); } while (0)
; #define PG8_WAIT_V(n) asm volatile("s_waitcnt vmcnt(" #n ")" ::: "memory")
; #define PG8_WAIT_L(n) asm volatile("s_waitcnt lgkmcnt(" #n ")" ::: "memory")
; #define PG8_BAR __builtin_amdgcn_s_barrier()
; #define PG8_SCHED __builtin_amdgcn_sched_barrier(0)
; template <class Epi>
; __device__ __forceinline__ void gemm_phase(LAS unsigned char* lds, const Gemm g, const StaticOrder& S, const Epi& E, const int tid) {
;     ...
;             PG8_LDA(At, 1, 1); PG8_STAGE(PG8_SB(1, 0), b3, voffB); PG8_STAGE(PG8_SB(1, 1), b3 + bhs, voffB); PG8_STAGE(PG8_SA(1, 0), a3, voffA);
;             PG8_WAIT_V(8); PG8_WAIT_L(0); PG8_BAR; PG8_MMA(1, 0, At, B0); PG8_MMA(1, 1, At, B1); PG8_BAR; PG8_SCHED;
;     ...
;         if (ALIGN_EPI) { if (wr == 0) PG8_BAR; }
	s_add_i32 s34, s44, s56
	v_lshl_add_u64 v[162:163], v[162:163], 0, s[70:71]
	s_mov_b32 m0, s34
	ds_read_b128 v[216:219], v184 offset:49152
	global_load_lds_dwordx4 v[162:163], off
	ds_read_b128 v[220:223], v184 offset:50176
	ds_read_b128 v[224:227], v184 offset:51200
	s_add_i32 m0, s34, 0x2000
	s_add_u32 s28, s28, 0x8080
	v_lshl_add_u64 v[162:163], v[248:249], 0, s[70:71]
	s_addc_u32 s29, s29, 0
	s_add_i32 s34, s45, s56
	global_load_lds_dwordx4 v[162:163], off
	ds_read_b128 v[228:231], v184 offset:52224
	ds_read_b128 v[232:235], v184 offset:53248
	v_lshl_add_u64 v[162:163], s[28:29], 0, v[132:133]
	s_mov_b32 m0, s34
	s_nop 0
	global_load_lds_dwordx4 v[162:163], off
	ds_read_b128 v[236:239], v184 offset:54272
	ds_read_b128 v[240:243], v184 offset:55296
	v_lshl_add_u64 v[162:163], s[28:29], 0, v[136:137]
	s_add_i32 m0, s34, 0x2000
	s_nop 0
	global_load_lds_dwordx4 v[162:163], off
	ds_read_b128 v[244:247], v184 offset:56320
	v_lshl_add_u64 v[162:163], v[172:173], 0, s[70:71]
	s_mov_b32 m0, s61
	s_nop 0
	global_load_lds_dwordx4 v[162:163], off
	v_lshl_add_u64 v[162:163], v[174:175], 0, s[70:71]
	s_mov_b32 m0, s62
	s_nop 0
	global_load_lds_dwordx4 v[162:163], off
	s_waitcnt vmcnt(8)
	s_waitcnt lgkmcnt(0)
	s_barrier
	s_setprio 1
	s_waitcnt lgkmcnt(0)
	v_mfma_f32_16x16x32_bf16 v[62:65], v[150:153], v[216:219], v[62:65]
	v_mfma_f32_16x16x32_bf16 v[58:61], v[158:161], v[216:219], v[58:61]
	v_mfma_f32_16x16x32_bf16 v[46:49], v[150:153], v[224:227], v[46:49]
	v_mfma_f32_16x16x32_bf16 v[42:45], v[158:161], v[224:227], v[42:45]
	v_mfma_f32_16x16x32_bf16 v[30:33], v[150:153], v[232:235], v[30:33]
	v_mfma_f32_16x16x32_bf16 v[26:29], v[158:161], v[232:235], v[26:29]
	v_mfma_f32_16x16x32_bf16 v[14:17], v[150:153], v[240:243], v[14:17]
	v_mfma_f32_16x16x32_bf16 v[10:13], v[158:161], v[240:243], v[10:13]
	v_mfma_f32_16x16x32_bf16 v[62:65], v[154:157], v[220:223], v[62:65]
	v_mfma_f32_16x16x32_bf16 v[58:61], v[186:189], v[220:223], v[58:61]
	v_mfma_f32_16x16x32_bf16 v[46:49], v[154:157], v[228:231], v[46:49]
	v_mfma_f32_16x16x32_bf16 v[42:45], v[186:189], v[228:231], v[42:45]
	v_mfma_f32_16x16x32_bf16 v[30:33], v[154:157], v[236:239], v[30:33]
	v_mfma_f32_16x16x32_bf16 v[26:29], v[186:189], v[236:239], v[26:29]
	v_mfma_f32_16x16x32_bf16 v[14:17], v[154:157], v[244:247], v[14:17]
	v_mfma_f32_16x16x32_bf16 v[10:13], v[186:189], v[244:247], v[10:13]
	s_setprio 0
	s_setprio 1
	v_mfma_f32_16x16x32_bf16 v[54:57], v[190:193], v[216:219], v[54:57]
	v_mfma_f32_16x16x32_bf16 v[50:53], v[198:201], v[216:219], v[50:53]
	v_mfma_f32_16x16x32_bf16 v[38:41], v[190:193], v[224:227], v[38:41]
	v_mfma_f32_16x16x32_bf16 v[34:37], v[198:201], v[224:227], v[34:37]
	v_mfma_f32_16x16x32_bf16 v[22:25], v[190:193], v[232:235], v[22:25]
	v_mfma_f32_16x16x32_bf16 v[18:21], v[198:201], v[232:235], v[18:21]
	v_mfma_f32_16x16x32_bf16 v[6:9], v[190:193], v[240:243], v[6:9]
	v_mfma_f32_16x16x32_bf16 v[2:5], v[198:201], v[240:243], v[2:5]
	v_mfma_f32_16x16x32_bf16 v[54:57], v[194:197], v[220:223], v[54:57]
	v_mfma_f32_16x16x32_bf16 v[50:53], v[212:215], v[220:223], v[50:53]
	v_mfma_f32_16x16x32_bf16 v[38:41], v[194:197], v[228:231], v[38:41]
	v_mfma_f32_16x16x32_bf16 v[34:37], v[212:215], v[228:231], v[34:37]
	v_mfma_f32_16x16x32_bf16 v[22:25], v[194:197], v[236:239], v[22:25]
	v_mfma_f32_16x16x32_bf16 v[18:21], v[212:215], v[236:239], v[18:21]
	v_mfma_f32_16x16x32_bf16 v[6:9], v[194:197], v[244:247], v[6:9]
	v_mfma_f32_16x16x32_bf16 v[2:5], v[212:215], v[244:247], v[2:5]
	s_setprio 0
	s_barrier
	s_add_i32 s39, s39, 2
	s_add_u32 s37, s37, 0x100
	s_addc_u32 s38, s38, 0
	s_add_u32 s26, s26, 0x100
	s_addc_u32 s27, s27, 0
	s_cmp_gt_u32 s39, 29
	s_cbranch_scc0 .LBB0_546
	s_and_b64 vcc, exec, s[14:15]
	s_cbranch_vccz .LBB0_549
	s_barrier

; #define PG8_STAGE(bufoff, gbase, voff) do { _Pragma("unroll") for (int _i = 0; _i < 2; ++_i) \
;         __builtin_amdgcn_global_load_lds((const unsigned*)((const char*)(gbase) + (voff)[_i]), (LAS unsigned*)(lds + (bufoff) + ldsw + _i * 8192), 16, 0, 0); } while (0)
; #define PG8_LDA(dst, b, h) do { _Pragma("unroll") for (int m = 0; m < 4; ++m) _Pragma("unroll") for (int k = 0; k < 2; ++k) dst[m][k] = *(const LAS bf16x8*)(lds + PG8_SA(b, h) + aoff + m * 2048 + k * 1024); } while (0)
; #define PG8_LDB(dst, b, h) do { _Pragma("unroll") for (int n = 0; n < 2; ++n) _Pragma("unroll") for (int k = 0; k < 2; ++k) dst[n][k] = *(const LAS bf16x8*)(lds + PG8_SB(b, h) + boff + n * 2048 + k * 1024); } while (0)
; #define PG8_MMA(ai, bj, At, Bt) do { __builtin_amdgcn_s_setprio(1); _Pragma("unroll") for (int m = 0; m < 4; ++m) _Pragma("unroll") for (int n = 0; n < 2; ++n) _Pragma("unroll") for (int k = 0; k < 2; ++k) \
;         acc[ai][bj][m][n] = __builtin_amdgcn_mfma_f32_16x16x32_bf16(Bt[n][k], At[m][k], acc[ai][bj][m][n], 0, 0, 0); __builtin_amdgcn_s_setprio(0); } while (0)
; #define PG8_WAIT_V(n) asm volatile("s_waitcnt vmcnt(" #n ")" ::: "memory")
; #define PG8_WAIT_L(n) asm volatile("s_waitcnt lgkmcnt(" #n ")" ::: "memory")
; #define PG8_BAR __builtin_amdgcn_s_barrier()
; template <class Epi>
; __device__ __forceinline__ void gemm_phase(LAS unsigned char* lds, const Gemm g, const StaticOrder& S, const Epi& E, const int tid) {
;     ...
;             const char* a2 = last ? nA : (s2 ? cA2 + (size_t)(t + 2 - nt) * kstep : cA + (size_t)(t + 2) * kstep);
;             const char* b2 = last ? nB : (s2 ? cB2 + (size_t)(t + 2 - nt) * kstep : cB + (size_t)(t + 2) * kstep);
;             const char* a3 = a2 + kstep; const char* b3 = b2 + kstep;
;             if constexpr (Epi::TWO) { if (t == nt) E.mid(acc, cur, wr, wc, fr, fq); }
;             if constexpr (SP2) {
;             PG8_LDB(B0, 0, 0); PG8_LDB(B1, 0, 1); PG8_SCHED; PG8_LDA(At, 0, 0); PG8_STAGE(PG8_SA(1, 1), a1 + hstep, voffA);
;             PG8_WAIT_V(8); PG8_WAIT_L(0); PG8_BAR; PG8_MMA(0, 0, At, B0); PG8_MMA(0, 1, At, B1); PG8_BAR; PG8_SCHED;
;             PG8_LDA(At, 0, 1); PG8_STAGE(PG8_SB(0, 0), b2, voffB); PG8_STAGE(PG8_SB(0, 1), b2 + bhs, voffB); PG8_STAGE(PG8_SA(0, 0), a2, voffA);
;             PG8_WAIT_V(8); PG8_WAIT_L(0); PG8_BAR; PG8_MMA(1, 0, At, B0); PG8_MMA(1, 1, At, B1); PG8_BAR; PG8_SCHED;
.LBB0_844:
	s_add_u32 s28, s26, 0xfff80080
	s_addc_u32 s29, s27, -1
	s_add_i32 s48, 0, 0x10000
	s_cmp_eq_u32 s47, 28
	s_cselect_b32 s31, s15, s29
	s_cselect_b32 s30, s43, s28
	v_add_u32_e32 v145, s48, v142
	s_cselect_b32 s29, s13, s46
	s_cselect_b32 s28, s44, s45
	s_add_i32 s50, 0, 0x14000
	ds_read_b128 v[146:149], v145
	ds_read_b128 v[150:153], v145 offset:1024
	ds_read_b128 v[154:157], v145 offset:2048
	ds_read_b128 v[158:161], v145 offset:3072
	v_add_u32_e32 v145, s50, v142
	ds_read_b128 v[162:165], v145
	ds_read_b128 v[166:169], v145 offset:1024
	ds_read_b128 v[178:181], v145 offset:2048
	ds_read_b128 v[182:185], v145 offset:3072
	v_lshl_add_u64 v[172:173], s[26:27], 0, v[138:139]
	s_add_i32 m0, s23, 0xc000
	ds_read_b128 v[186:189], v144
	global_load_lds_dwordx4 v[172:173], off
	ds_read_b128 v[190:193], v144 offset:1024
	ds_read_b128 v[194:197], v144 offset:2048
	v_lshl_add_u64 v[172:173], s[26:27], 0, v[136:137]
	s_add_i32 m0, s23, 0xe000
	s_nop 0
	global_load_lds_dwordx4 v[172:173], off
	ds_read_b128 v[198:201], v144 offset:3072
	ds_read_b128 v[212:215], v144 offset:4096
	ds_read_b128 v[216:219], v144 offset:5120
	ds_read_b128 v[220:223], v144 offset:6144
	ds_read_b128 v[224:227], v144 offset:7168
	s_waitcnt vmcnt(8)
	s_waitcnt lgkmcnt(0)
	s_barrier
	s_setprio 1
	s_waitcnt lgkmcnt(0)
	v_mfma_f32_16x16x32_bf16 v[126:129], v[146:149], v[186:189], v[126:129]
	v_mfma_f32_16x16x32_bf16 v[122:125], v[154:157], v[186:189], v[122:125]
	v_mfma_f32_16x16x32_bf16 v[118:121], v[146:149], v[194:197], v[118:121]
	v_mfma_f32_16x16x32_bf16 v[110:113], v[154:157], v[194:197], v[110:113]
	v_mfma_f32_16x16x32_bf16 v[102:105], v[146:149], v[212:215], v[102:105]
	v_mfma_f32_16x16x32_bf16 v[94:97], v[154:157], v[212:215], v[94:97]
	v_mfma_f32_16x16x32_bf16 v[86:89], v[146:149], v[220:223], v[86:89]
	v_mfma_f32_16x16x32_bf16 v[78:81], v[154:157], v[220:223], v[78:81]
	v_mfma_f32_16x16x32_bf16 v[126:129], v[150:153], v[190:193], v[126:129]
	v_mfma_f32_16x16x32_bf16 v[122:125], v[158:161], v[190:193], v[122:125]
	v_mfma_f32_16x16x32_bf16 v[118:121], v[150:153], v[198:201], v[118:121]
	v_mfma_f32_16x16x32_bf16 v[110:113], v[158:161], v[198:201], v[110:113]
	v_mfma_f32_16x16x32_bf16 v[102:105], v[150:153], v[216:219], v[102:105]
	v_mfma_f32_16x16x32_bf16 v[94:97], v[158:161], v[216:219], v[94:97]
	v_mfma_f32_16x16x32_bf16 v[86:89], v[150:153], v[224:227], v[86:89]
	v_mfma_f32_16x16x32_bf16 v[78:81], v[158:161], v[224:227], v[78:81]
	s_setprio 0
	s_setprio 1
	v_mfma_f32_16x16x32_bf16 v[114:117], v[162:165], v[186:189], v[114:117]
	v_mfma_f32_16x16x32_bf16 v[106:109], v[178:181], v[186:189], v[106:109]
	v_mfma_f32_16x16x32_bf16 v[98:101], v[162:165], v[194:197], v[98:101]
	v_mfma_f32_16x16x32_bf16 v[90:93], v[178:181], v[194:197], v[90:93]
	v_mfma_f32_16x16x32_bf16 v[82:85], v[162:165], v[212:215], v[82:85]
	v_mfma_f32_16x16x32_bf16 v[74:77], v[178:181], v[212:215], v[74:77]
	v_mfma_f32_16x16x32_bf16 v[70:73], v[162:165], v[220:223], v[70:73]
	v_mfma_f32_16x16x32_bf16 v[66:69], v[178:181], v[220:223], v[66:69]
	v_mfma_f32_16x16x32_bf16 v[114:117], v[166:169], v[190:193], v[114:117]
	v_mfma_f32_16x16x32_bf16 v[106:109], v[182:185], v[190:193], v[106:109]
	v_mfma_f32_16x16x32_bf16 v[98:101], v[166:169], v[198:201], v[98:101]
	v_mfma_f32_16x16x32_bf16 v[90:93], v[182:185], v[198:201], v[90:93]
	v_mfma_f32_16x16x32_bf16 v[82:85], v[166:169], v[216:219], v[82:85]
	v_mfma_f32_16x16x32_bf16 v[74:77], v[182:185], v[216:219], v[74:77]
	v_mfma_f32_16x16x32_bf16 v[70:73], v[166:169], v[224:227], v[70:73]
	v_mfma_f32_16x16x32_bf16 v[66:69], v[182:185], v[224:227], v[66:69]
	s_setprio 0
	s_barrier
	s_add_i32 s48, s48, s37
	v_lshl_add_u64 v[172:173], s[28:29], 0, v[0:1]
	s_mov_b32 m0, s48
	ds_read_b128 v[186:189], v144 offset:16384
	global_load_lds_dwordx4 v[172:173], off
	ds_read_b128 v[190:193], v144 offset:17408
	ds_read_b128 v[194:197], v144 offset:18432
	s_add_i32 m0, s48, 0x2000
	s_add_u32 s48, s28, 0x8000
	v_lshl_add_u64 v[174:175], s[28:29], 0, v[134:135]
	s_addc_u32 s49, s29, 0
	s_add_i32 s50, s50, s37
	global_load_lds_dwordx4 v[174:175], off
	ds_read_b128 v[198:201], v144 offset:19456
	ds_read_b128 v[212:215], v144 offset:20480
	v_lshl_add_u64 v[176:177], s[48:49], 0, v[0:1]
	s_mov_b32 m0, s50
	v_lshl_add_u64 v[228:229], s[30:31], 0, v[132:133]
	global_load_lds_dwordx4 v[176:177], off
	ds_read_b128 v[216:219], v144 offset:21504
	ds_read_b128 v[220:223], v144 offset:22528
	v_lshl_add_u64 v[176:177], s[48:49], 0, v[134:135]
	s_add_i32 m0, s50, 0x2000
	s_nop 0
	global_load_lds_dwordx4 v[176:177], off
	ds_read_b128 v[224:227], v144 offset:23552
	v_lshl_add_u64 v[176:177], s[30:31], 0, v[130:131]
	s_mov_b32 m0, s23
	s_nop 0
	global_load_lds_dwordx4 v[176:177], off
	s_mov_b32 m0, s25
	s_nop 0
	global_load_lds_dwordx4 v[228:229], off
	s_waitcnt vmcnt(8)
	s_waitcnt lgkmcnt(0)
	s_barrier
; #define PG8_STAGE(bufoff, gbase, voff) do { _Pragma("unroll") for (int _i = 0; _i < 2; ++_i) \
;         __builtin_amdgcn_global_load_lds((const unsigned*)((const char*)(gbase) + (voff)[_i]), (LAS unsigned*)(lds + (bufoff) + ldsw + _i * 8192), 16, 0, 0); } while (0)
; #define PG8_LDA(dst, b, h) do { _Pragma("unroll") for (int m = 0; m < 4; ++m) _Pragma("unroll") for (int k = 0; k < 2; ++k) dst[m][k] = *(const LAS bf16x8*)(lds + PG8_SA(b, h) + aoff + m * 2048 + k * 1024); } while (0)
; #define PG8_LDB(dst, b, h) do { _Pragma("unroll") for (int n = 0; n < 2; ++n) _Pragma("unroll") for (int k = 0; k < 2; ++k) dst[n][k] = *(const LAS bf16x8*)(lds + PG8_SB(b, h) + boff + n * 2048 + k * 1024); } while (0)
; #define PG8_MMA(ai, bj, At, Bt) do { __builtin_amdgcn_s_setprio(1); _Pragma("unroll") for (int m = 0; m < 4; ++m) _Pragma("unroll") for (int n = 0; n < 2; ++n) _Pragma("unroll") for (int k = 0; k < 2; ++k) \
;         acc[ai][bj][m][n] = __builtin_amdgcn_mfma_f32_16x16x32_bf16(Bt[n][k], At[m][k], acc[ai][bj][m][n], 0, 0, 0); __builtin_amdgcn_s_setprio(0); } while (0)
; #define PG8_WAIT_V(n) asm volatile("s_waitcnt vmcnt(" #n ")" ::: "memory")
; #define PG8_WAIT_L(n) asm volatile("s_waitcnt lgkmcnt(" #n ")" ::: "memory")
; #define PG8_BAR __builtin_amdgcn_s_barrier()
; #define PG8_SCHED __builtin_amdgcn_sched_barrier(0)
; template <class Epi>
; __device__ __forceinline__ void gemm_phase(LAS unsigned char* lds, const Gemm g, const StaticOrder& S, const Epi& E, const int tid) {
;     ...
;             PG8_WAIT_V(8); PG8_WAIT_L(0); PG8_BAR; PG8_MMA(1, 0, At, B0); PG8_MMA(1, 1, At, B1); PG8_BAR; PG8_SCHED;
;             PG8_LDB(B0, 1, 0); PG8_LDB(B1, 1, 1); PG8_SCHED; PG8_LDA(At, 1, 0); PG8_STAGE(PG8_SA(0, 1), a2 + hstep, voffA);
;             PG8_WAIT_V(8); PG8_WAIT_L(0); PG8_BAR; PG8_MMA(0, 0, At, B0); PG8_MMA(0, 1, At, B1); PG8_BAR; PG8_SCHED;
	s_setprio 1
	s_waitcnt lgkmcnt(0)
	v_mfma_f32_16x16x32_bf16 v[62:65], v[146:149], v[186:189], v[62:65]
	v_mfma_f32_16x16x32_bf16 v[58:61], v[154:157], v[186:189], v[58:61]
	v_mfma_f32_16x16x32_bf16 v[54:57], v[146:149], v[194:197], v[54:57]
	v_mfma_f32_16x16x32_bf16 v[46:49], v[154:157], v[194:197], v[46:49]
	v_mfma_f32_16x16x32_bf16 v[38:41], v[146:149], v[212:215], v[38:41]
	v_mfma_f32_16x16x32_bf16 v[30:33], v[154:157], v[212:215], v[30:33]
	v_mfma_f32_16x16x32_bf16 v[22:25], v[146:149], v[220:223], v[22:25]
	v_mfma_f32_16x16x32_bf16 v[14:17], v[154:157], v[220:223], v[14:17]
	v_mfma_f32_16x16x32_bf16 v[62:65], v[150:153], v[190:193], v[62:65]
	v_mfma_f32_16x16x32_bf16 v[58:61], v[158:161], v[190:193], v[58:61]
	v_mfma_f32_16x16x32_bf16 v[54:57], v[150:153], v[198:201], v[54:57]
	v_mfma_f32_16x16x32_bf16 v[46:49], v[158:161], v[198:201], v[46:49]
	v_mfma_f32_16x16x32_bf16 v[38:41], v[150:153], v[216:219], v[38:41]
	v_mfma_f32_16x16x32_bf16 v[30:33], v[158:161], v[216:219], v[30:33]
	v_mfma_f32_16x16x32_bf16 v[22:25], v[150:153], v[224:227], v[22:25]
	v_mfma_f32_16x16x32_bf16 v[14:17], v[158:161], v[224:227], v[14:17]
	s_setprio 0
	s_setprio 1
	v_mfma_f32_16x16x32_bf16 v[50:53], v[162:165], v[186:189], v[50:53]
	v_mfma_f32_16x16x32_bf16 v[42:45], v[178:181], v[186:189], v[42:45]
	v_mfma_f32_16x16x32_bf16 v[34:37], v[162:165], v[194:197], v[34:37]
	v_mfma_f32_16x16x32_bf16 v[26:29], v[178:181], v[194:197], v[26:29]
	v_mfma_f32_16x16x32_bf16 v[18:21], v[162:165], v[212:215], v[18:21]
	v_mfma_f32_16x16x32_bf16 v[10:13], v[178:181], v[212:215], v[10:13]
	v_mfma_f32_16x16x32_bf16 v[6:9], v[162:165], v[220:223], v[6:9]
	v_mfma_f32_16x16x32_bf16 v[2:5], v[178:181], v[220:223], v[2:5]
	v_mfma_f32_16x16x32_bf16 v[50:53], v[166:169], v[190:193], v[50:53]
	v_mfma_f32_16x16x32_bf16 v[42:45], v[182:185], v[190:193], v[42:45]
	v_mfma_f32_16x16x32_bf16 v[34:37], v[166:169], v[198:201], v[34:37]
	v_mfma_f32_16x16x32_bf16 v[26:29], v[182:185], v[198:201], v[26:29]
	v_mfma_f32_16x16x32_bf16 v[18:21], v[166:169], v[216:219], v[18:21]
	v_mfma_f32_16x16x32_bf16 v[10:13], v[182:185], v[216:219], v[10:13]
	v_mfma_f32_16x16x32_bf16 v[6:9], v[166:169], v[224:227], v[6:9]
	v_mfma_f32_16x16x32_bf16 v[2:5], v[182:185], v[224:227], v[2:5]
	s_setprio 0
	s_barrier
	s_add_i32 s48, 0, 0x18000
	v_add_u32_e32 v145, s48, v142
	s_add_i32 s49, 0, 0x1c000
	ds_read_b128 v[146:149], v145
	ds_read_b128 v[150:153], v145 offset:1024
	ds_read_b128 v[154:157], v145 offset:2048
	ds_read_b128 v[158:161], v145 offset:3072
	v_add_u32_e32 v145, s49, v142
	ds_read_b128 v[162:165], v145
	ds_read_b128 v[166:169], v145 offset:1024
	ds_read_b128 v[178:181], v145 offset:2048
	ds_read_b128 v[182:185], v145 offset:3072
	s_add_u32 s30, s30, 0x80000
	s_addc_u32 s31, s31, 0
	s_mov_b32 m0, s38
	v_lshl_add_u64 v[230:231], s[30:31], 0, v[130:131]
	ds_read_b128 v[186:189], v144 offset:32768
	global_load_lds_dwordx4 v[230:231], off
	ds_read_b128 v[190:193], v144 offset:33792
	ds_read_b128 v[194:197], v144 offset:34816
	v_lshl_add_u64 v[230:231], s[30:31], 0, v[132:133]
	s_mov_b32 m0, s39
	s_nop 0
	global_load_lds_dwordx4 v[230:231], off
	ds_read_b128 v[198:201], v144 offset:35840
	ds_read_b128 v[212:215], v144 offset:36864
	ds_read_b128 v[216:219], v144 offset:37888
	ds_read_b128 v[220:223], v144 offset:38912
	ds_read_b128 v[224:227], v144 offset:39936
	s_waitcnt vmcnt(8)
	s_waitcnt lgkmcnt(0)
	s_barrier
	s_setprio 1
	s_waitcnt lgkmcnt(0)
	v_mfma_f32_16x16x32_bf16 v[126:129], v[146:149], v[186:189], v[126:129]
	v_mfma_f32_16x16x32_bf16 v[122:125], v[154:157], v[186:189], v[122:125]
	v_mfma_f32_16x16x32_bf16 v[118:121], v[146:149], v[194:197], v[118:121]
	v_mfma_f32_16x16x32_bf16 v[110:113], v[154:157], v[194:197], v[110:113]
	v_mfma_f32_16x16x32_bf16 v[102:105], v[146:149], v[212:215], v[102:105]
	v_mfma_f32_16x16x32_bf16 v[94:97], v[154:157], v[212:215], v[94:97]
	v_mfma_f32_16x16x32_bf16 v[86:89], v[146:149], v[220:223], v[86:89]
	v_mfma_f32_16x16x32_bf16 v[78:81], v[154:157], v[220:223], v[78:81]
	v_mfma_f32_16x16x32_bf16 v[126:129], v[150:153], v[190:193], v[126:129]
	v_mfma_f32_16x16x32_bf16 v[122:125], v[158:161], v[190:193], v[122:125]
	v_mfma_f32_16x16x32_bf16 v[118:121], v[150:153], v[198:201], v[118:121]
	v_mfma_f32_16x16x32_bf16 v[110:113], v[158:161], v[198:201], v[110:113]
	v_mfma_f32_16x16x32_bf16 v[102:105], v[150:153], v[216:219], v[102:105]
	v_mfma_f32_16x16x32_bf16 v[94:97], v[158:161], v[216:219], v[94:97]
	v_mfma_f32_16x16x32_bf16 v[86:89], v[150:153], v[224:227], v[86:89]
	v_mfma_f32_16x16x32_bf16 v[78:81], v[158:161], v[224:227], v[78:81]
	s_setprio 0
	s_setprio 1
	v_mfma_f32_16x16x32_bf16 v[114:117], v[162:165], v[186:189], v[114:117]
	v_mfma_f32_16x16x32_bf16 v[106:109], v[178:181], v[186:189], v[106:109]
	v_mfma_f32_16x16x32_bf16 v[98:101], v[162:165], v[194:197], v[98:101]
	v_mfma_f32_16x16x32_bf16 v[90:93], v[178:181], v[194:197], v[90:93]
	v_mfma_f32_16x16x32_bf16 v[82:85], v[162:165], v[212:215], v[82:85]
	v_mfma_f32_16x16x32_bf16 v[74:77], v[178:181], v[212:215], v[74:77]
	v_mfma_f32_16x16x32_bf16 v[70:73], v[162:165], v[220:223], v[70:73]
	v_mfma_f32_16x16x32_bf16 v[66:69], v[178:181], v[220:223], v[66:69]
	v_mfma_f32_16x16x32_bf16 v[114:117], v[166:169], v[190:193], v[114:117]
	v_mfma_f32_16x16x32_bf16 v[106:109], v[182:185], v[190:193], v[106:109]
	v_mfma_f32_16x16x32_bf16 v[98:101], v[166:169], v[198:201], v[98:101]
	v_mfma_f32_16x16x32_bf16 v[90:93], v[182:185], v[198:201], v[90:93]
	v_mfma_f32_16x16x32_bf16 v[82:85], v[166:169], v[216:219], v[82:85]
	v_mfma_f32_16x16x32_bf16 v[74:77], v[182:185], v[216:219], v[74:77]
	v_mfma_f32_16x16x32_bf16 v[70:73], v[166:169], v[224:227], v[70:73]
	v_mfma_f32_16x16x32_bf16 v[66:69], v[182:185], v[224:227], v[66:69]
	s_setprio 0
	s_barrier
; #define PG8_STAGE(bufoff, gbase, voff) do { _Pragma("unroll") for (int _i = 0; _i < 2; ++_i) \
;         __builtin_amdgcn_global_load_lds((const unsigned*)((const char*)(gbase) + (voff)[_i]), (LAS unsigned*)(lds + (bufoff) + ldsw + _i * 8192), 16, 0, 0); } while (0)
; #define PG8_LDA(dst, b, h) do { _Pragma("unroll") for (int m = 0; m < 4; ++m) _Pragma("unroll") for (int k = 0; k < 2; ++k) dst[m][k] = *(const LAS bf16x8*)(lds + PG8_SA(b, h) + aoff + m * 2048 + k * 1024); } while (0)
; #define PG8_MMA(ai, bj, At, Bt) do { __builtin_amdgcn_s_setprio(1); _Pragma("unroll") for (int m = 0; m < 4; ++m) _Pragma("unroll") for (int n = 0; n < 2; ++n) _Pragma("unroll") for (int k = 0; k < 2; ++k) \
;         acc[ai][bj][m][n] = __builtin_amdgcn_mfma_f32_16x16x32_bf16(Bt[n][k], At[m][k], acc[ai][bj][m][n], 0, 0, 0); __builtin_amdgcn_s_setprio(0); } while (0)
; #define PG8_WAIT_V(n) asm volatile("s_waitcnt vmcnt(" #n ")" ::: "memory")
; #define PG8_WAIT_L(n) asm volatile("s_waitcnt lgkmcnt(" #n ")" ::: "memory")
; #define PG8_BAR __builtin_amdgcn_s_barrier()
; #define PG8_SCHED __builtin_amdgcn_sched_barrier(0)
; template <class Epi>
; __device__ __forceinline__ void gemm_phase(LAS unsigned char* lds, const Gemm g, const StaticOrder& S, const Epi& E, const int tid) {
;     ...
;             PG8_LDA(At, 1, 1); PG8_STAGE(PG8_SB(1, 0), b3, voffB); PG8_STAGE(PG8_SB(1, 1), b3 + bhs, voffB); PG8_STAGE(PG8_SA(1, 0), a3, voffA);
;             PG8_WAIT_V(8); PG8_WAIT_L(0); PG8_BAR; PG8_MMA(1, 0, At, B0); PG8_MMA(1, 1, At, B1); PG8_BAR; PG8_SCHED;
;     ...
;         if (ALIGN_EPI) { if (wr == 0) PG8_BAR; }
	s_add_i32 s30, s48, s37
	v_lshl_add_u64 v[172:173], v[172:173], 0, s[70:71]
	s_mov_b32 m0, s30
	ds_read_b128 v[186:189], v144 offset:49152
	global_load_lds_dwordx4 v[172:173], off
	ds_read_b128 v[190:193], v144 offset:50176
	ds_read_b128 v[194:197], v144 offset:51200
	s_add_i32 m0, s30, 0x2000
	s_add_u32 s28, s28, 0x8080
	v_lshl_add_u64 v[172:173], v[174:175], 0, s[70:71]
	s_addc_u32 s29, s29, 0
	s_add_i32 s30, s49, s37
	global_load_lds_dwordx4 v[172:173], off
	ds_read_b128 v[198:201], v144 offset:52224
	ds_read_b128 v[212:215], v144 offset:53248
	v_lshl_add_u64 v[172:173], s[28:29], 0, v[0:1]
	s_mov_b32 m0, s30
	s_nop 0
	global_load_lds_dwordx4 v[172:173], off
	ds_read_b128 v[216:219], v144 offset:54272
	ds_read_b128 v[220:223], v144 offset:55296
	v_lshl_add_u64 v[172:173], s[28:29], 0, v[134:135]
	s_add_i32 m0, s30, 0x2000
	s_nop 0
	global_load_lds_dwordx4 v[172:173], off
	ds_read_b128 v[224:227], v144 offset:56320
	v_lshl_add_u64 v[172:173], v[176:177], 0, s[70:71]
	s_mov_b32 m0, s40
	s_nop 0
	global_load_lds_dwordx4 v[172:173], off
	v_lshl_add_u64 v[172:173], v[228:229], 0, s[70:71]
	s_mov_b32 m0, s41
	s_nop 0
	global_load_lds_dwordx4 v[172:173], off
	s_waitcnt vmcnt(8)
	s_waitcnt lgkmcnt(0)
	s_barrier
	s_setprio 1
	s_waitcnt lgkmcnt(0)
	v_mfma_f32_16x16x32_bf16 v[62:65], v[146:149], v[186:189], v[62:65]
	v_mfma_f32_16x16x32_bf16 v[58:61], v[154:157], v[186:189], v[58:61]
	v_mfma_f32_16x16x32_bf16 v[54:57], v[146:149], v[194:197], v[54:57]
	v_mfma_f32_16x16x32_bf16 v[46:49], v[154:157], v[194:197], v[46:49]
	v_mfma_f32_16x16x32_bf16 v[38:41], v[146:149], v[212:215], v[38:41]
	v_mfma_f32_16x16x32_bf16 v[30:33], v[154:157], v[212:215], v[30:33]
	v_mfma_f32_16x16x32_bf16 v[22:25], v[146:149], v[220:223], v[22:25]
	v_mfma_f32_16x16x32_bf16 v[14:17], v[154:157], v[220:223], v[14:17]
	v_mfma_f32_16x16x32_bf16 v[62:65], v[150:153], v[190:193], v[62:65]
	v_mfma_f32_16x16x32_bf16 v[58:61], v[158:161], v[190:193], v[58:61]
	v_mfma_f32_16x16x32_bf16 v[54:57], v[150:153], v[198:201], v[54:57]
	v_mfma_f32_16x16x32_bf16 v[46:49], v[158:161], v[198:201], v[46:49]
	v_mfma_f32_16x16x32_bf16 v[38:41], v[150:153], v[216:219], v[38:41]
	v_mfma_f32_16x16x32_bf16 v[30:33], v[158:161], v[216:219], v[30:33]
	v_mfma_f32_16x16x32_bf16 v[22:25], v[150:153], v[224:227], v[22:25]
	v_mfma_f32_16x16x32_bf16 v[14:17], v[158:161], v[224:227], v[14:17]
	s_setprio 0
	s_setprio 1
	v_mfma_f32_16x16x32_bf16 v[50:53], v[162:165], v[186:189], v[50:53]
	v_mfma_f32_16x16x32_bf16 v[42:45], v[178:181], v[186:189], v[42:45]
	v_mfma_f32_16x16x32_bf16 v[34:37], v[162:165], v[194:197], v[34:37]
	v_mfma_f32_16x16x32_bf16 v[26:29], v[178:181], v[194:197], v[26:29]
	v_mfma_f32_16x16x32_bf16 v[18:21], v[162:165], v[212:215], v[18:21]
	v_mfma_f32_16x16x32_bf16 v[10:13], v[178:181], v[212:215], v[10:13]
	v_mfma_f32_16x16x32_bf16 v[6:9], v[162:165], v[220:223], v[6:9]
	v_mfma_f32_16x16x32_bf16 v[2:5], v[178:181], v[220:223], v[2:5]
	v_mfma_f32_16x16x32_bf16 v[50:53], v[166:169], v[190:193], v[50:53]
	v_mfma_f32_16x16x32_bf16 v[42:45], v[182:185], v[190:193], v[42:45]
	v_mfma_f32_16x16x32_bf16 v[34:37], v[166:169], v[198:201], v[34:37]
	v_mfma_f32_16x16x32_bf16 v[26:29], v[182:185], v[198:201], v[26:29]
	v_mfma_f32_16x16x32_bf16 v[18:21], v[166:169], v[216:219], v[18:21]
	v_mfma_f32_16x16x32_bf16 v[10:13], v[182:185], v[216:219], v[10:13]
	v_mfma_f32_16x16x32_bf16 v[6:9], v[166:169], v[224:227], v[6:9]
	v_mfma_f32_16x16x32_bf16 v[2:5], v[182:185], v[224:227], v[2:5]
	s_setprio 0
	s_barrier
	s_add_i32 s47, s47, 2
	s_add_u32 s45, s45, 0x100
	s_addc_u32 s46, s46, 0
	s_add_u32 s26, s26, 0x100
	s_addc_u32 s27, s27, 0
	s_cmp_gt_u32 s47, 29
	s_cbranch_scc0 .LBB0_844
	s_and_b64 vcc, exec, s[10:11]
	s_cbranch_vccz .LBB0_847
	s_barrier

; #define PG8_STAGE(bufoff, gbase, voff) do { _Pragma("unroll") for (int _i = 0; _i < 2; ++_i) \
;         __builtin_amdgcn_global_load_lds((const unsigned*)((const char*)(gbase) + (voff)[_i]), (LAS unsigned*)(lds + (bufoff) + ldsw + _i * 8192), 16, 0, 0); } while (0)
; #define PG8_LDA(dst, b, h) do { _Pragma("unroll") for (int m = 0; m < 4; ++m) _Pragma("unroll") for (int k = 0; k < 2; ++k) dst[m][k] = *(const LAS bf16x8*)(lds + PG8_SA(b, h) + aoff + m * 2048 + k * 1024); } while (0)
; #define PG8_LDB(dst, b, h) do { _Pragma("unroll") for (int n = 0; n < 2; ++n) _Pragma("unroll") for (int k = 0; k < 2; ++k) dst[n][k] = *(const LAS bf16x8*)(lds + PG8_SB(b, h) + boff + n * 2048 + k * 1024); } while (0)
; #define PG8_MMA(ai, bj, At, Bt) do { __builtin_amdgcn_s_setprio(1); _Pragma("unroll") for (int m = 0; m < 4; ++m) _Pragma("unroll") for (int n = 0; n < 2; ++n) _Pragma("unroll") for (int k = 0; k < 2; ++k) \
;         acc[ai][bj][m][n] = __builtin_amdgcn_mfma_f32_16x16x32_bf16(Bt[n][k], At[m][k], acc[ai][bj][m][n], 0, 0, 0); __builtin_amdgcn_s_setprio(0); } while (0)
; #define PG8_WAIT_V(n) asm volatile("s_waitcnt vmcnt(" #n ")" ::: "memory")
; #define PG8_WAIT_L(n) asm volatile("s_waitcnt lgkmcnt(" #n ")" ::: "memory")
; #define PG8_BAR __builtin_amdgcn_s_barrier()
; template <class Epi>
; __device__ __forceinline__ void gemm_phase(LAS unsigned char* lds, const Gemm g, const StaticOrder& S, const Epi& E, const int tid) {
;     ...
;             const char* a2 = last ? nA : (s2 ? cA2 + (size_t)(t + 2 - nt) * kstep : cA + (size_t)(t + 2) * kstep);
;             const char* b2 = last ? nB : (s2 ? cB2 + (size_t)(t + 2 - nt) * kstep : cB + (size_t)(t + 2) * kstep);
;             const char* a3 = a2 + kstep; const char* b3 = b2 + kstep;
;             if constexpr (Epi::TWO) { if (t == nt) E.mid(acc, cur, wr, wc, fr, fq); }
;             if constexpr (SP2) {
;             PG8_LDB(B0, 0, 0); PG8_LDB(B1, 0, 1); PG8_SCHED; PG8_LDA(At, 0, 0); PG8_STAGE(PG8_SA(1, 1), a1 + hstep, voffA);
;             PG8_WAIT_V(8); PG8_WAIT_L(0); PG8_BAR; PG8_MMA(0, 0, At, B0); PG8_MMA(0, 1, At, B1); PG8_BAR; PG8_SCHED;
;             PG8_LDA(At, 0, 1); PG8_STAGE(PG8_SB(0, 0), b2, voffB); PG8_STAGE(PG8_SB(0, 1), b2 + bhs, voffB); PG8_STAGE(PG8_SA(0, 0), a2, voffA);
;             PG8_WAIT_V(8); PG8_WAIT_L(0); PG8_BAR; PG8_MMA(1, 0, At, B0); PG8_MMA(1, 1, At, B1); PG8_BAR; PG8_SCHED;
.LBB0_861:
	s_add_u32 s30, s28, 0xfff80080
	s_addc_u32 s31, s29, -1
	s_add_i32 s51, 0, 0x10000
	s_cmp_eq_u32 s50, 28
	s_cselect_b32 s35, s17, s31
	s_cselect_b32 s34, s46, s30
	v_add_u32_e32 v145, s51, v142
	s_cselect_b32 s31, s15, s49
	s_cselect_b32 s30, s47, s48
	s_add_i32 s54, 0, 0x14000
	ds_read_b128 v[146:149], v145
	ds_read_b128 v[150:153], v145 offset:1024
	ds_read_b128 v[154:157], v145 offset:2048
	ds_read_b128 v[158:161], v145 offset:3072
	v_add_u32_e32 v145, s54, v142
	ds_read_b128 v[162:165], v145
	ds_read_b128 v[166:169], v145 offset:1024
	ds_read_b128 v[178:181], v145 offset:2048
	ds_read_b128 v[182:185], v145 offset:3072
	v_lshl_add_u64 v[172:173], s[28:29], 0, v[138:139]
	s_add_i32 m0, s25, 0xc000
	ds_read_b128 v[186:189], v144
	global_load_lds_dwordx4 v[172:173], off
	ds_read_b128 v[190:193], v144 offset:1024
	ds_read_b128 v[194:197], v144 offset:2048
	v_lshl_add_u64 v[172:173], s[28:29], 0, v[136:137]
	s_add_i32 m0, s25, 0xe000
	s_nop 0
	global_load_lds_dwordx4 v[172:173], off
	ds_read_b128 v[198:201], v144 offset:3072
	ds_read_b128 v[212:215], v144 offset:4096
	ds_read_b128 v[216:219], v144 offset:5120
	ds_read_b128 v[220:223], v144 offset:6144
	ds_read_b128 v[224:227], v144 offset:7168
	s_waitcnt vmcnt(8)
	s_waitcnt lgkmcnt(0)
	s_barrier
	s_setprio 1
	s_waitcnt lgkmcnt(0)
	v_mfma_f32_16x16x32_bf16 v[126:129], v[146:149], v[186:189], v[126:129]
	v_mfma_f32_16x16x32_bf16 v[122:125], v[154:157], v[186:189], v[122:125]
	v_mfma_f32_16x16x32_bf16 v[118:121], v[146:149], v[194:197], v[118:121]
	v_mfma_f32_16x16x32_bf16 v[110:113], v[154:157], v[194:197], v[110:113]
	v_mfma_f32_16x16x32_bf16 v[102:105], v[146:149], v[212:215], v[102:105]
	v_mfma_f32_16x16x32_bf16 v[94:97], v[154:157], v[212:215], v[94:97]
	v_mfma_f32_16x16x32_bf16 v[86:89], v[146:149], v[220:223], v[86:89]
	v_mfma_f32_16x16x32_bf16 v[78:81], v[154:157], v[220:223], v[78:81]
	v_mfma_f32_16x16x32_bf16 v[126:129], v[150:153], v[190:193], v[126:129]
	v_mfma_f32_16x16x32_bf16 v[122:125], v[158:161], v[190:193], v[122:125]
	v_mfma_f32_16x16x32_bf16 v[118:121], v[150:153], v[198:201], v[118:121]
	v_mfma_f32_16x16x32_bf16 v[110:113], v[158:161], v[198:201], v[110:113]
	v_mfma_f32_16x16x32_bf16 v[102:105], v[150:153], v[216:219], v[102:105]
	v_mfma_f32_16x16x32_bf16 v[94:97], v[158:161], v[216:219], v[94:97]
	v_mfma_f32_16x16x32_bf16 v[86:89], v[150:153], v[224:227], v[86:89]
	v_mfma_f32_16x16x32_bf16 v[78:81], v[158:161], v[224:227], v[78:81]
	s_setprio 0
	s_setprio 1
	v_mfma_f32_16x16x32_bf16 v[114:117], v[162:165], v[186:189], v[114:117]
	v_mfma_f32_16x16x32_bf16 v[106:109], v[178:181], v[186:189], v[106:109]
	v_mfma_f32_16x16x32_bf16 v[98:101], v[162:165], v[194:197], v[98:101]
	v_mfma_f32_16x16x32_bf16 v[90:93], v[178:181], v[194:197], v[90:93]
	v_mfma_f32_16x16x32_bf16 v[82:85], v[162:165], v[212:215], v[82:85]
	v_mfma_f32_16x16x32_bf16 v[74:77], v[178:181], v[212:215], v[74:77]
	v_mfma_f32_16x16x32_bf16 v[70:73], v[162:165], v[220:223], v[70:73]
	v_mfma_f32_16x16x32_bf16 v[66:69], v[178:181], v[220:223], v[66:69]
	v_mfma_f32_16x16x32_bf16 v[114:117], v[166:169], v[190:193], v[114:117]
	v_mfma_f32_16x16x32_bf16 v[106:109], v[182:185], v[190:193], v[106:109]
	v_mfma_f32_16x16x32_bf16 v[98:101], v[166:169], v[198:201], v[98:101]
	v_mfma_f32_16x16x32_bf16 v[90:93], v[182:185], v[198:201], v[90:93]
	v_mfma_f32_16x16x32_bf16 v[82:85], v[166:169], v[216:219], v[82:85]
	v_mfma_f32_16x16x32_bf16 v[74:77], v[182:185], v[216:219], v[74:77]
	v_mfma_f32_16x16x32_bf16 v[70:73], v[166:169], v[224:227], v[70:73]
	v_mfma_f32_16x16x32_bf16 v[66:69], v[182:185], v[224:227], v[66:69]
	s_setprio 0
	s_barrier
	s_add_i32 s51, s51, s40
	v_lshl_add_u64 v[172:173], s[30:31], 0, v[0:1]
	s_mov_b32 m0, s51
	ds_read_b128 v[186:189], v144 offset:16384
	global_load_lds_dwordx4 v[172:173], off
	ds_read_b128 v[190:193], v144 offset:17408
	ds_read_b128 v[194:197], v144 offset:18432
	s_add_i32 m0, s51, 0x2000
	s_add_u32 s52, s30, 0x8000
	v_lshl_add_u64 v[174:175], s[30:31], 0, v[134:135]
	s_addc_u32 s53, s31, 0
	s_add_i32 s51, s54, s40
	global_load_lds_dwordx4 v[174:175], off
	ds_read_b128 v[198:201], v144 offset:19456
	ds_read_b128 v[212:215], v144 offset:20480
	v_lshl_add_u64 v[176:177], s[52:53], 0, v[0:1]
	s_mov_b32 m0, s51
	v_lshl_add_u64 v[228:229], s[34:35], 0, v[132:133]
	global_load_lds_dwordx4 v[176:177], off
	ds_read_b128 v[216:219], v144 offset:21504
	ds_read_b128 v[220:223], v144 offset:22528
	v_lshl_add_u64 v[176:177], s[52:53], 0, v[134:135]
	s_add_i32 m0, s51, 0x2000
	s_nop 0
	global_load_lds_dwordx4 v[176:177], off
	ds_read_b128 v[224:227], v144 offset:23552
	v_lshl_add_u64 v[176:177], s[34:35], 0, v[130:131]
	s_mov_b32 m0, s25
	s_nop 0
	global_load_lds_dwordx4 v[176:177], off
	s_mov_b32 m0, s27
	s_nop 0
	global_load_lds_dwordx4 v[228:229], off
	s_waitcnt vmcnt(8)
	s_waitcnt lgkmcnt(0)
	s_barrier
; #define PG8_STAGE(bufoff, gbase, voff) do { _Pragma("unroll") for (int _i = 0; _i < 2; ++_i) \
;         __builtin_amdgcn_global_load_lds((const unsigned*)((const char*)(gbase) + (voff)[_i]), (LAS unsigned*)(lds + (bufoff) + ldsw + _i * 8192), 16, 0, 0); } while (0)
; #define PG8_LDA(dst, b, h) do { _Pragma("unroll") for (int m = 0; m < 4; ++m) _Pragma("unroll") for (int k = 0; k < 2; ++k) dst[m][k] = *(const LAS bf16x8*)(lds + PG8_SA(b, h) + aoff + m * 2048 + k * 1024); } while (0)
; #define PG8_LDB(dst, b, h) do { _Pragma("unroll") for (int n = 0; n < 2; ++n) _Pragma("unroll") for (int k = 0; k < 2; ++k) dst[n][k] = *(const LAS bf16x8*)(lds + PG8_SB(b, h) + boff + n * 2048 + k * 1024); } while (0)
; #define PG8_MMA(ai, bj, At, Bt) do { __builtin_amdgcn_s_setprio(1); _Pragma("unroll") for (int m = 0; m < 4; ++m) _Pragma("unroll") for (int n = 0; n < 2; ++n) _Pragma("unroll") for (int k = 0; k < 2; ++k) \
;         acc[ai][bj][m][n] = __builtin_amdgcn_mfma_f32_16x16x32_bf16(Bt[n][k], At[m][k], acc[ai][bj][m][n], 0, 0, 0); __builtin_amdgcn_s_setprio(0); } while (0)
; #define PG8_WAIT_V(n) asm volatile("s_waitcnt vmcnt(" #n ")" ::: "memory")
; #define PG8_WAIT_L(n) asm volatile("s_waitcnt lgkmcnt(" #n ")" ::: "memory")
; #define PG8_BAR __builtin_amdgcn_s_barrier()
; #define PG8_SCHED __builtin_amdgcn_sched_barrier(0)
; template <class Epi>
; __device__ __forceinline__ void gemm_phase(LAS unsigned char* lds, const Gemm g, const StaticOrder& S, const Epi& E, const int tid) {
;     ...
;             PG8_WAIT_V(8); PG8_WAIT_L(0); PG8_BAR; PG8_MMA(1, 0, At, B0); PG8_MMA(1, 1, At, B1); PG8_BAR; PG8_SCHED;
;             PG8_LDB(B0, 1, 0); PG8_LDB(B1, 1, 1); PG8_SCHED; PG8_LDA(At, 1, 0); PG8_STAGE(PG8_SA(0, 1), a2 + hstep, voffA);
;             PG8_WAIT_V(8); PG8_WAIT_L(0); PG8_BAR; PG8_MMA(0, 0, At, B0); PG8_MMA(0, 1, At, B1); PG8_BAR; PG8_SCHED;
	s_setprio 1
	s_waitcnt lgkmcnt(0)
	v_mfma_f32_16x16x32_bf16 v[62:65], v[146:149], v[186:189], v[62:65]
	v_mfma_f32_16x16x32_bf16 v[58:61], v[154:157], v[186:189], v[58:61]
	v_mfma_f32_16x16x32_bf16 v[54:57], v[146:149], v[194:197], v[54:57]
	v_mfma_f32_16x16x32_bf16 v[46:49], v[154:157], v[194:197], v[46:49]
	v_mfma_f32_16x16x32_bf16 v[38:41], v[146:149], v[212:215], v[38:41]
	v_mfma_f32_16x16x32_bf16 v[30:33], v[154:157], v[212:215], v[30:33]
	v_mfma_f32_16x16x32_bf16 v[22:25], v[146:149], v[220:223], v[22:25]
	v_mfma_f32_16x16x32_bf16 v[14:17], v[154:157], v[220:223], v[14:17]
	v_mfma_f32_16x16x32_bf16 v[62:65], v[150:153], v[190:193], v[62:65]
	v_mfma_f32_16x16x32_bf16 v[58:61], v[158:161], v[190:193], v[58:61]
	v_mfma_f32_16x16x32_bf16 v[54:57], v[150:153], v[198:201], v[54:57]
	v_mfma_f32_16x16x32_bf16 v[46:49], v[158:161], v[198:201], v[46:49]
	v_mfma_f32_16x16x32_bf16 v[38:41], v[150:153], v[216:219], v[38:41]
	v_mfma_f32_16x16x32_bf16 v[30:33], v[158:161], v[216:219], v[30:33]
	v_mfma_f32_16x16x32_bf16 v[22:25], v[150:153], v[224:227], v[22:25]
	v_mfma_f32_16x16x32_bf16 v[14:17], v[158:161], v[224:227], v[14:17]
	s_setprio 0
	s_setprio 1
	v_mfma_f32_16x16x32_bf16 v[50:53], v[162:165], v[186:189], v[50:53]
	v_mfma_f32_16x16x32_bf16 v[42:45], v[178:181], v[186:189], v[42:45]
	v_mfma_f32_16x16x32_bf16 v[34:37], v[162:165], v[194:197], v[34:37]
	v_mfma_f32_16x16x32_bf16 v[26:29], v[178:181], v[194:197], v[26:29]
	v_mfma_f32_16x16x32_bf16 v[18:21], v[162:165], v[212:215], v[18:21]
	v_mfma_f32_16x16x32_bf16 v[10:13], v[178:181], v[212:215], v[10:13]
	v_mfma_f32_16x16x32_bf16 v[6:9], v[162:165], v[220:223], v[6:9]
	v_mfma_f32_16x16x32_bf16 v[2:5], v[178:181], v[220:223], v[2:5]
	v_mfma_f32_16x16x32_bf16 v[50:53], v[166:169], v[190:193], v[50:53]
	v_mfma_f32_16x16x32_bf16 v[42:45], v[182:185], v[190:193], v[42:45]
	v_mfma_f32_16x16x32_bf16 v[34:37], v[166:169], v[198:201], v[34:37]
	v_mfma_f32_16x16x32_bf16 v[26:29], v[182:185], v[198:201], v[26:29]
	v_mfma_f32_16x16x32_bf16 v[18:21], v[166:169], v[216:219], v[18:21]
	v_mfma_f32_16x16x32_bf16 v[10:13], v[182:185], v[216:219], v[10:13]
	v_mfma_f32_16x16x32_bf16 v[6:9], v[166:169], v[224:227], v[6:9]
	v_mfma_f32_16x16x32_bf16 v[2:5], v[182:185], v[224:227], v[2:5]
	s_setprio 0
	s_barrier
	s_add_i32 s51, 0, 0x18000
	v_add_u32_e32 v145, s51, v142
	s_add_i32 s52, 0, 0x1c000
	ds_read_b128 v[146:149], v145
	ds_read_b128 v[150:153], v145 offset:1024
	ds_read_b128 v[154:157], v145 offset:2048
	ds_read_b128 v[158:161], v145 offset:3072
	v_add_u32_e32 v145, s52, v142
	ds_read_b128 v[162:165], v145
	ds_read_b128 v[166:169], v145 offset:1024
	ds_read_b128 v[178:181], v145 offset:2048
	ds_read_b128 v[182:185], v145 offset:3072
	s_add_u32 s34, s34, 0x80000
	s_addc_u32 s35, s35, 0
	s_mov_b32 m0, s41
	v_lshl_add_u64 v[230:231], s[34:35], 0, v[130:131]
	ds_read_b128 v[186:189], v144 offset:32768
	global_load_lds_dwordx4 v[230:231], off
	ds_read_b128 v[190:193], v144 offset:33792
	ds_read_b128 v[194:197], v144 offset:34816
	v_lshl_add_u64 v[230:231], s[34:35], 0, v[132:133]
	s_mov_b32 m0, s42
	s_nop 0
	global_load_lds_dwordx4 v[230:231], off
	ds_read_b128 v[198:201], v144 offset:35840
	ds_read_b128 v[212:215], v144 offset:36864
	ds_read_b128 v[216:219], v144 offset:37888
	ds_read_b128 v[220:223], v144 offset:38912
	ds_read_b128 v[224:227], v144 offset:39936
	s_waitcnt vmcnt(8)
	s_waitcnt lgkmcnt(0)
	s_barrier
	s_setprio 1
	s_waitcnt lgkmcnt(0)
	v_mfma_f32_16x16x32_bf16 v[126:129], v[146:149], v[186:189], v[126:129]
	v_mfma_f32_16x16x32_bf16 v[122:125], v[154:157], v[186:189], v[122:125]
	v_mfma_f32_16x16x32_bf16 v[118:121], v[146:149], v[194:197], v[118:121]
	v_mfma_f32_16x16x32_bf16 v[110:113], v[154:157], v[194:197], v[110:113]
	v_mfma_f32_16x16x32_bf16 v[102:105], v[146:149], v[212:215], v[102:105]
	v_mfma_f32_16x16x32_bf16 v[94:97], v[154:157], v[212:215], v[94:97]
	v_mfma_f32_16x16x32_bf16 v[86:89], v[146:149], v[220:223], v[86:89]
	v_mfma_f32_16x16x32_bf16 v[78:81], v[154:157], v[220:223], v[78:81]
	v_mfma_f32_16x16x32_bf16 v[126:129], v[150:153], v[190:193], v[126:129]
	v_mfma_f32_16x16x32_bf16 v[122:125], v[158:161], v[190:193], v[122:125]
	v_mfma_f32_16x16x32_bf16 v[118:121], v[150:153], v[198:201], v[118:121]
	v_mfma_f32_16x16x32_bf16 v[110:113], v[158:161], v[198:201], v[110:113]
	v_mfma_f32_16x16x32_bf16 v[102:105], v[150:153], v[216:219], v[102:105]
	v_mfma_f32_16x16x32_bf16 v[94:97], v[158:161], v[216:219], v[94:97]
	v_mfma_f32_16x16x32_bf16 v[86:89], v[150:153], v[224:227], v[86:89]
	v_mfma_f32_16x16x32_bf16 v[78:81], v[158:161], v[224:227], v[78:81]
	s_setprio 0
	s_setprio 1
	v_mfma_f32_16x16x32_bf16 v[114:117], v[162:165], v[186:189], v[114:117]
	v_mfma_f32_16x16x32_bf16 v[106:109], v[178:181], v[186:189], v[106:109]
	v_mfma_f32_16x16x32_bf16 v[98:101], v[162:165], v[194:197], v[98:101]
	v_mfma_f32_16x16x32_bf16 v[90:93], v[178:181], v[194:197], v[90:93]
	v_mfma_f32_16x16x32_bf16 v[82:85], v[162:165], v[212:215], v[82:85]
	v_mfma_f32_16x16x32_bf16 v[74:77], v[178:181], v[212:215], v[74:77]
	v_mfma_f32_16x16x32_bf16 v[70:73], v[162:165], v[220:223], v[70:73]
	v_mfma_f32_16x16x32_bf16 v[66:69], v[178:181], v[220:223], v[66:69]
	v_mfma_f32_16x16x32_bf16 v[114:117], v[166:169], v[190:193], v[114:117]
	v_mfma_f32_16x16x32_bf16 v[106:109], v[182:185], v[190:193], v[106:109]
	v_mfma_f32_16x16x32_bf16 v[98:101], v[166:169], v[198:201], v[98:101]
	v_mfma_f32_16x16x32_bf16 v[90:93], v[182:185], v[198:201], v[90:93]
	v_mfma_f32_16x16x32_bf16 v[82:85], v[166:169], v[216:219], v[82:85]
	v_mfma_f32_16x16x32_bf16 v[74:77], v[182:185], v[216:219], v[74:77]
	v_mfma_f32_16x16x32_bf16 v[70:73], v[166:169], v[224:227], v[70:73]
	v_mfma_f32_16x16x32_bf16 v[66:69], v[182:185], v[224:227], v[66:69]
	s_setprio 0
	s_barrier
; #define PG8_STAGE(bufoff, gbase, voff) do { _Pragma("unroll") for (int _i = 0; _i < 2; ++_i) \
;         __builtin_amdgcn_global_load_lds((const unsigned*)((const char*)(gbase) + (voff)[_i]), (LAS unsigned*)(lds + (bufoff) + ldsw + _i * 8192), 16, 0, 0); } while (0)
; #define PG8_LDA(dst, b, h) do { _Pragma("unroll") for (int m = 0; m < 4; ++m) _Pragma("unroll") for (int k = 0; k < 2; ++k) dst[m][k] = *(const LAS bf16x8*)(lds + PG8_SA(b, h) + aoff + m * 2048 + k * 1024); } while (0)
; #define PG8_MMA(ai, bj, At, Bt) do { __builtin_amdgcn_s_setprio(1); _Pragma("unroll") for (int m = 0; m < 4; ++m) _Pragma("unroll") for (int n = 0; n < 2; ++n) _Pragma("unroll") for (int k = 0; k < 2; ++k) \
;         acc[ai][bj][m][n] = __builtin_amdgcn_mfma_f32_16x16x32_bf16(Bt[n][k], At[m][k], acc[ai][bj][m][n], 0, 0, 0); __builtin_amdgcn_s_setprio(0); } while (0)
; #define PG8_WAIT_V(n) asm volatile("s_waitcnt vmcnt(" #n ")" ::: "memory")
; #define PG8_WAIT_L(n) asm volatile("s_waitcnt lgkmcnt(" #n ")" ::: "memory")
; #define PG8_BAR __builtin_amdgcn_s_barrier()
; #define PG8_SCHED __builtin_amdgcn_sched_barrier(0)
; template <class Epi>
; __device__ __forceinline__ void gemm_phase(LAS unsigned char* lds, const Gemm g, const StaticOrder& S, const Epi& E, const int tid) {
;     ...
;             PG8_LDA(At, 1, 1); PG8_STAGE(PG8_SB(1, 0), b3, voffB); PG8_STAGE(PG8_SB(1, 1), b3 + bhs, voffB); PG8_STAGE(PG8_SA(1, 0), a3, voffA);
;             PG8_WAIT_V(8); PG8_WAIT_L(0); PG8_BAR; PG8_MMA(1, 0, At, B0); PG8_MMA(1, 1, At, B1); PG8_BAR; PG8_SCHED;
;     ...
;         if (ALIGN_EPI) { if (wr == 0) PG8_BAR; }
	s_add_i32 s34, s51, s40
	v_lshl_add_u64 v[172:173], v[172:173], 0, s[70:71]
	s_mov_b32 m0, s34
	ds_read_b128 v[186:189], v144 offset:49152
	global_load_lds_dwordx4 v[172:173], off
	ds_read_b128 v[190:193], v144 offset:50176
	ds_read_b128 v[194:197], v144 offset:51200
	s_add_i32 m0, s34, 0x2000
	s_add_u32 s30, s30, 0x8080
	v_lshl_add_u64 v[172:173], v[174:175], 0, s[70:71]
	s_addc_u32 s31, s31, 0
	s_add_i32 s34, s52, s40
	global_load_lds_dwordx4 v[172:173], off
	ds_read_b128 v[198:201], v144 offset:52224
	ds_read_b128 v[212:215], v144 offset:53248
	v_lshl_add_u64 v[172:173], s[30:31], 0, v[0:1]
	s_mov_b32 m0, s34
	s_nop 0
	global_load_lds_dwordx4 v[172:173], off
	ds_read_b128 v[216:219], v144 offset:54272
	ds_read_b128 v[220:223], v144 offset:55296
	v_lshl_add_u64 v[172:173], s[30:31], 0, v[134:135]
	s_add_i32 m0, s34, 0x2000
	s_nop 0
	global_load_lds_dwordx4 v[172:173], off
	ds_read_b128 v[224:227], v144 offset:56320
	v_lshl_add_u64 v[172:173], v[176:177], 0, s[70:71]
	s_mov_b32 m0, s43
	s_nop 0
	global_load_lds_dwordx4 v[172:173], off
	v_lshl_add_u64 v[172:173], v[228:229], 0, s[70:71]
	s_mov_b32 m0, s44
	s_nop 0
	global_load_lds_dwordx4 v[172:173], off
	s_waitcnt vmcnt(8)
	s_waitcnt lgkmcnt(0)
	s_barrier
	s_setprio 1
	s_waitcnt lgkmcnt(0)
	v_mfma_f32_16x16x32_bf16 v[62:65], v[146:149], v[186:189], v[62:65]
	v_mfma_f32_16x16x32_bf16 v[58:61], v[154:157], v[186:189], v[58:61]
	v_mfma_f32_16x16x32_bf16 v[54:57], v[146:149], v[194:197], v[54:57]
	v_mfma_f32_16x16x32_bf16 v[46:49], v[154:157], v[194:197], v[46:49]
	v_mfma_f32_16x16x32_bf16 v[38:41], v[146:149], v[212:215], v[38:41]
	v_mfma_f32_16x16x32_bf16 v[30:33], v[154:157], v[212:215], v[30:33]
	v_mfma_f32_16x16x32_bf16 v[22:25], v[146:149], v[220:223], v[22:25]
	v_mfma_f32_16x16x32_bf16 v[14:17], v[154:157], v[220:223], v[14:17]
	v_mfma_f32_16x16x32_bf16 v[62:65], v[150:153], v[190:193], v[62:65]
	v_mfma_f32_16x16x32_bf16 v[58:61], v[158:161], v[190:193], v[58:61]
	v_mfma_f32_16x16x32_bf16 v[54:57], v[150:153], v[198:201], v[54:57]
	v_mfma_f32_16x16x32_bf16 v[46:49], v[158:161], v[198:201], v[46:49]
	v_mfma_f32_16x16x32_bf16 v[38:41], v[150:153], v[216:219], v[38:41]
	v_mfma_f32_16x16x32_bf16 v[30:33], v[158:161], v[216:219], v[30:33]
	v_mfma_f32_16x16x32_bf16 v[22:25], v[150:153], v[224:227], v[22:25]
	v_mfma_f32_16x16x32_bf16 v[14:17], v[158:161], v[224:227], v[14:17]
	s_setprio 0
	s_setprio 1
	v_mfma_f32_16x16x32_bf16 v[50:53], v[162:165], v[186:189], v[50:53]
	v_mfma_f32_16x16x32_bf16 v[42:45], v[178:181], v[186:189], v[42:45]
	v_mfma_f32_16x16x32_bf16 v[34:37], v[162:165], v[194:197], v[34:37]
	v_mfma_f32_16x16x32_bf16 v[26:29], v[178:181], v[194:197], v[26:29]
	v_mfma_f32_16x16x32_bf16 v[18:21], v[162:165], v[212:215], v[18:21]
	v_mfma_f32_16x16x32_bf16 v[10:13], v[178:181], v[212:215], v[10:13]
	v_mfma_f32_16x16x32_bf16 v[6:9], v[162:165], v[220:223], v[6:9]
	v_mfma_f32_16x16x32_bf16 v[2:5], v[178:181], v[220:223], v[2:5]
	v_mfma_f32_16x16x32_bf16 v[50:53], v[166:169], v[190:193], v[50:53]
	v_mfma_f32_16x16x32_bf16 v[42:45], v[182:185], v[190:193], v[42:45]
	v_mfma_f32_16x16x32_bf16 v[34:37], v[166:169], v[198:201], v[34:37]
	v_mfma_f32_16x16x32_bf16 v[26:29], v[182:185], v[198:201], v[26:29]
	v_mfma_f32_16x16x32_bf16 v[18:21], v[166:169], v[216:219], v[18:21]
	v_mfma_f32_16x16x32_bf16 v[10:13], v[182:185], v[216:219], v[10:13]
	v_mfma_f32_16x16x32_bf16 v[6:9], v[166:169], v[224:227], v[6:9]
	v_mfma_f32_16x16x32_bf16 v[2:5], v[182:185], v[224:227], v[2:5]
	s_setprio 0
	s_barrier
	s_add_i32 s50, s50, 2
	s_add_u32 s48, s48, 0x100
	s_addc_u32 s49, s49, 0
	s_add_u32 s28, s28, 0x100
	s_addc_u32 s29, s29, 0
	s_cmp_gt_u32 s50, 29
	s_cbranch_scc0 .LBB0_861
	s_and_b64 vcc, exec, s[12:13]
	s_cbranch_vccz .LBB0_864
	s_barrier
